# baseline (speedup 1.0000x reference)
; DEVI unsigned pack2(float a, float b) { f32v2 v = {a, b}; return __builtin_bit_cast(unsigned, __builtin_convertvector(v, bf16v2)); }
; DEVI void lds_barrier() { asm volatile("s_waitcnt lgkmcnt(0)" ::: "memory"); __builtin_amdgcn_s_barrier(); asm volatile("" ::: "memory"); }
; DEVI void tconv_store(const TcPre& R, u16* __restrict__ Wt, int K, int N, int t, float* lds, bool perm) {
;   const int tid = threadIdx.x;
;   const int tnN = N / 128;
;   int tk = t / tnN, tn = t % tnN, k0 = tk * 64, n0 = tn * 128;
;   {
;     float* d = lds + (tid >> 5) * 129 + (tid & 31) * 4;
;     d[0] = R.a[0]; d[1] = R.a[1]; d[2] = R.a[2]; d[3] = R.a[3];
;     d[16 * 129] = R.b[0]; d[16 * 129 + 1] = R.b[1]; d[16 * 129 + 2] = R.b[2]; d[16 * 129 + 3] = R.b[3];
;     d[32 * 129] = R.c[0]; d[32 * 129 + 1] = R.c[1]; d[32 * 129 + 2] = R.c[2]; d[32 * 129 + 3] = R.c[3];
;     d[48 * 129] = R.d[0]; d[48 * 129 + 1] = R.d[1]; d[48 * 129 + 2] = R.d[2]; d[48 * 129 + 3] = R.d[3];
;   }
;   lds_barrier();
;   int n0p = !perm ? n0 : (n0 < DFF ? (n0 / 128) * 256 : ((n0 - DFF) / 128) * 256 + 128);
; #pragma unroll
;   for (int p = 0; p < 2; ++p) {
;     int item = p * 512 + tid, n = item >> 3, kg = item & 7;
;     const float* s = lds + (kg * 8) * 129 + n;
;     uint4 o;
;     o.x = pack2(s[0], s[129]); o.y = pack2(s[2 * 129], s[3 * 129]);
;     o.z = pack2(s[4 * 129], s[5 * 129]); o.w = pack2(s[6 * 129], s[7 * 129]);
;     *(uint4*)(Wt + (size_t)(n0p + n) * K + k0 + kg * 8) = o;
;   }
;   lds_barrier();
; }
; DEVI void tconv(const float* __restrict__ W, u16* __restrict__ Wt, int K, int N, float* lds) {
;     ...
;   for (; t < ntile; t += gridDim.x) {
;     TcPre C = R;
;     int nx = t + (int)gridDim.x;
;     tconv_load(W, N, nx < ntile ? nx : t, R);
;     tconv_store(C, Wt, K, N, t, lds, false);
;   }
.LBB0_104:
	s_add_i32 s15, s11, s14
	s_cmpk_lt_i32 s15, 0x1a00
	s_cselect_b64 s[4:5], -1, 0
	s_and_b64 vcc, s[4:5], exec
	s_cselect_b32 s4, s15, s11
	s_mul_hi_i32 s5, s4, 0x4ec4ec4f
	s_lshr_b32 s33, s5, 31
	s_ashr_i32 s5, s5, 5
	s_add_i32 s5, s5, s33
	s_mul_i32 s33, s5, 0x68
	v_lshl_or_b32 v40, s5, 6, v22
	s_sub_i32 s33, s4, s33
	v_mad_i64_i32 v[40:41], s[4:5], v40, s3, v[20:21]
	s_lshl_b32 s4, s33, 7
	s_ashr_i32 s5, s4, 31
	v_lshl_add_u64 v[40:41], s[4:5], 2, v[40:41]
	v_lshl_add_u64 v[44:45], v[40:41], 0, v[16:17]
	v_add_co_u32_e64 v52, s[4:5], s6, v44
	global_load_dwordx4 v[40:43], v[44:45], off
	s_nop 0
	v_addc_co_u32_e64 v53, s[4:5], 0, v45, s[4:5]
	v_add_co_u32_e64 v48, s[4:5], s7, v44
	s_nop 1
	v_addc_co_u32_e64 v49, s[4:5], 0, v45, s[4:5]
	v_add_co_u32_e64 v44, s[4:5], s8, v44
	s_nop 1
	v_addc_co_u32_e64 v45, s[4:5], 0, v45, s[4:5]
	global_load_dwordx4 v[44:47], v[44:45], off
	s_nop 0
	global_load_dwordx4 v[48:51], v[48:49], off
	s_nop 0
	global_load_dwordx4 v[52:55], v[52:53], off
	s_mul_hi_i32 s4, s11, 0x4ec4ec4f
	s_lshr_b32 s5, s4, 31
	s_ashr_i32 s4, s4, 5
	s_add_i32 s5, s4, s5
	s_mov_b32 s11, s15
	s_mul_i32 s15, s5, 0xffffcc00
	s_add_i32 s15, s15, s9
	s_waitcnt vmcnt(7)
	ds_write2_b32 v23, v0, v1 offset1:1
	ds_write2_b32 v23, v2, v3 offset0:2 offset1:3
	s_waitcnt vmcnt(6)
	ds_write2_b32 v28, v4, v5 offset1:1
	ds_write2_b32 v29, v6, v7 offset1:1
	s_waitcnt vmcnt(5)
	ds_write2_b32 v30, v12, v13 offset1:1
	ds_write2_b32 v31, v14, v15 offset1:1
	s_waitcnt vmcnt(4)
	ds_write2_b32 v32, v8, v9 offset1:1
	ds_write2_b32 v33, v10, v11 offset1:1
	s_lshl_b32 s4, s5, 6
	v_add_u32_e32 v2, s15, v24
	v_add_u32_e32 v4, s15, v26
	s_ashr_i32 s5, s4, 31
	v_ashrrev_i32_e32 v3, 31, v2
	v_ashrrev_i32_e32 v5, 31, v4
	v_lshl_add_u64 v[0:1], s[4:5], 1, v[18:19]
	v_lshlrev_b64 v[2:3], 13, v[2:3]
	v_lshlrev_b64 v[4:5], 13, v[4:5]
	s_waitcnt lgkmcnt(0)
	s_barrier
	v_lshl_add_u64 v[8:9], v[0:1], 0, v[2:3]
	v_lshl_add_u64 v[10:11], v[0:1], 0, v[4:5]
	ds_read2_b32 v[0:1], v25 offset1:129
	ds_read2_b32 v[2:3], v34 offset0:2 offset1:131
	ds_read2_b32 v[4:5], v35 offset0:4 offset1:133
	ds_read2_b32 v[6:7], v36 offset0:6 offset1:135
	ds_read2_b32 v[12:13], v27 offset1:129
	ds_read2_b32 v[14:15], v37 offset0:2 offset1:131
	ds_read2_b32 v[56:57], v38 offset0:4 offset1:133
	ds_read2_b32 v[58:59], v39 offset0:6 offset1:135
	s_waitcnt lgkmcnt(7)
	v_cvt_pk_bf16_f32 v0, v0, v1
	s_waitcnt lgkmcnt(6)
	v_cvt_pk_bf16_f32 v1, v2, v3
	s_waitcnt lgkmcnt(5)
	v_cvt_pk_bf16_f32 v2, v4, v5
	s_waitcnt lgkmcnt(4)
	v_cvt_pk_bf16_f32 v3, v6, v7
	s_waitcnt lgkmcnt(3)
	v_cvt_pk_bf16_f32 v4, v12, v13
	s_waitcnt lgkmcnt(2)
	v_cvt_pk_bf16_f32 v5, v14, v15
	s_waitcnt lgkmcnt(1)
	v_cvt_pk_bf16_f32 v6, v56, v57
	s_waitcnt lgkmcnt(0)
	v_cvt_pk_bf16_f32 v7, v58, v59
	global_store_dwordx4 v[8:9], v[0:3], off sc1
	global_store_dwordx4 v[10:11], v[4:7], off sc1
	s_waitcnt lgkmcnt(0)
	s_barrier
	s_add_i32 s9, s9, s10
	s_waitcnt vmcnt(5)
	v_mov_b64_e32 v[0:1], v[40:41]
	v_mov_b64_e32 v[2:3], v[42:43]
	s_waitcnt vmcnt(4)
	v_mov_b64_e32 v[8:9], v[44:45]
	s_waitcnt vmcnt(3)
	v_mov_b64_e32 v[12:13], v[48:49]
	s_waitcnt vmcnt(2)
	v_mov_b64_e32 v[4:5], v[52:53]
	v_mov_b64_e32 v[10:11], v[46:47]
	v_mov_b64_e32 v[14:15], v[50:51]
	v_mov_b64_e32 v[6:7], v[54:55]
	s_cbranch_vccnz .LBB0_104

; DEVI unsigned pack2(float a, float b) { f32v2 v = {a, b}; return __builtin_bit_cast(unsigned, __builtin_convertvector(v, bf16v2)); }
; DEVI void lds_barrier() { asm volatile("s_waitcnt lgkmcnt(0)" ::: "memory"); __builtin_amdgcn_s_barrier(); asm volatile("" ::: "memory"); }
; DEVI void tconv_store(const TcPre& R, u16* __restrict__ Wt, int K, int N, int t, float* lds, bool perm) {
;   const int tid = threadIdx.x;
;   const int tnN = N / 128;
;   int tk = t / tnN, tn = t % tnN, k0 = tk * 64, n0 = tn * 128;
;   {
;     float* d = lds + (tid >> 5) * 129 + (tid & 31) * 4;
;     d[0] = R.a[0]; d[1] = R.a[1]; d[2] = R.a[2]; d[3] = R.a[3];
;     d[16 * 129] = R.b[0]; d[16 * 129 + 1] = R.b[1]; d[16 * 129 + 2] = R.b[2]; d[16 * 129 + 3] = R.b[3];
;     d[32 * 129] = R.c[0]; d[32 * 129 + 1] = R.c[1]; d[32 * 129 + 2] = R.c[2]; d[32 * 129 + 3] = R.c[3];
;     d[48 * 129] = R.d[0]; d[48 * 129 + 1] = R.d[1]; d[48 * 129 + 2] = R.d[2]; d[48 * 129 + 3] = R.d[3];
;   }
;   lds_barrier();
;   int n0p = !perm ? n0 : (n0 < DFF ? (n0 / 128) * 256 : ((n0 - DFF) / 128) * 256 + 128);
; #pragma unroll
;   for (int p = 0; p < 2; ++p) {
;     int item = p * 512 + tid, n = item >> 3, kg = item & 7;
;     const float* s = lds + (kg * 8) * 129 + n;
;     uint4 o;
;     o.x = pack2(s[0], s[129]); o.y = pack2(s[2 * 129], s[3 * 129]);
;     o.z = pack2(s[4 * 129], s[5 * 129]); o.w = pack2(s[6 * 129], s[7 * 129]);
;     *(uint4*)(Wt + (size_t)(n0p + n) * K + k0 + kg * 8) = o;
;   }
;   lds_barrier();
; }
; DEVI void tconv(const float* __restrict__ W, u16* __restrict__ Wt, int K, int N, float* lds) {
;     ...
;   for (; t < ntile; t += gridDim.x) {
;     TcPre C = R;
;     int nx = t + (int)gridDim.x;
;     tconv_load(W, N, nx < ntile ? nx : t, R);
;     tconv_store(C, Wt, K, N, t, lds, false);
;   }
.LBB0_107:
	s_add_i32 s9, s8, s14
	s_cmpk_lt_i32 s9, 0x400
	s_cselect_b32 s10, s9, s8
	s_ashr_i32 s11, s10, 31
	s_lshr_b32 s11, s11, 28
	s_add_i32 s11, s10, s11
	s_and_b32 s15, s11, 0x1fffff0
	s_lshl_b32 s11, s11, 2
	s_andn2_b32 s11, s11, 63
	v_or_b32_e32 v38, s11, v20
	s_sub_i32 s10, s10, s15
	v_ashrrev_i32_e32 v39, 31, v38
	s_lshl_b32 s10, s10, 7
	v_lshlrev_b64 v[38:39], 13, v[38:39]
	s_ashr_i32 s11, s10, 31
	v_lshl_add_u64 v[38:39], s[44:45], 0, v[38:39]
	v_lshl_add_u64 v[38:39], s[10:11], 2, v[38:39]
	v_lshl_add_u64 v[42:43], v[38:39], 0, v[16:17]
	v_add_co_u32_e32 v54, vcc, s3, v42
	global_load_dwordx4 v[38:41], v[42:43], off
	s_nop 0
	v_addc_co_u32_e32 v55, vcc, 0, v43, vcc
	v_add_co_u32_e32 v56, vcc, s4, v42
	s_ashr_i32 s10, s8, 31
	s_nop 0
	v_addc_co_u32_e32 v57, vcc, 0, v43, vcc
	v_add_co_u32_e32 v42, vcc, s5, v42
	s_lshr_b32 s10, s10, 28
	s_nop 0
	v_addc_co_u32_e32 v43, vcc, 0, v43, vcc
	global_load_dwordx4 v[42:45], v[42:43], off
	s_nop 0
	global_load_dwordx4 v[46:49], v[56:57], off
	global_load_dwordx4 v[50:53], v[54:55], off
	s_add_i32 s10, s8, s10
	s_ashr_i32 s11, s10, 4
	s_lshl_b32 s15, s11, 11
	s_sub_i32 s15, s6, s15
	s_waitcnt vmcnt(7)
	ds_write2_b32 v21, v0, v1 offset1:1
	ds_write2_b32 v21, v2, v3 offset0:2 offset1:3
	s_waitcnt vmcnt(6)
	ds_write2_b32 v26, v4, v5 offset1:1
	ds_write2_b32 v27, v6, v7 offset1:1
	s_waitcnt vmcnt(5)
	ds_write2_b32 v28, v12, v13 offset1:1
	ds_write2_b32 v29, v14, v15 offset1:1
	s_waitcnt vmcnt(4)
	ds_write2_b32 v30, v8, v9 offset1:1
	ds_write2_b32 v31, v10, v11 offset1:1
	s_lshl_b32 s10, s11, 6
	v_add_u32_e32 v2, s15, v22
	v_add_u32_e32 v4, s15, v24
	s_ashr_i32 s11, s10, 31
	v_ashrrev_i32_e32 v3, 31, v2
	v_ashrrev_i32_e32 v5, 31, v4
	v_lshl_add_u64 v[0:1], s[10:11], 1, v[18:19]
	v_lshlrev_b64 v[2:3], 13, v[2:3]
	v_lshlrev_b64 v[4:5], 13, v[4:5]
	s_waitcnt lgkmcnt(0)
	s_barrier
	v_lshl_add_u64 v[8:9], v[0:1], 0, v[2:3]
	v_lshl_add_u64 v[10:11], v[0:1], 0, v[4:5]
	ds_read2_b32 v[0:1], v23 offset1:129
	ds_read2_b32 v[2:3], v32 offset0:2 offset1:131
	ds_read2_b32 v[4:5], v33 offset0:4 offset1:133
	ds_read2_b32 v[6:7], v34 offset0:6 offset1:135
	ds_read2_b32 v[12:13], v25 offset1:129
	ds_read2_b32 v[14:15], v35 offset0:2 offset1:131
	ds_read2_b32 v[54:55], v36 offset0:4 offset1:133
	ds_read2_b32 v[56:57], v37 offset0:6 offset1:135
	s_waitcnt lgkmcnt(7)
	v_cvt_pk_bf16_f32 v0, v0, v1
	s_waitcnt lgkmcnt(6)
	v_cvt_pk_bf16_f32 v1, v2, v3
	s_waitcnt lgkmcnt(5)
	v_cvt_pk_bf16_f32 v2, v4, v5
	s_waitcnt lgkmcnt(4)
	v_cvt_pk_bf16_f32 v3, v6, v7
	s_waitcnt lgkmcnt(3)
	v_cvt_pk_bf16_f32 v4, v12, v13
	s_waitcnt lgkmcnt(2)
	v_cvt_pk_bf16_f32 v5, v14, v15
	s_waitcnt lgkmcnt(1)
	v_cvt_pk_bf16_f32 v6, v54, v55
	s_waitcnt lgkmcnt(0)
	v_cvt_pk_bf16_f32 v7, v56, v57
	global_store_dwordx4 v[8:9], v[0:3], off sc1
	global_store_dwordx4 v[10:11], v[4:7], off sc1
	s_waitcnt lgkmcnt(0)
	s_barrier
	s_add_i32 s6, s6, s7
	s_mov_b32 s8, s9
	s_cmpk_gt_i32 s9, 0x3ff
	s_waitcnt vmcnt(5)
	v_mov_b64_e32 v[0:1], v[38:39]
	v_mov_b64_e32 v[2:3], v[40:41]
	s_waitcnt vmcnt(4)
	v_mov_b64_e32 v[8:9], v[42:43]
	s_waitcnt vmcnt(3)
	v_mov_b64_e32 v[12:13], v[46:47]
	s_waitcnt vmcnt(2)
	v_mov_b64_e32 v[4:5], v[50:51]
	v_mov_b64_e32 v[10:11], v[44:45]
	v_mov_b64_e32 v[14:15], v[48:49]
	v_mov_b64_e32 v[6:7], v[52:53]
	s_cbranch_scc0 .LBB0_107

; template <int MODE> ...
;     ...
;           for (int it = 0; it < 4; ++it) {
;             int item = it * 512 + t2, row = item >> 4, hp = item & 15, head = hp >> 3, c = hp & 7;
;             int q0 = head * 32 + 2 * c, sw2 = ((row >> 2) & 3) << 3;
;             const char* rp = ls + row * 1024;
;             float4 a0 = *(const float4*)(rp + ((q0 ^ sw2) << 4)), a1 = *(const float4*)(rp + (((q0 + 1) ^ sw2) << 4));
;             float4 b0 = *(const float4*)(rp + (((q0 + 16) ^ sw2) << 4)), b1 = *(const float4*)(rp + (((q0 + 17) ^ sw2) << 4));
;             long tok = brow + ai * HALF + row;
;             const float* cs = aux0 + tok * 64 + 8 * c; const float* sn = aux1 + tok * 64 + 8 * c;
;             float4 c0 = *(const float4*)cs, c1 = *(const float4*)(cs + 4), s0 = *(const float4*)sn, s1 = *(const float4*)(sn + 4);
;             float o1[8], o2[8];
;             o1[0] = (a0.x * c0.x - b0.x * s0.x) * scale; o2[0] = (b0.x * c0.x + a0.x * s0.x) * scale;
;             o1[1] = (a0.y * c0.y - b0.y * s0.y) * scale; o2[1] = (b0.y * c0.y + a0.y * s0.y) * scale;
;             o1[2] = (a0.z * c0.z - b0.z * s0.z) * scale; o2[2] = (b0.z * c0.z + a0.z * s0.z) * scale;
;             o1[3] = (a0.w * c0.w - b0.w * s0.w) * scale; o2[3] = (b0.w * c0.w + a0.w * s0.w) * scale;
;             o1[4] = (a1.x * c1.x - b1.x * s1.x) * scale; o2[4] = (b1.x * c1.x + a1.x * s1.x) * scale;
;             o1[5] = (a1.y * c1.y - b1.y * s1.y) * scale; o2[5] = (b1.y * c1.y + a1.y * s1.y) * scale;
;             o1[6] = (a1.z * c1.z - b1.z * s1.z) * scale; o2[6] = (b1.z * c1.z + a1.z * s1.z) * scale;
;             o1[7] = (a1.w * c1.w - b1.w * s1.w) * scale; o2[7] = (b1.w * c1.w + a1.w * s1.w) * scale;
;             u16* op = outb + tok * ldc + bcol + head * 128 + 8 * c;
;             *(uint4*)op = pack8(o1); *(uint4*)(op + 64) = pack8(o2);
;           }
.LBB0_159:
	v_add_u32_e32 v212, s69, v170
	v_ashrrev_i32_e32 v213, 4, v212
	v_add_u32_e32 v210, s68, v213
	v_ashrrev_i32_e32 v211, 31, v210
	v_lshlrev_b64 v[194:195], 8, v[210:211]
	v_lshl_add_u64 v[206:207], v[140:141], 0, v[194:195]
	v_lshl_add_u64 v[198:199], v[142:143], 0, v[194:195]
	global_load_dwordx4 v[194:197], v[198:199], off
	s_nop 0
	global_load_dwordx4 v[198:201], v[198:199], off offset:16
	s_nop 0
	global_load_dwordx4 v[202:205], v[206:207], off
	s_nop 0
	global_load_dwordx4 v[206:209], v[206:207], off offset:16
	v_add_u32_e32 v211, 0x200, v212
	v_lshlrev_b32_e32 v212, 10, v213
	v_ashrrev_i32_e32 v242, 4, v211
	v_or_b32_e32 v211, v212, v175
	v_or_b32_e32 v214, v212, v176
	v_or_b32_e32 v218, v212, v177
	v_or_b32_e32 v222, v212, v178
	v_mad_i64_i32 v[226:227], s[72:73], v210, s81, v[144:145]
	ds_read_b128 v[210:213], v211
	ds_read_b128 v[214:217], v214
	ds_read_b128 v[218:221], v218
	ds_read_b128 v[222:225], v222
	v_add_u32_e32 v228, s68, v242
	v_ashrrev_i32_e32 v229, 31, v228
	v_lshlrev_b64 v[230:231], 8, v[228:229]
	v_lshl_add_u64 v[232:233], v[140:141], 0, v[230:231]
	v_lshl_add_u64 v[230:231], v[142:143], 0, v[230:231]
	s_addk_i32 s69, 0x400
	s_cmpk_eq_i32 s69, 0x800
	s_waitcnt vmcnt(0) lgkmcnt(0)
	v_pk_mul_f32 v[234:235], v[218:219], v[194:195]
	v_pk_mul_f32 v[194:195], v[210:211], v[194:195]
	v_pk_mul_f32 v[236:237], v[220:221], v[196:197]
	v_pk_mul_f32 v[196:197], v[212:213], v[196:197]
	v_pk_mul_f32 v[238:239], v[222:223], v[198:199]
	v_pk_mul_f32 v[198:199], v[214:215], v[198:199]
	v_pk_mul_f32 v[240:241], v[224:225], v[200:201]
	v_pk_mul_f32 v[200:201], v[216:217], v[200:201]
	v_pk_fma_f32 v[210:211], v[210:211], v[202:203], v[234:235] neg_lo:[0,0,1] neg_hi:[0,0,1]
	v_pk_fma_f32 v[194:195], v[218:219], v[202:203], v[194:195]
	v_pk_fma_f32 v[202:203], v[212:213], v[204:205], v[236:237] neg_lo:[0,0,1] neg_hi:[0,0,1]
	v_pk_fma_f32 v[196:197], v[220:221], v[204:205], v[196:197]
	v_pk_fma_f32 v[204:205], v[214:215], v[206:207], v[238:239] neg_lo:[0,0,1] neg_hi:[0,0,1]
	v_pk_fma_f32 v[198:199], v[222:223], v[206:207], v[198:199]
	v_pk_fma_f32 v[206:207], v[216:217], v[208:209], v[240:241] neg_lo:[0,0,1] neg_hi:[0,0,1]
	v_pk_fma_f32 v[200:201], v[224:225], v[208:209], v[200:201]
	v_pk_mul_f32 v[208:209], v[138:139], v[210:211]
	v_pk_mul_f32 v[202:203], v[138:139], v[202:203]
	v_pk_mul_f32 v[212:213], v[138:139], v[196:197]
	v_pk_mul_f32 v[196:197], v[138:139], v[204:205]
	v_pk_mul_f32 v[204:205], v[138:139], v[198:199]
	v_pk_mul_f32 v[198:199], v[138:139], v[206:207]
	v_pk_mul_f32 v[210:211], v[138:139], v[194:195]
	v_pk_mul_f32 v[206:207], v[138:139], v[200:201]
	v_cvt_pk_bf16_f32 v194, v208, v209
	v_cvt_pk_bf16_f32 v195, v202, v203
	v_cvt_pk_bf16_f32 v196, v196, v197
	v_cvt_pk_bf16_f32 v197, v198, v199
	v_cvt_pk_bf16_f32 v198, v210, v211
	v_cvt_pk_bf16_f32 v199, v212, v213
	v_cvt_pk_bf16_f32 v200, v204, v205
	v_cvt_pk_bf16_f32 v201, v206, v207
	global_store_dwordx4 v[226:227], v[194:197], off sc1
	global_store_dwordx4 v[226:227], v[198:201], off offset:128 sc1
	global_load_dwordx4 v[194:197], v[230:231], off
	s_nop 0
	global_load_dwordx4 v[198:201], v[230:231], off offset:16
	global_load_dwordx4 v[202:205], v[232:233], off
	global_load_dwordx4 v[206:209], v[232:233], off offset:16
	v_lshlrev_b32_e32 v210, 10, v242
	v_or_b32_e32 v214, v210, v175
	v_or_b32_e32 v218, v210, v176
	v_or_b32_e32 v211, v210, v177
	v_or_b32_e32 v222, v210, v178
	ds_read_b128 v[210:213], v211
	ds_read_b128 v[214:217], v214
	ds_read_b128 v[218:221], v218
	ds_read_b128 v[222:225], v222
	v_mad_i64_i32 v[226:227], s[72:73], v228, s81, v[144:145]
	s_waitcnt vmcnt(3) lgkmcnt(3)
	v_pk_mul_f32 v[228:229], v[210:211], v[194:195]
	s_waitcnt lgkmcnt(2)
	v_pk_mul_f32 v[194:195], v[214:215], v[194:195]
	v_pk_mul_f32 v[230:231], v[212:213], v[196:197]
	v_pk_mul_f32 v[196:197], v[216:217], v[196:197]
	s_waitcnt vmcnt(2) lgkmcnt(0)
	v_pk_mul_f32 v[232:233], v[222:223], v[198:199]
	v_pk_mul_f32 v[198:199], v[218:219], v[198:199]
	v_pk_mul_f32 v[234:235], v[224:225], v[200:201]
	v_pk_mul_f32 v[200:201], v[220:221], v[200:201]
	s_waitcnt vmcnt(1)
	v_pk_fma_f32 v[214:215], v[214:215], v[202:203], v[228:229] neg_lo:[0,0,1] neg_hi:[0,0,1]
	v_pk_fma_f32 v[194:195], v[210:211], v[202:203], v[194:195]
	v_pk_fma_f32 v[202:203], v[216:217], v[204:205], v[230:231] neg_lo:[0,0,1] neg_hi:[0,0,1]
	v_pk_fma_f32 v[196:197], v[212:213], v[204:205], v[196:197]
	s_waitcnt vmcnt(0)
	v_pk_fma_f32 v[204:205], v[218:219], v[206:207], v[232:233] neg_lo:[0,0,1] neg_hi:[0,0,1]
	v_pk_fma_f32 v[198:199], v[222:223], v[206:207], v[198:199]
	v_pk_fma_f32 v[206:207], v[220:221], v[208:209], v[234:235] neg_lo:[0,0,1] neg_hi:[0,0,1]
	v_pk_fma_f32 v[200:201], v[224:225], v[208:209], v[200:201]
	v_pk_mul_f32 v[208:209], v[138:139], v[214:215]
	v_pk_mul_f32 v[202:203], v[138:139], v[202:203]
	v_pk_mul_f32 v[212:213], v[138:139], v[196:197]
	v_pk_mul_f32 v[196:197], v[138:139], v[204:205]
	v_pk_mul_f32 v[204:205], v[138:139], v[198:199]
	v_pk_mul_f32 v[198:199], v[138:139], v[206:207]
	v_pk_mul_f32 v[210:211], v[138:139], v[194:195]
	v_pk_mul_f32 v[206:207], v[138:139], v[200:201]
	v_cvt_pk_bf16_f32 v194, v208, v209
	v_cvt_pk_bf16_f32 v195, v202, v203
	v_cvt_pk_bf16_f32 v196, v196, v197
	v_cvt_pk_bf16_f32 v197, v198, v199
	v_cvt_pk_bf16_f32 v198, v210, v211
	v_cvt_pk_bf16_f32 v199, v212, v213
	v_cvt_pk_bf16_f32 v200, v204, v205
	v_cvt_pk_bf16_f32 v201, v206, v207
	global_store_dwordx4 v[226:227], v[194:197], off sc1
	global_store_dwordx4 v[226:227], v[198:201], off offset:128 sc1
	s_cbranch_scc0 .LBB0_159
	s_waitcnt lgkmcnt(0)
	s_barrier
; DEVI void lds_barrier() { asm volatile("s_waitcnt lgkmcnt(0)" ::: "memory"); __builtin_amdgcn_s_barrier(); asm volatile("" ::: "memory"); }
; template <int MODE> ...
;     ...
;           if (ai) lds_barrier();
; #pragma unroll
;           for (int bj = 0; bj < 2; ++bj)
; #pragma unroll
;             for (int m = 0; m < 4; ++m)
; #pragma unroll
;               for (int n = 0; n < 2; ++n)
; #pragma unroll
;                 for (int j = 0; j < 4; ++j)
;                   *(float*)(ls + wbase + ((m * 16 + j) * 1024 + (bj * 32 + n * 4) * 16)) = acc[ai][bj][m][n][j];
;           lds_barrier();
	ds_write2_b32 v179, v64, v56 offset1:16
	ds_write2_b32 v128, v65, v57 offset1:16
	ds_write2_b32 v180, v66, v58 offset1:16
	ds_write2_b32 v181, v67, v59 offset1:16
	ds_write2_b32 v182, v52, v48 offset1:16
	ds_write2_b32 v183, v53, v49 offset1:16
	ds_write2_b32 v184, v54, v50 offset1:16
	ds_write2_b32 v185, v55, v51 offset1:16
	ds_write2_b32 v186, v44, v40 offset1:16
	ds_write2_b32 v187, v45, v41 offset1:16
	ds_write2_b32 v188, v46, v42 offset1:16
	ds_write2_b32 v189, v47, v43 offset1:16
	ds_write2_b32 v190, v36, v32 offset1:16
	ds_write2_b32 v191, v37, v33 offset1:16
	ds_write2_b32 v192, v38, v34 offset1:16
	ds_write2_b32 v193, v39, v35 offset1:16
	ds_write2_b32 v179, v28, v24 offset0:128 offset1:144
	ds_write2_b32 v128, v29, v25 offset0:128 offset1:144
	ds_write2_b32 v180, v30, v26 offset0:128 offset1:144
	ds_write2_b32 v181, v31, v27 offset0:128 offset1:144
	ds_write2_b32 v182, v20, v16 offset0:128 offset1:144
	ds_write2_b32 v183, v21, v17 offset0:128 offset1:144
	ds_write2_b32 v184, v22, v18 offset0:128 offset1:144
	ds_write2_b32 v185, v23, v19 offset0:128 offset1:144
	ds_write2_b32 v186, v12, v8 offset0:128 offset1:144
	ds_write2_b32 v187, v13, v9 offset0:128 offset1:144
	ds_write2_b32 v188, v14, v10 offset0:128 offset1:144
	ds_write2_b32 v189, v15, v11 offset0:128 offset1:144
	ds_write2_b32 v190, v4, v0 offset0:128 offset1:144
	ds_write2_b32 v191, v5, v1 offset0:128 offset1:144
	ds_write2_b32 v192, v6, v2 offset0:128 offset1:144
	ds_write2_b32 v193, v7, v3 offset0:128 offset1:144
	s_waitcnt lgkmcnt(0)
	s_barrier
	s_mov_b32 s69, 0
; template <int MODE> ...
;     ...
;           for (int it = 0; it < 4; ++it) {
;             int item = it * 512 + t2, row = item >> 4, hp = item & 15, head = hp >> 3, c = hp & 7;
;             int q0 = head * 32 + 2 * c, sw2 = ((row >> 2) & 3) << 3;
;             const char* rp = ls + row * 1024;
;             float4 a0 = *(const float4*)(rp + ((q0 ^ sw2) << 4)), a1 = *(const float4*)(rp + (((q0 + 1) ^ sw2) << 4));
;             float4 b0 = *(const float4*)(rp + (((q0 + 16) ^ sw2) << 4)), b1 = *(const float4*)(rp + (((q0 + 17) ^ sw2) << 4));
;             long tok = brow + ai * HALF + row;
;             const float* cs = aux0 + tok * 64 + 8 * c; const float* sn = aux1 + tok * 64 + 8 * c;
;             float4 c0 = *(const float4*)cs, c1 = *(const float4*)(cs + 4), s0 = *(const float4*)sn, s1 = *(const float4*)(sn + 4);
;             float o1[8], o2[8];
;             o1[0] = (a0.x * c0.x - b0.x * s0.x) * scale; o2[0] = (b0.x * c0.x + a0.x * s0.x) * scale;
;             o1[1] = (a0.y * c0.y - b0.y * s0.y) * scale; o2[1] = (b0.y * c0.y + a0.y * s0.y) * scale;
;             o1[2] = (a0.z * c0.z - b0.z * s0.z) * scale; o2[2] = (b0.z * c0.z + a0.z * s0.z) * scale;
;             o1[3] = (a0.w * c0.w - b0.w * s0.w) * scale; o2[3] = (b0.w * c0.w + a0.w * s0.w) * scale;
;             o1[4] = (a1.x * c1.x - b1.x * s1.x) * scale; o2[4] = (b1.x * c1.x + a1.x * s1.x) * scale;
;             o1[5] = (a1.y * c1.y - b1.y * s1.y) * scale; o2[5] = (b1.y * c1.y + a1.y * s1.y) * scale;
;             o1[6] = (a1.z * c1.z - b1.z * s1.z) * scale; o2[6] = (b1.z * c1.z + a1.z * s1.z) * scale;
;             o1[7] = (a1.w * c1.w - b1.w * s1.w) * scale; o2[7] = (b1.w * c1.w + a1.w * s1.w) * scale;
;             u16* op = outb + tok * ldc + bcol + head * 128 + 8 * c;
;             *(uint4*)op = pack8(o1); *(uint4*)(op + 64) = pack8(o2);
;           }
.LBB0_161:
	v_add_u32_e32 v128, s69, v170
	v_ashrrev_i32_e32 v179, 4, v128
	v_add_u32_e32 v196, s70, v179
	v_ashrrev_i32_e32 v197, 31, v196
	v_lshlrev_b64 v[180:181], 8, v[196:197]
	v_lshl_add_u64 v[192:193], v[140:141], 0, v[180:181]
	v_lshl_add_u64 v[184:185], v[142:143], 0, v[180:181]
	global_load_dwordx4 v[180:183], v[184:185], off
	s_nop 0
	global_load_dwordx4 v[184:187], v[184:185], off offset:16
	s_nop 0
	global_load_dwordx4 v[188:191], v[192:193], off
	s_nop 0
	global_load_dwordx4 v[192:195], v[192:193], off offset:16
	v_lshlrev_b32_e32 v179, 10, v179
	v_or_b32_e32 v197, v179, v175
	v_or_b32_e32 v200, v179, v176
	v_or_b32_e32 v204, v179, v177
	v_or_b32_e32 v179, v179, v178
	v_mad_i64_i32 v[212:213], s[72:73], v196, s81, v[144:145]
	ds_read_b128 v[196:199], v197
	ds_read_b128 v[200:203], v200
	ds_read_b128 v[204:207], v204
	ds_read_b128 v[208:211], v179
	v_add_u32_e32 v128, 0x200, v128
	v_ashrrev_i32_e32 v128, 4, v128
	v_add_u32_e32 v214, s70, v128
	v_ashrrev_i32_e32 v215, 31, v214
	v_lshlrev_b64 v[216:217], 8, v[214:215]
	v_lshl_add_u64 v[218:219], v[140:141], 0, v[216:217]
	v_lshl_add_u64 v[216:217], v[142:143], 0, v[216:217]
	v_lshlrev_b32_e32 v128, 10, v128
	v_or_b32_e32 v179, v128, v175
	s_addk_i32 s69, 0x400
	s_cmpk_eq_i32 s69, 0x800
	s_waitcnt vmcnt(3) lgkmcnt(1)
	v_pk_mul_f32 v[220:221], v[204:205], v[180:181]
	v_pk_mul_f32 v[180:181], v[196:197], v[180:181]
	v_pk_mul_f32 v[222:223], v[206:207], v[182:183]
	v_pk_mul_f32 v[182:183], v[198:199], v[182:183]
	s_waitcnt vmcnt(2) lgkmcnt(0)
	v_pk_mul_f32 v[224:225], v[208:209], v[184:185]
	v_pk_mul_f32 v[184:185], v[200:201], v[184:185]
	v_pk_mul_f32 v[226:227], v[210:211], v[186:187]
	v_pk_mul_f32 v[186:187], v[202:203], v[186:187]
	s_waitcnt vmcnt(1)
	v_pk_fma_f32 v[196:197], v[196:197], v[188:189], v[220:221] neg_lo:[0,0,1] neg_hi:[0,0,1]
	v_pk_fma_f32 v[180:181], v[204:205], v[188:189], v[180:181]
	v_pk_fma_f32 v[188:189], v[198:199], v[190:191], v[222:223] neg_lo:[0,0,1] neg_hi:[0,0,1]
	v_pk_fma_f32 v[182:183], v[206:207], v[190:191], v[182:183]
	s_waitcnt vmcnt(0)
	v_pk_fma_f32 v[190:191], v[200:201], v[192:193], v[224:225] neg_lo:[0,0,1] neg_hi:[0,0,1]
	v_pk_fma_f32 v[184:185], v[208:209], v[192:193], v[184:185]
	v_pk_fma_f32 v[192:193], v[202:203], v[194:195], v[226:227] neg_lo:[0,0,1] neg_hi:[0,0,1]
	v_pk_fma_f32 v[186:187], v[210:211], v[194:195], v[186:187]
	v_pk_mul_f32 v[194:195], v[138:139], v[196:197]
	v_pk_mul_f32 v[188:189], v[138:139], v[188:189]
	v_pk_mul_f32 v[198:199], v[138:139], v[182:183]
	v_pk_mul_f32 v[182:183], v[138:139], v[190:191]
	v_pk_mul_f32 v[190:191], v[138:139], v[184:185]
	v_pk_mul_f32 v[184:185], v[138:139], v[192:193]
	v_pk_mul_f32 v[196:197], v[138:139], v[180:181]
	v_pk_mul_f32 v[192:193], v[138:139], v[186:187]
	v_cvt_pk_bf16_f32 v180, v194, v195
	v_cvt_pk_bf16_f32 v181, v188, v189
	v_cvt_pk_bf16_f32 v182, v182, v183
	v_cvt_pk_bf16_f32 v183, v184, v185
	v_cvt_pk_bf16_f32 v184, v196, v197
	v_cvt_pk_bf16_f32 v185, v198, v199
	v_cvt_pk_bf16_f32 v186, v190, v191
	v_cvt_pk_bf16_f32 v187, v192, v193
	global_store_dwordx4 v[212:213], v[180:183], off sc1
	global_store_dwordx4 v[212:213], v[184:187], off offset:128 sc1
	global_load_dwordx4 v[180:183], v[216:217], off
	s_nop 0
	global_load_dwordx4 v[184:187], v[216:217], off offset:16
	global_load_dwordx4 v[188:191], v[218:219], off
	global_load_dwordx4 v[192:195], v[218:219], off offset:16
	v_or_b32_e32 v204, v128, v176
	v_or_b32_e32 v196, v128, v177
	v_or_b32_e32 v128, v128, v178
	ds_read_b128 v[196:199], v196
	ds_read_b128 v[200:203], v179
	ds_read_b128 v[204:207], v204
	ds_read_b128 v[208:211], v128
	v_mad_i64_i32 v[212:213], s[72:73], v214, s81, v[144:145]
	s_waitcnt vmcnt(3) lgkmcnt(3)
	v_pk_mul_f32 v[214:215], v[196:197], v[180:181]
	s_waitcnt lgkmcnt(2)
	v_pk_mul_f32 v[180:181], v[200:201], v[180:181]
	v_pk_mul_f32 v[216:217], v[198:199], v[182:183]
	v_pk_mul_f32 v[182:183], v[202:203], v[182:183]
	s_waitcnt vmcnt(2) lgkmcnt(0)
	v_pk_mul_f32 v[218:219], v[208:209], v[184:185]
	v_pk_mul_f32 v[184:185], v[204:205], v[184:185]
	v_pk_mul_f32 v[220:221], v[210:211], v[186:187]
	v_pk_mul_f32 v[186:187], v[206:207], v[186:187]
	s_waitcnt vmcnt(1)
	v_pk_fma_f32 v[200:201], v[200:201], v[188:189], v[214:215] neg_lo:[0,0,1] neg_hi:[0,0,1]
	v_pk_fma_f32 v[180:181], v[196:197], v[188:189], v[180:181]
	v_pk_fma_f32 v[188:189], v[202:203], v[190:191], v[216:217] neg_lo:[0,0,1] neg_hi:[0,0,1]
	v_pk_fma_f32 v[182:183], v[198:199], v[190:191], v[182:183]
	s_waitcnt vmcnt(0)
	v_pk_fma_f32 v[190:191], v[204:205], v[192:193], v[218:219] neg_lo:[0,0,1] neg_hi:[0,0,1]
	v_pk_fma_f32 v[184:185], v[208:209], v[192:193], v[184:185]
	v_pk_fma_f32 v[192:193], v[206:207], v[194:195], v[220:221] neg_lo:[0,0,1] neg_hi:[0,0,1]
	v_pk_fma_f32 v[186:187], v[210:211], v[194:195], v[186:187]
	v_pk_mul_f32 v[194:195], v[138:139], v[200:201]
	v_pk_mul_f32 v[188:189], v[138:139], v[188:189]
	v_pk_mul_f32 v[198:199], v[138:139], v[182:183]
	v_pk_mul_f32 v[182:183], v[138:139], v[190:191]
	v_pk_mul_f32 v[190:191], v[138:139], v[184:185]
	v_pk_mul_f32 v[184:185], v[138:139], v[192:193]
	v_pk_mul_f32 v[196:197], v[138:139], v[180:181]
	v_pk_mul_f32 v[192:193], v[138:139], v[186:187]
	v_cvt_pk_bf16_f32 v180, v194, v195
	v_cvt_pk_bf16_f32 v181, v188, v189
	v_cvt_pk_bf16_f32 v182, v182, v183
	v_cvt_pk_bf16_f32 v183, v184, v185
	v_cvt_pk_bf16_f32 v184, v196, v197
	v_cvt_pk_bf16_f32 v185, v198, v199
	v_cvt_pk_bf16_f32 v186, v190, v191
	v_cvt_pk_bf16_f32 v187, v192, v193
	global_store_dwordx4 v[212:213], v[180:183], off sc1
	global_store_dwordx4 v[212:213], v[184:187], off offset:128 sc1
	s_cbranch_scc0 .LBB0_161
	s_mov_b64 s[72:73], 0

; template <int MODE> ...
;     ...
;         for (int it = 0; it < 16; ++it) {
;           int item = it * 512 + t2, row = item >> 5, q = item & 31;
;           uint4 v = *(const uint4*)(ls + row * 512 + ((q ^ (((row >> 2) & 3) << 2)) << 4));
;           *(uint4*)(ob + (long)row * ldc + q * 8) = v;
;         }
.LBB0_165:
	v_add_u32_e32 v3, s66, v170
	v_ashrrev_i32_e32 v4, 5, v3
	v_add_u32_e32 v5, 0x200, v3
	v_add_u32_e32 v6, 0x400, v3
	v_add_u32_e32 v3, 0x600, v3
	v_lshl_or_b32 v7, v4, 9, v2
	v_mad_i64_i32 v[20:21], s[68:69], v4, s81, v[0:1]
	v_ashrrev_i32_e32 v4, 5, v5
	v_ashrrev_i32_e32 v5, 5, v6
	v_ashrrev_i32_e32 v3, 5, v3
	v_lshl_or_b32 v8, v4, 9, v2
	v_lshl_or_b32 v12, v5, 9, v2
	v_lshl_or_b32 v16, v3, 9, v2
	v_mad_i64_i32 v[22:23], s[68:69], v4, s81, v[0:1]
	v_mad_i64_i32 v[24:25], s[68:69], v5, s81, v[0:1]
	ds_read_b128 v[4:7], v7
	ds_read_b128 v[8:11], v8
	ds_read_b128 v[12:15], v12
	ds_read_b128 v[16:19], v16
	s_addk_i32 s66, 0x800
	s_cmpk_eq_i32 s66, 0x2000
	v_mad_i64_i32 v[26:27], s[68:69], v3, s81, v[0:1]
	s_waitcnt lgkmcnt(0)
	global_store_dwordx4 v[20:21], v[4:7], off sc1
	global_store_dwordx4 v[22:23], v[8:11], off sc1
	global_store_dwordx4 v[24:25], v[12:15], off sc1
	global_store_dwordx4 v[26:27], v[16:19], off sc1
	s_cbranch_scc0 .LBB0_165
	s_branch .LBB0_150

; template <int MODE> ...
;     ...
;         for (int it = 0; it < 16; ++it) {
;           int item = it * 512 + t2, row = item >> 5, q = item & 31;
;           uint4 v = *(const uint4*)(ls + row * 512 + ((q ^ (((row >> 2) & 3) << 2)) << 4));
;           *(uint4*)(ob + (long)row * ldc + q * 8) = v;
;         }
.LBB0_181:
	v_add_u32_e32 v3, s62, v138
	v_ashrrev_i32_e32 v8, 5, v3
	v_add_u32_e32 v4, 0x200, v3
	v_add_u32_e32 v5, 0x400, v3
	v_add_u32_e32 v3, 0x600, v3
	v_ashrrev_i32_e32 v9, 31, v8
	v_ashrrev_i32_e32 v12, 5, v4
	v_ashrrev_i32_e32 v14, 5, v5
	v_ashrrev_i32_e32 v20, 5, v3
	v_lshl_or_b32 v6, v8, 9, v2
	v_lshlrev_b64 v[8:9], 12, v[8:9]
	v_lshl_or_b32 v3, v12, 9, v2
	v_ashrrev_i32_e32 v13, 31, v12
	v_lshl_or_b32 v16, v14, 9, v2
	v_ashrrev_i32_e32 v15, 31, v14
	v_lshl_or_b32 v17, v20, 9, v2
	ds_read_b128 v[4:7], v6
	v_lshl_add_u64 v[22:23], v[0:1], 0, v[8:9]
	ds_read_b128 v[8:11], v3
	v_lshlrev_b64 v[24:25], 12, v[12:13]
	v_lshlrev_b64 v[26:27], 12, v[14:15]
	ds_read_b128 v[12:15], v16
	ds_read_b128 v[16:19], v17
	s_addk_i32 s62, 0x800
	v_ashrrev_i32_e32 v21, 31, v20
	s_cmpk_eq_i32 s62, 0x2000
	v_lshlrev_b64 v[20:21], 12, v[20:21]
	v_lshl_add_u64 v[24:25], v[0:1], 0, v[24:25]
	v_lshl_add_u64 v[26:27], v[0:1], 0, v[26:27]
	v_lshl_add_u64 v[20:21], v[0:1], 0, v[20:21]
	s_waitcnt lgkmcnt(0)
	global_store_dwordx4 v[22:23], v[4:7], off sc1
	global_store_dwordx4 v[24:25], v[8:11], off sc1
	global_store_dwordx4 v[26:27], v[12:15], off sc1
	global_store_dwordx4 v[20:21], v[16:19], off sc1
	s_cbranch_scc0 .LBB0_181
	s_waitcnt lgkmcnt(0)
	s_barrier
	s_add_i32 s3, s3, s14
	s_cmp_gt_i32 s3, 15
	s_cbranch_scc0 .LBB0_170

; DEVI unsigned pack2(float a, float b) { f32v2 v = {a, b}; return __builtin_bit_cast(unsigned, __builtin_convertvector(v, bf16v2)); }
; DEVI void lds_barrier() { asm volatile("s_waitcnt lgkmcnt(0)" ::: "memory"); __builtin_amdgcn_s_barrier(); asm volatile("" ::: "memory"); }
; DEVI void tconv_store(const TcPre& R, u16* __restrict__ Wt, int K, int N, int t, float* lds, bool perm) {
;     ...
;     float* d = lds + (tid >> 5) * 129 + (tid & 31) * 4;
;     d[0] = R.a[0]; d[1] = R.a[1]; d[2] = R.a[2]; d[3] = R.a[3];
;     d[16 * 129] = R.b[0]; d[16 * 129 + 1] = R.b[1]; d[16 * 129 + 2] = R.b[2]; d[16 * 129 + 3] = R.b[3];
;     d[32 * 129] = R.c[0]; d[32 * 129 + 1] = R.c[1]; d[32 * 129 + 2] = R.c[2]; d[32 * 129 + 3] = R.c[3];
;     d[48 * 129] = R.d[0]; d[48 * 129 + 1] = R.d[1]; d[48 * 129 + 2] = R.d[2]; d[48 * 129 + 3] = R.d[3];
;   }
;   lds_barrier();
;   int n0p = !perm ? n0 : (n0 < DFF ? (n0 / 128) * 256 : ((n0 - DFF) / 128) * 256 + 128);
; #pragma unroll
;   for (int p = 0; p < 2; ++p) {
;     int item = p * 512 + tid, n = item >> 3, kg = item & 7;
;     const float* s = lds + (kg * 8) * 129 + n;
;     uint4 o;
;     o.x = pack2(s[0], s[129]); o.y = pack2(s[2 * 129], s[3 * 129]);
;     o.z = pack2(s[4 * 129], s[5 * 129]); o.w = pack2(s[6 * 129], s[7 * 129]);
;     *(uint4*)(Wt + (size_t)(n0p + n) * K + k0 + kg * 8) = o;
.Ldcv0_npd_st0:
	s_add_u32 s72, s84, s6
	s_addc_u32 s73, s85, 0
	s_add_u32 s78, s72, 0x80000
	s_addc_u32 s79, s73, 0
	s_waitcnt vmcnt(20)
	ds_write2_b32 v58, v168, v169 offset1:1
	ds_write2_b32 v58, v170, v171 offset0:2 offset1:3
	ds_write2_b32 v59, v172, v173 offset1:1
	ds_write2_b32 v59, v174, v175 offset0:2 offset1:3
	ds_write2_b32 v60, v176, v177 offset1:1
	ds_write2_b32 v60, v178, v179 offset0:2 offset1:3
	ds_write2_b32 v61, v180, v181 offset1:1
	ds_write2_b32 v61, v182, v183 offset0:2 offset1:3
	global_load_dwordx4 v[168:171], v54, s[68:69]
	s_add_u32 s68, s68, s70
	s_addc_u32 s69, s69, 0
	global_load_dwordx4 v[172:175], v54, s[68:69]
	s_add_u32 s68, s68, s70
	s_addc_u32 s69, s69, 0
	global_load_dwordx4 v[176:179], v54, s[68:69]
	s_add_u32 s68, s68, s70
	s_addc_u32 s69, s69, 0
	global_load_dwordx4 v[180:183], v54, s[68:69]
	s_mul_i32 s6, s70, 3
	s_sub_u32 s68, s68, s6
	s_subb_u32 s69, s69, 0
	s_add_u32 s68, s68, 0x200
	s_addc_u32 s69, s69, 0
	s_waitcnt lgkmcnt(0)
	s_barrier
	ds_read2_b32 v[104:105], v66 offset1:129
	ds_read2_b32 v[106:107], v67 offset1:129
	ds_read2_b32 v[108:109], v68 offset1:129
	ds_read2_b32 v[110:111], v69 offset1:129
	ds_read2_b32 v[112:113], v70 offset1:129
	ds_read2_b32 v[114:115], v71 offset1:129
	ds_read2_b32 v[116:117], v72 offset1:129
	ds_read2_b32 v[118:119], v73 offset1:129
	s_waitcnt lgkmcnt(4)
	v_cvt_pk_bf16_f32 v120, v104, v105
	v_cvt_pk_bf16_f32 v121, v106, v107
	v_cvt_pk_bf16_f32 v122, v108, v109
	v_cvt_pk_bf16_f32 v123, v110, v111
	global_store_dwordx4 v57, v[120:123], s[72:73] sc1
	s_waitcnt lgkmcnt(0)
	v_cvt_pk_bf16_f32 v124, v112, v113
	v_cvt_pk_bf16_f32 v125, v114, v115
	v_cvt_pk_bf16_f32 v126, v116, v117
	v_cvt_pk_bf16_f32 v127, v118, v119
	global_store_dwordx4 v57, v[124:127], s[78:79] sc1
	s_add_u32 s6, s86, 1
	s_cmp_eq_u32 s87, 0
	s_cbranch_scc1 .Ldcv0_np_st1
	s_lshl_b32 s7, s6, 8
	s_sub_u32 s15, s7, 0x5580
	s_cmp_lt_u32 s6, 86
	s_cselect_b32 s6, s7, s15
	s_lshl_b32 s6, s6, 13
	s_branch .Ldcv0_npd_st1

; DEVI unsigned pack2(float a, float b) { f32v2 v = {a, b}; return __builtin_bit_cast(unsigned, __builtin_convertvector(v, bf16v2)); }
; DEVI void lds_barrier() { asm volatile("s_waitcnt lgkmcnt(0)" ::: "memory"); __builtin_amdgcn_s_barrier(); asm volatile("" ::: "memory"); }
; DEVI void tconv_store(const TcPre& R, u16* __restrict__ Wt, int K, int N, int t, float* lds, bool perm) {
;     ...
;     float* d = lds + (tid >> 5) * 129 + (tid & 31) * 4;
;     d[0] = R.a[0]; d[1] = R.a[1]; d[2] = R.a[2]; d[3] = R.a[3];
;     d[16 * 129] = R.b[0]; d[16 * 129 + 1] = R.b[1]; d[16 * 129 + 2] = R.b[2]; d[16 * 129 + 3] = R.b[3];
;     d[32 * 129] = R.c[0]; d[32 * 129 + 1] = R.c[1]; d[32 * 129 + 2] = R.c[2]; d[32 * 129 + 3] = R.c[3];
;     d[48 * 129] = R.d[0]; d[48 * 129 + 1] = R.d[1]; d[48 * 129 + 2] = R.d[2]; d[48 * 129 + 3] = R.d[3];
;   }
;   lds_barrier();
;   int n0p = !perm ? n0 : (n0 < DFF ? (n0 / 128) * 256 : ((n0 - DFF) / 128) * 256 + 128);
; #pragma unroll
;   for (int p = 0; p < 2; ++p) {
;     int item = p * 512 + tid, n = item >> 3, kg = item & 7;
;     const float* s = lds + (kg * 8) * 129 + n;
;     uint4 o;
;     o.x = pack2(s[0], s[129]); o.y = pack2(s[2 * 129], s[3 * 129]);
;     o.z = pack2(s[4 * 129], s[5 * 129]); o.w = pack2(s[6 * 129], s[7 * 129]);
;     *(uint4*)(Wt + (size_t)(n0p + n) * K + k0 + kg * 8) = o;
.Ldcv0_npd_st1:
	s_add_u32 s72, s84, s6
	s_addc_u32 s73, s85, 0
	s_add_u32 s78, s72, 0x80000
	s_addc_u32 s79, s73, 0
	s_waitcnt vmcnt(20)
	ds_write2_b32 v62, v184, v185 offset1:1
	ds_write2_b32 v62, v186, v187 offset0:2 offset1:3
	ds_write2_b32 v63, v188, v189 offset1:1
	ds_write2_b32 v63, v190, v191 offset0:2 offset1:3
	ds_write2_b32 v64, v192, v193 offset1:1
	ds_write2_b32 v64, v194, v195 offset0:2 offset1:3
	ds_write2_b32 v65, v196, v197 offset1:1
	ds_write2_b32 v65, v198, v199 offset0:2 offset1:3
	global_load_dwordx4 v[184:187], v54, s[68:69]
	s_add_u32 s68, s68, s70
	s_addc_u32 s69, s69, 0
	global_load_dwordx4 v[188:191], v54, s[68:69]
	s_add_u32 s68, s68, s70
	s_addc_u32 s69, s69, 0
	global_load_dwordx4 v[192:195], v54, s[68:69]
	s_add_u32 s68, s68, s70
	s_addc_u32 s69, s69, 0
	global_load_dwordx4 v[196:199], v54, s[68:69]
	s_mul_i32 s6, s70, 3
	s_sub_u32 s68, s68, s6
	s_subb_u32 s69, s69, 0
	s_add_u32 s68, s68, 0x200
	s_addc_u32 s69, s69, 0
	s_waitcnt lgkmcnt(0)
	s_barrier
	ds_read2_b32 v[104:105], v74 offset1:129
	ds_read2_b32 v[106:107], v75 offset1:129
	ds_read2_b32 v[108:109], v76 offset1:129
	ds_read2_b32 v[110:111], v77 offset1:129
	ds_read2_b32 v[112:113], v78 offset1:129
	ds_read2_b32 v[114:115], v79 offset1:129
	ds_read2_b32 v[116:117], v80 offset1:129
	ds_read2_b32 v[118:119], v81 offset1:129
	s_waitcnt lgkmcnt(4)
	v_cvt_pk_bf16_f32 v120, v104, v105
	v_cvt_pk_bf16_f32 v121, v106, v107
	v_cvt_pk_bf16_f32 v122, v108, v109
	v_cvt_pk_bf16_f32 v123, v110, v111
	global_store_dwordx4 v57, v[120:123], s[72:73] sc1
	s_waitcnt lgkmcnt(0)
	v_cvt_pk_bf16_f32 v124, v112, v113
	v_cvt_pk_bf16_f32 v125, v114, v115
	v_cvt_pk_bf16_f32 v126, v116, v117
	v_cvt_pk_bf16_f32 v127, v118, v119
	global_store_dwordx4 v57, v[124:127], s[78:79] sc1
	s_add_u32 s6, s86, 2
	s_cmp_eq_u32 s87, 0
	s_cbranch_scc1 .Ldcv0_np_st2
	s_lshl_b32 s7, s6, 8
	s_sub_u32 s15, s7, 0x5580
	s_cmp_lt_u32 s6, 86
	s_cselect_b32 s6, s7, s15
	s_lshl_b32 s6, s6, 13
	s_branch .Ldcv0_npd_st2

; DEVI unsigned pack2(float a, float b) { f32v2 v = {a, b}; return __builtin_bit_cast(unsigned, __builtin_convertvector(v, bf16v2)); }
; DEVI void lds_barrier() { asm volatile("s_waitcnt lgkmcnt(0)" ::: "memory"); __builtin_amdgcn_s_barrier(); asm volatile("" ::: "memory"); }
; DEVI void tconv_store(const TcPre& R, u16* __restrict__ Wt, int K, int N, int t, float* lds, bool perm) {
;     ...
;     float* d = lds + (tid >> 5) * 129 + (tid & 31) * 4;
;     d[0] = R.a[0]; d[1] = R.a[1]; d[2] = R.a[2]; d[3] = R.a[3];
;     d[16 * 129] = R.b[0]; d[16 * 129 + 1] = R.b[1]; d[16 * 129 + 2] = R.b[2]; d[16 * 129 + 3] = R.b[3];
;     d[32 * 129] = R.c[0]; d[32 * 129 + 1] = R.c[1]; d[32 * 129 + 2] = R.c[2]; d[32 * 129 + 3] = R.c[3];
;     d[48 * 129] = R.d[0]; d[48 * 129 + 1] = R.d[1]; d[48 * 129 + 2] = R.d[2]; d[48 * 129 + 3] = R.d[3];
;   }
;   lds_barrier();
;   int n0p = !perm ? n0 : (n0 < DFF ? (n0 / 128) * 256 : ((n0 - DFF) / 128) * 256 + 128);
; #pragma unroll
;   for (int p = 0; p < 2; ++p) {
;     int item = p * 512 + tid, n = item >> 3, kg = item & 7;
;     const float* s = lds + (kg * 8) * 129 + n;
;     uint4 o;
;     o.x = pack2(s[0], s[129]); o.y = pack2(s[2 * 129], s[3 * 129]);
;     o.z = pack2(s[4 * 129], s[5 * 129]); o.w = pack2(s[6 * 129], s[7 * 129]);
;     *(uint4*)(Wt + (size_t)(n0p + n) * K + k0 + kg * 8) = o;
.Ldcv0_npd_st2:
	s_add_u32 s72, s84, s6
	s_addc_u32 s73, s85, 0
	s_add_u32 s78, s72, 0x80000
	s_addc_u32 s79, s73, 0
	s_waitcnt vmcnt(20)
	ds_write2_b32 v58, v200, v201 offset1:1
	ds_write2_b32 v58, v202, v203 offset0:2 offset1:3
	ds_write2_b32 v59, v204, v205 offset1:1
	ds_write2_b32 v59, v206, v207 offset0:2 offset1:3
	ds_write2_b32 v60, v208, v209 offset1:1
	ds_write2_b32 v60, v210, v211 offset0:2 offset1:3
	ds_write2_b32 v61, v212, v213 offset1:1
	ds_write2_b32 v61, v214, v215 offset0:2 offset1:3
	global_load_dwordx4 v[200:203], v54, s[68:69]
	s_add_u32 s68, s68, s70
	s_addc_u32 s69, s69, 0
	global_load_dwordx4 v[204:207], v54, s[68:69]
	s_add_u32 s68, s68, s70
	s_addc_u32 s69, s69, 0
	global_load_dwordx4 v[208:211], v54, s[68:69]
	s_add_u32 s68, s68, s70
	s_addc_u32 s69, s69, 0
	global_load_dwordx4 v[212:215], v54, s[68:69]
	s_mul_i32 s6, s70, 3
	s_sub_u32 s68, s68, s6
	s_subb_u32 s69, s69, 0
	s_add_u32 s68, s68, 0x200
	s_addc_u32 s69, s69, 0
	s_waitcnt lgkmcnt(0)
	s_barrier
	ds_read2_b32 v[104:105], v66 offset1:129
	ds_read2_b32 v[106:107], v67 offset1:129
	ds_read2_b32 v[108:109], v68 offset1:129
	ds_read2_b32 v[110:111], v69 offset1:129
	ds_read2_b32 v[112:113], v70 offset1:129
	ds_read2_b32 v[114:115], v71 offset1:129
	ds_read2_b32 v[116:117], v72 offset1:129
	ds_read2_b32 v[118:119], v73 offset1:129
	s_waitcnt lgkmcnt(4)
	v_cvt_pk_bf16_f32 v120, v104, v105
	v_cvt_pk_bf16_f32 v121, v106, v107
	v_cvt_pk_bf16_f32 v122, v108, v109
	v_cvt_pk_bf16_f32 v123, v110, v111
	global_store_dwordx4 v57, v[120:123], s[72:73] sc1
	s_waitcnt lgkmcnt(0)
	v_cvt_pk_bf16_f32 v124, v112, v113
	v_cvt_pk_bf16_f32 v125, v114, v115
	v_cvt_pk_bf16_f32 v126, v116, v117
	v_cvt_pk_bf16_f32 v127, v118, v119
	global_store_dwordx4 v57, v[124:127], s[78:79] sc1
	s_add_u32 s6, s86, 3
	s_cmp_eq_u32 s87, 0
	s_cbranch_scc1 .Ldcv0_np_st3
	s_lshl_b32 s7, s6, 8
	s_sub_u32 s15, s7, 0x5580
	s_cmp_lt_u32 s6, 86
	s_cselect_b32 s6, s7, s15
	s_lshl_b32 s6, s6, 13
	s_branch .Ldcv0_npd_st3

; DEVI unsigned pack2(float a, float b) { f32v2 v = {a, b}; return __builtin_bit_cast(unsigned, __builtin_convertvector(v, bf16v2)); }
; DEVI void lds_barrier() { asm volatile("s_waitcnt lgkmcnt(0)" ::: "memory"); __builtin_amdgcn_s_barrier(); asm volatile("" ::: "memory"); }
; DEVI void tconv_store(const TcPre& R, u16* __restrict__ Wt, int K, int N, int t, float* lds, bool perm) {
;     ...
;     int item = p * 512 + tid, n = item >> 3, kg = item & 7;
;     const float* s = lds + (kg * 8) * 129 + n;
;     uint4 o;
;     o.x = pack2(s[0], s[129]); o.y = pack2(s[2 * 129], s[3 * 129]);
;     o.z = pack2(s[4 * 129], s[5 * 129]); o.w = pack2(s[6 * 129], s[7 * 129]);
;     *(uint4*)(Wt + (size_t)(n0p + n) * K + k0 + kg * 8) = o;
; DEVI void deferred_conv(const Params& p, char* smem, const int which) {
;     ...
;     if (threadIdx.x == 0) *qs = tlo + (int)atomicAdd(ctr, (unsigned)DQ_GRAB);
;     lds_barrier();
;     int base = *qs;
.Ldcv0_b_st:
	s_waitcnt lgkmcnt(0)
	s_barrier
	ds_read2_b32 v[104:105], v74 offset1:129
	ds_read2_b32 v[106:107], v75 offset1:129
	ds_read2_b32 v[108:109], v76 offset1:129
	ds_read2_b32 v[110:111], v77 offset1:129
	ds_read2_b32 v[112:113], v78 offset1:129
	ds_read2_b32 v[114:115], v79 offset1:129
	ds_read2_b32 v[116:117], v80 offset1:129
	ds_read2_b32 v[118:119], v81 offset1:129
	ds_read_b32 v82, v84
	s_waitcnt lgkmcnt(5)
	v_cvt_pk_bf16_f32 v120, v104, v105
	v_cvt_pk_bf16_f32 v121, v106, v107
	v_cvt_pk_bf16_f32 v122, v108, v109
	v_cvt_pk_bf16_f32 v123, v110, v111
	global_store_dwordx4 v57, v[120:123], s[72:73] sc1
	s_waitcnt lgkmcnt(1)
	v_cvt_pk_bf16_f32 v124, v112, v113
	v_cvt_pk_bf16_f32 v125, v114, v115
	v_cvt_pk_bf16_f32 v126, v116, v117
	v_cvt_pk_bf16_f32 v127, v118, v119
	global_store_dwordx4 v57, v[124:127], s[78:79] sc1
	s_waitcnt lgkmcnt(0)
	v_readfirstlane_b32 s5, v82
	s_mov_b32 s3, s4
	s_mov_b32 s4, s5
	s_branch .Ldcv0_loop

; DEVI unsigned pack2(float a, float b) { f32v2 v = {a, b}; return __builtin_bit_cast(unsigned, __builtin_convertvector(v, bf16v2)); }
; DEVI void lds_barrier() { asm volatile("s_waitcnt lgkmcnt(0)" ::: "memory"); __builtin_amdgcn_s_barrier(); asm volatile("" ::: "memory"); }
; DEVI void tconv_store(const TcPre& R, u16* __restrict__ Wt, int K, int N, int t, float* lds, bool perm) {
;     ...
;     float* d = lds + (tid >> 5) * 129 + (tid & 31) * 4;
;     d[0] = R.a[0]; d[1] = R.a[1]; d[2] = R.a[2]; d[3] = R.a[3];
;     d[16 * 129] = R.b[0]; d[16 * 129 + 1] = R.b[1]; d[16 * 129 + 2] = R.b[2]; d[16 * 129 + 3] = R.b[3];
;     d[32 * 129] = R.c[0]; d[32 * 129 + 1] = R.c[1]; d[32 * 129 + 2] = R.c[2]; d[32 * 129 + 3] = R.c[3];
;     d[48 * 129] = R.d[0]; d[48 * 129 + 1] = R.d[1]; d[48 * 129 + 2] = R.d[2]; d[48 * 129 + 3] = R.d[3];
;   }
;   lds_barrier();
;   int n0p = !perm ? n0 : (n0 < DFF ? (n0 / 128) * 256 : ((n0 - DFF) / 128) * 256 + 128);
; #pragma unroll
;   for (int p = 0; p < 2; ++p) {
;     int item = p * 512 + tid, n = item >> 3, kg = item & 7;
;     const float* s = lds + (kg * 8) * 129 + n;
;     uint4 o;
;     o.x = pack2(s[0], s[129]); o.y = pack2(s[2 * 129], s[3 * 129]);
;     o.z = pack2(s[4 * 129], s[5 * 129]); o.w = pack2(s[6 * 129], s[7 * 129]);
;     *(uint4*)(Wt + (size_t)(n0p + n) * K + k0 + kg * 8) = o;
.Ldcv0_npd_la0:
	s_add_u32 s72, s84, s6
	s_addc_u32 s73, s85, 0
	s_add_u32 s78, s72, 0x80000
	s_addc_u32 s79, s73, 0
	ds_write2_b32 v58, v168, v169 offset1:1
	ds_write2_b32 v58, v170, v171 offset0:2 offset1:3
	ds_write2_b32 v59, v172, v173 offset1:1
	ds_write2_b32 v59, v174, v175 offset0:2 offset1:3
	ds_write2_b32 v60, v176, v177 offset1:1
	ds_write2_b32 v60, v178, v179 offset0:2 offset1:3
	ds_write2_b32 v61, v180, v181 offset1:1
	ds_write2_b32 v61, v182, v183 offset0:2 offset1:3
	s_waitcnt lgkmcnt(0)
	s_barrier
	ds_read2_b32 v[104:105], v66 offset1:129
	ds_read2_b32 v[106:107], v67 offset1:129
	ds_read2_b32 v[108:109], v68 offset1:129
	ds_read2_b32 v[110:111], v69 offset1:129
	ds_read2_b32 v[112:113], v70 offset1:129
	ds_read2_b32 v[114:115], v71 offset1:129
	ds_read2_b32 v[116:117], v72 offset1:129
	ds_read2_b32 v[118:119], v73 offset1:129
	s_waitcnt lgkmcnt(4)
	v_cvt_pk_bf16_f32 v120, v104, v105
	v_cvt_pk_bf16_f32 v121, v106, v107
	v_cvt_pk_bf16_f32 v122, v108, v109
	v_cvt_pk_bf16_f32 v123, v110, v111
	global_store_dwordx4 v57, v[120:123], s[72:73] sc1
	s_waitcnt lgkmcnt(0)
	v_cvt_pk_bf16_f32 v124, v112, v113
	v_cvt_pk_bf16_f32 v125, v114, v115
	v_cvt_pk_bf16_f32 v126, v116, v117
	v_cvt_pk_bf16_f32 v127, v118, v119
	global_store_dwordx4 v57, v[124:127], s[78:79] sc1
	s_add_u32 s6, s86, 1
	s_cmp_eq_u32 s87, 0
	s_cbranch_scc1 .Ldcv0_np_la1
	s_lshl_b32 s7, s6, 8
	s_sub_u32 s15, s7, 0x5580
	s_cmp_lt_u32 s6, 86
	s_cselect_b32 s6, s7, s15
	s_lshl_b32 s6, s6, 13
	s_branch .Ldcv0_npd_la1

; DEVI unsigned pack2(float a, float b) { f32v2 v = {a, b}; return __builtin_bit_cast(unsigned, __builtin_convertvector(v, bf16v2)); }
; DEVI void lds_barrier() { asm volatile("s_waitcnt lgkmcnt(0)" ::: "memory"); __builtin_amdgcn_s_barrier(); asm volatile("" ::: "memory"); }
; DEVI void tconv_store(const TcPre& R, u16* __restrict__ Wt, int K, int N, int t, float* lds, bool perm) {
;     ...
;     float* d = lds + (tid >> 5) * 129 + (tid & 31) * 4;
;     d[0] = R.a[0]; d[1] = R.a[1]; d[2] = R.a[2]; d[3] = R.a[3];
;     d[16 * 129] = R.b[0]; d[16 * 129 + 1] = R.b[1]; d[16 * 129 + 2] = R.b[2]; d[16 * 129 + 3] = R.b[3];
;     d[32 * 129] = R.c[0]; d[32 * 129 + 1] = R.c[1]; d[32 * 129 + 2] = R.c[2]; d[32 * 129 + 3] = R.c[3];
;     d[48 * 129] = R.d[0]; d[48 * 129 + 1] = R.d[1]; d[48 * 129 + 2] = R.d[2]; d[48 * 129 + 3] = R.d[3];
;   }
;   lds_barrier();
;   int n0p = !perm ? n0 : (n0 < DFF ? (n0 / 128) * 256 : ((n0 - DFF) / 128) * 256 + 128);
; #pragma unroll
;   for (int p = 0; p < 2; ++p) {
;     int item = p * 512 + tid, n = item >> 3, kg = item & 7;
;     const float* s = lds + (kg * 8) * 129 + n;
;     uint4 o;
;     o.x = pack2(s[0], s[129]); o.y = pack2(s[2 * 129], s[3 * 129]);
;     o.z = pack2(s[4 * 129], s[5 * 129]); o.w = pack2(s[6 * 129], s[7 * 129]);
;     *(uint4*)(Wt + (size_t)(n0p + n) * K + k0 + kg * 8) = o;
.Ldcv0_npd_la1:
	s_add_u32 s72, s84, s6
	s_addc_u32 s73, s85, 0
	s_add_u32 s78, s72, 0x80000
	s_addc_u32 s79, s73, 0
	ds_write2_b32 v62, v184, v185 offset1:1
	ds_write2_b32 v62, v186, v187 offset0:2 offset1:3
	ds_write2_b32 v63, v188, v189 offset1:1
	ds_write2_b32 v63, v190, v191 offset0:2 offset1:3
	ds_write2_b32 v64, v192, v193 offset1:1
	ds_write2_b32 v64, v194, v195 offset0:2 offset1:3
	ds_write2_b32 v65, v196, v197 offset1:1
	ds_write2_b32 v65, v198, v199 offset0:2 offset1:3
	s_waitcnt lgkmcnt(0)
	s_barrier
	ds_read2_b32 v[104:105], v74 offset1:129
	ds_read2_b32 v[106:107], v75 offset1:129
	ds_read2_b32 v[108:109], v76 offset1:129
	ds_read2_b32 v[110:111], v77 offset1:129
	ds_read2_b32 v[112:113], v78 offset1:129
	ds_read2_b32 v[114:115], v79 offset1:129
	ds_read2_b32 v[116:117], v80 offset1:129
	ds_read2_b32 v[118:119], v81 offset1:129
	s_waitcnt lgkmcnt(4)
	v_cvt_pk_bf16_f32 v120, v104, v105
	v_cvt_pk_bf16_f32 v121, v106, v107
	v_cvt_pk_bf16_f32 v122, v108, v109
	v_cvt_pk_bf16_f32 v123, v110, v111
	global_store_dwordx4 v57, v[120:123], s[72:73] sc1
	s_waitcnt lgkmcnt(0)
	v_cvt_pk_bf16_f32 v124, v112, v113
	v_cvt_pk_bf16_f32 v125, v114, v115
	v_cvt_pk_bf16_f32 v126, v116, v117
	v_cvt_pk_bf16_f32 v127, v118, v119
	global_store_dwordx4 v57, v[124:127], s[78:79] sc1
	s_add_u32 s6, s86, 2
	s_cmp_eq_u32 s87, 0
	s_cbranch_scc1 .Ldcv0_np_la2
	s_lshl_b32 s7, s6, 8
	s_sub_u32 s15, s7, 0x5580
	s_cmp_lt_u32 s6, 86
	s_cselect_b32 s6, s7, s15
	s_lshl_b32 s6, s6, 13
	s_branch .Ldcv0_npd_la2

; DEVI unsigned pack2(float a, float b) { f32v2 v = {a, b}; return __builtin_bit_cast(unsigned, __builtin_convertvector(v, bf16v2)); }
; DEVI void lds_barrier() { asm volatile("s_waitcnt lgkmcnt(0)" ::: "memory"); __builtin_amdgcn_s_barrier(); asm volatile("" ::: "memory"); }
; DEVI void tconv_store(const TcPre& R, u16* __restrict__ Wt, int K, int N, int t, float* lds, bool perm) {
;     ...
;     float* d = lds + (tid >> 5) * 129 + (tid & 31) * 4;
;     d[0] = R.a[0]; d[1] = R.a[1]; d[2] = R.a[2]; d[3] = R.a[3];
;     d[16 * 129] = R.b[0]; d[16 * 129 + 1] = R.b[1]; d[16 * 129 + 2] = R.b[2]; d[16 * 129 + 3] = R.b[3];
;     d[32 * 129] = R.c[0]; d[32 * 129 + 1] = R.c[1]; d[32 * 129 + 2] = R.c[2]; d[32 * 129 + 3] = R.c[3];
;     d[48 * 129] = R.d[0]; d[48 * 129 + 1] = R.d[1]; d[48 * 129 + 2] = R.d[2]; d[48 * 129 + 3] = R.d[3];
;   }
;   lds_barrier();
;   int n0p = !perm ? n0 : (n0 < DFF ? (n0 / 128) * 256 : ((n0 - DFF) / 128) * 256 + 128);
; #pragma unroll
;   for (int p = 0; p < 2; ++p) {
;     int item = p * 512 + tid, n = item >> 3, kg = item & 7;
;     const float* s = lds + (kg * 8) * 129 + n;
;     uint4 o;
;     o.x = pack2(s[0], s[129]); o.y = pack2(s[2 * 129], s[3 * 129]);
;     o.z = pack2(s[4 * 129], s[5 * 129]); o.w = pack2(s[6 * 129], s[7 * 129]);
;     *(uint4*)(Wt + (size_t)(n0p + n) * K + k0 + kg * 8) = o;
.Ldcv0_npd_la2:
	s_add_u32 s72, s84, s6
	s_addc_u32 s73, s85, 0
	s_add_u32 s78, s72, 0x80000
	s_addc_u32 s79, s73, 0
	ds_write2_b32 v58, v200, v201 offset1:1
	ds_write2_b32 v58, v202, v203 offset0:2 offset1:3
	ds_write2_b32 v59, v204, v205 offset1:1
	ds_write2_b32 v59, v206, v207 offset0:2 offset1:3
	ds_write2_b32 v60, v208, v209 offset1:1
	ds_write2_b32 v60, v210, v211 offset0:2 offset1:3
	ds_write2_b32 v61, v212, v213 offset1:1
	ds_write2_b32 v61, v214, v215 offset0:2 offset1:3
	s_waitcnt lgkmcnt(0)
	s_barrier
	ds_read2_b32 v[104:105], v66 offset1:129
	ds_read2_b32 v[106:107], v67 offset1:129
	ds_read2_b32 v[108:109], v68 offset1:129
	ds_read2_b32 v[110:111], v69 offset1:129
	ds_read2_b32 v[112:113], v70 offset1:129
	ds_read2_b32 v[114:115], v71 offset1:129
	ds_read2_b32 v[116:117], v72 offset1:129
	ds_read2_b32 v[118:119], v73 offset1:129
	s_waitcnt lgkmcnt(4)
	v_cvt_pk_bf16_f32 v120, v104, v105
	v_cvt_pk_bf16_f32 v121, v106, v107
	v_cvt_pk_bf16_f32 v122, v108, v109
	v_cvt_pk_bf16_f32 v123, v110, v111
	global_store_dwordx4 v57, v[120:123], s[72:73] sc1
	s_waitcnt lgkmcnt(0)
	v_cvt_pk_bf16_f32 v124, v112, v113
	v_cvt_pk_bf16_f32 v125, v114, v115
	v_cvt_pk_bf16_f32 v126, v116, v117
	v_cvt_pk_bf16_f32 v127, v118, v119
	global_store_dwordx4 v57, v[124:127], s[78:79] sc1
	s_add_u32 s6, s86, 3
	s_cmp_eq_u32 s87, 0
	s_cbranch_scc1 .Ldcv0_np_la3
	s_lshl_b32 s7, s6, 8
	s_sub_u32 s15, s7, 0x5580
	s_cmp_lt_u32 s6, 86
	s_cselect_b32 s6, s7, s15
	s_lshl_b32 s6, s6, 13
	s_branch .Ldcv0_npd_la3

; DEVI unsigned pack2(float a, float b) { f32v2 v = {a, b}; return __builtin_bit_cast(unsigned, __builtin_convertvector(v, bf16v2)); }
; DEVI void lds_barrier() { asm volatile("s_waitcnt lgkmcnt(0)" ::: "memory"); __builtin_amdgcn_s_barrier(); asm volatile("" ::: "memory"); }
; DEVI void tconv_store(const TcPre& R, u16* __restrict__ Wt, int K, int N, int t, float* lds, bool perm) {
;     ...
;     float* d = lds + (tid >> 5) * 129 + (tid & 31) * 4;
;     d[0] = R.a[0]; d[1] = R.a[1]; d[2] = R.a[2]; d[3] = R.a[3];
;     d[16 * 129] = R.b[0]; d[16 * 129 + 1] = R.b[1]; d[16 * 129 + 2] = R.b[2]; d[16 * 129 + 3] = R.b[3];
;     d[32 * 129] = R.c[0]; d[32 * 129 + 1] = R.c[1]; d[32 * 129 + 2] = R.c[2]; d[32 * 129 + 3] = R.c[3];
;     d[48 * 129] = R.d[0]; d[48 * 129 + 1] = R.d[1]; d[48 * 129 + 2] = R.d[2]; d[48 * 129 + 3] = R.d[3];
;   }
;   lds_barrier();
;   int n0p = !perm ? n0 : (n0 < DFF ? (n0 / 128) * 256 : ((n0 - DFF) / 128) * 256 + 128);
; #pragma unroll
;   for (int p = 0; p < 2; ++p) {
;     int item = p * 512 + tid, n = item >> 3, kg = item & 7;
;     const float* s = lds + (kg * 8) * 129 + n;
;     uint4 o;
;     o.x = pack2(s[0], s[129]); o.y = pack2(s[2 * 129], s[3 * 129]);
;     o.z = pack2(s[4 * 129], s[5 * 129]); o.w = pack2(s[6 * 129], s[7 * 129]);
;     *(uint4*)(Wt + (size_t)(n0p + n) * K + k0 + kg * 8) = o;
.Ldcv0_npd_la3:
	s_add_u32 s72, s84, s6
	s_addc_u32 s73, s85, 0
	s_add_u32 s78, s72, 0x80000
	s_addc_u32 s79, s73, 0
	ds_write2_b32 v62, v216, v217 offset1:1
	ds_write2_b32 v62, v218, v219 offset0:2 offset1:3
	ds_write2_b32 v63, v220, v221 offset1:1
	ds_write2_b32 v63, v222, v223 offset0:2 offset1:3
	ds_write2_b32 v64, v224, v225 offset1:1
	ds_write2_b32 v64, v226, v227 offset0:2 offset1:3
	ds_write2_b32 v65, v228, v229 offset1:1
	ds_write2_b32 v65, v230, v231 offset0:2 offset1:3
	s_waitcnt lgkmcnt(0)
	s_barrier
	ds_read2_b32 v[104:105], v74 offset1:129
	ds_read2_b32 v[106:107], v75 offset1:129
	ds_read2_b32 v[108:109], v76 offset1:129
	ds_read2_b32 v[110:111], v77 offset1:129
	ds_read2_b32 v[112:113], v78 offset1:129
	ds_read2_b32 v[114:115], v79 offset1:129
	ds_read2_b32 v[116:117], v80 offset1:129
	ds_read2_b32 v[118:119], v81 offset1:129
	s_waitcnt lgkmcnt(4)
	v_cvt_pk_bf16_f32 v120, v104, v105
	v_cvt_pk_bf16_f32 v121, v106, v107
	v_cvt_pk_bf16_f32 v122, v108, v109
	v_cvt_pk_bf16_f32 v123, v110, v111
	global_store_dwordx4 v57, v[120:123], s[72:73] sc1
	s_waitcnt lgkmcnt(0)
	v_cvt_pk_bf16_f32 v124, v112, v113
	v_cvt_pk_bf16_f32 v125, v114, v115
	v_cvt_pk_bf16_f32 v126, v116, v117
	v_cvt_pk_bf16_f32 v127, v118, v119
	global_store_dwordx4 v57, v[124:127], s[78:79] sc1

; __device__ NOINL void phase_scan_combine(const Params& p) {
;     ...
;     for (int cc = 0; cc < 64; ++cc) {
;       int c = dir ? 63 - cc : cc;
;       float uu[8]; unpack8(*(const uint4*)(u + (size_t)c * 16384), uu);
;       float4 d0 = *(const float4*)(dc + c * 128), d1 = *(const float4*)(dc + c * 128 + 4);
;       *(uint4*)(so + (size_t)c * 16384) = pack8(s);
;       s[0] = d0.x * s[0] + uu[0]; s[1] = d0.y * s[1] + uu[1]; s[2] = d0.z * s[2] + uu[2]; s[3] = d0.w * s[3] + uu[3];
;       s[4] = d1.x * s[4] + uu[4]; s[5] = d1.y * s[5] + uu[5]; s[6] = d1.z * s[6] + uu[6]; s[7] = d1.w * s[7] + uu[7];
;     }
.LBB0_373:
	s_add_i32 s44, s35, 15
	v_mov_b32_e32 v4, s34
	s_add_i32 s45, s35, 14
	s_add_i32 s48, s34, 1
	s_add_i32 s49, s35, 13
	s_add_i32 s50, s34, 2
	s_add_i32 s51, s35, 12
	s_add_i32 s60, s34, 3
	s_add_i32 s61, s35, 11
	s_add_i32 s62, s34, 4
	s_add_i32 s63, s35, 10
	s_add_i32 s64, s34, 5
	s_add_i32 s65, s35, 9
	s_add_i32 s66, s34, 6
	s_add_i32 s67, s35, 8
	s_add_i32 s68, s34, 7
	v_mov_b32_e32 v20, s44
	s_add_i32 s69, s35, 7
	s_add_i32 s70, s34, 8
	s_add_i32 s71, s35, 6
	s_add_i32 s72, s34, 9
	s_add_i32 s73, s35, 5
	s_add_i32 s74, s34, 10
	s_add_i32 s75, s35, 4
	s_add_i32 s76, s34, 11
	v_mov_b32_e32 v22, s45
	v_mov_b32_e32 v24, s48
	v_mov_b32_e32 v26, s49
	v_mov_b32_e32 v28, s50
	v_mov_b32_e32 v30, s51
	v_mov_b32_e32 v32, s60
	v_mov_b32_e32 v34, s61
	v_mov_b32_e32 v36, s62
	v_mov_b32_e32 v38, s63
	v_mov_b32_e32 v41, s64
	v_mov_b32_e32 v42, s65
	v_mov_b32_e32 v44, s66
	v_mov_b32_e32 v46, s67
	v_mov_b32_e32 v48, s68
	v_cndmask_b32_e32 v20, v20, v4, vcc
	s_add_i32 s77, s35, 3
	s_add_i32 s78, s34, 12
	s_add_i32 s79, s35, 2
	s_add_i32 s81, s34, 13
	v_mov_b32_e32 v50, s69
	v_mov_b32_e32 v51, s70
	v_mov_b32_e32 v52, s71
	v_mov_b32_e32 v53, s72
	v_mov_b32_e32 v54, s73
	v_mov_b32_e32 v55, s74
	v_mov_b32_e32 v56, s75
	v_mov_b32_e32 v57, s76
	v_cndmask_b32_e32 v62, v22, v24, vcc
	v_cndmask_b32_e32 v78, v26, v28, vcc
	v_cndmask_b32_e32 v79, v30, v32, vcc
	v_cndmask_b32_e32 v80, v34, v36, vcc
	v_cndmask_b32_e32 v41, v38, v41, vcc
	v_cndmask_b32_e32 v84, v42, v44, vcc
	v_cndmask_b32_e32 v88, v46, v48, vcc
	v_lshlrev_b32_e32 v4, 15, v20
	v_mov_b32_e32 v21, v5
	v_cvt_pk_bf16_f32 v0, v12, v13
	v_cvt_pk_bf16_f32 v1, v14, v15
	v_cvt_pk_bf16_f32 v2, v16, v17
	v_cvt_pk_bf16_f32 v3, v18, v19
	v_mov_b32_e32 v25, v5
	v_mov_b32_e32 v27, v5
	v_mov_b32_e32 v29, v5
	v_mov_b32_e32 v31, v5
	v_mov_b32_e32 v33, v5
	v_mov_b32_e32 v35, v5
	v_mov_b32_e32 v58, s77
	v_mov_b32_e32 v59, s78
	v_mov_b32_e32 v60, s79
	v_mov_b32_e32 v61, s81
	v_cndmask_b32_e32 v92, v50, v51, vcc
	v_cndmask_b32_e32 v96, v52, v53, vcc
	v_cndmask_b32_e32 v100, v54, v55, vcc
	v_cndmask_b32_e32 v104, v56, v57, vcc
	v_lshlrev_b32_e32 v20, 7, v20
	v_lshlrev_b32_e32 v24, 7, v78
	v_lshlrev_b32_e32 v26, 7, v79
	v_lshlrev_b32_e32 v28, 7, v80
	v_lshlrev_b32_e32 v30, 7, v41
	v_lshlrev_b32_e32 v32, 7, v84
	v_lshlrev_b32_e32 v34, 7, v88
	v_lshl_add_u64 v[50:51], v[6:7], 0, v[4:5]
	v_lshl_add_u64 v[54:55], v[10:11], 0, v[4:5]
	v_lshlrev_b32_e32 v4, 15, v62
	v_mov_b32_e32 v23, v5
	v_mov_b32_e32 v37, v5
	v_mov_b32_e32 v39, v5
	v_mov_b32_e32 v43, v5
	v_mov_b32_e32 v45, v5
	v_cndmask_b32_e32 v108, v58, v59, vcc
	v_cndmask_b32_e32 v112, v60, v61, vcc
	v_lshlrev_b32_e32 v22, 7, v62
	v_lshlrev_b32_e32 v36, 7, v92
	v_lshlrev_b32_e32 v38, 7, v96
	v_lshlrev_b32_e32 v42, 7, v100
	v_lshlrev_b32_e32 v44, 7, v104
	v_lshl_add_u64 v[52:53], v[20:21], 2, v[8:9]
	v_lshl_add_u64 v[58:59], v[24:25], 2, v[8:9]
	v_lshl_add_u64 v[60:61], v[26:27], 2, v[8:9]
	v_lshl_add_u64 v[62:63], v[28:29], 2, v[8:9]
	v_lshl_add_u64 v[64:65], v[30:31], 2, v[8:9]
	v_lshl_add_u64 v[66:67], v[32:33], 2, v[8:9]
	v_lshl_add_u64 v[68:69], v[34:35], 2, v[8:9]
	global_load_dwordx4 v[24:27], v[50:51], off
	global_load_dwordx4 v[28:31], v[52:53], off
	global_load_dwordx4 v[32:35], v[52:53], off offset:16
	v_lshl_add_u64 v[56:57], v[22:23], 2, v[8:9]
	global_store_dwordx4 v[54:55], v[0:3], off sc1
	v_lshl_add_u64 v[70:71], v[36:37], 2, v[8:9]
	v_lshl_add_u64 v[72:73], v[38:39], 2, v[8:9]
	v_lshl_add_u64 v[0:1], v[6:7], 0, v[4:5]
	v_lshl_add_u64 v[74:75], v[42:43], 2, v[8:9]
	v_lshl_add_u64 v[76:77], v[44:45], 2, v[8:9]
	global_load_dwordx4 v[0:3], v[0:1], off
	s_nop 0
	global_load_dwordx4 v[36:39], v[56:57], off offset:16
	global_load_dwordx4 v[42:45], v[56:57], off
	v_mov_b32_e32 v47, v5
	v_lshlrev_b32_e32 v46, 7, v108
	v_mov_b32_e32 v49, v5
	v_lshlrev_b32_e32 v48, 7, v112
	v_lshl_add_u64 v[22:23], v[46:47], 2, v[8:9]
	v_lshl_add_u64 v[46:47], v[10:11], 0, v[4:5]
	v_lshlrev_b32_e32 v4, 15, v78
	v_lshl_add_u64 v[20:21], v[48:49], 2, v[8:9]
	v_lshl_add_u64 v[48:49], v[6:7], 0, v[4:5]
	v_lshl_add_u64 v[50:51], v[10:11], 0, v[4:5]
	v_lshlrev_b32_e32 v4, 15, v79
	v_lshl_add_u64 v[52:53], v[6:7], 0, v[4:5]
	v_lshl_add_u64 v[54:55], v[10:11], 0, v[4:5]
	v_lshlrev_b32_e32 v4, 15, v80
	v_lshl_add_u64 v[56:57], v[6:7], 0, v[4:5]
	v_lshl_add_u64 v[78:79], v[10:11], 0, v[4:5]
	v_lshlrev_b32_e32 v4, 15, v41
	v_lshl_add_u64 v[80:81], v[6:7], 0, v[4:5]
	v_lshl_add_u64 v[82:83], v[10:11], 0, v[4:5]
	v_lshlrev_b32_e32 v4, 15, v84
	v_lshl_add_u64 v[84:85], v[6:7], 0, v[4:5]
	v_lshl_add_u64 v[86:87], v[10:11], 0, v[4:5]
	v_lshlrev_b32_e32 v4, 15, v88
	v_lshl_add_u64 v[88:89], v[6:7], 0, v[4:5]
	v_lshl_add_u64 v[90:91], v[10:11], 0, v[4:5]
	v_lshlrev_b32_e32 v4, 15, v92
	v_lshl_add_u64 v[92:93], v[6:7], 0, v[4:5]
	v_lshl_add_u64 v[94:95], v[10:11], 0, v[4:5]
	v_lshlrev_b32_e32 v4, 15, v96
	v_lshl_add_u64 v[96:97], v[6:7], 0, v[4:5]
	v_lshl_add_u64 v[98:99], v[10:11], 0, v[4:5]
	v_lshlrev_b32_e32 v4, 15, v100
	v_lshl_add_u64 v[100:101], v[6:7], 0, v[4:5]
	v_lshl_add_u64 v[102:103], v[10:11], 0, v[4:5]
	v_lshlrev_b32_e32 v4, 15, v104
	v_lshl_add_u64 v[104:105], v[6:7], 0, v[4:5]
	v_lshl_add_u64 v[106:107], v[10:11], 0, v[4:5]
	v_lshlrev_b32_e32 v4, 15, v108
	v_lshl_add_u64 v[108:109], v[6:7], 0, v[4:5]
	v_lshl_add_u64 v[110:111], v[10:11], 0, v[4:5]
	v_lshlrev_b32_e32 v4, 15, v112
	v_lshl_add_u64 v[112:113], v[6:7], 0, v[4:5]
	s_add_i32 s44, s35, 1
	s_add_i32 s45, s34, 14
	s_add_i32 s48, s34, 15
	v_mov_b32_e32 v41, s44
	s_add_i32 s34, s34, 16
	s_waitcnt vmcnt(6)
; __device__ NOINL void phase_scan_combine(const Params& p) {
;     ...
;     for (int cc = 0; cc < 64; ++cc) {
;       int c = dir ? 63 - cc : cc;
;       float uu[8]; unpack8(*(const uint4*)(u + (size_t)c * 16384), uu);
;       float4 d0 = *(const float4*)(dc + c * 128), d1 = *(const float4*)(dc + c * 128 + 4);
;       *(uint4*)(so + (size_t)c * 16384) = pack8(s);
;       s[0] = d0.x * s[0] + uu[0]; s[1] = d0.y * s[1] + uu[1]; s[2] = d0.z * s[2] + uu[2]; s[3] = d0.w * s[3] + uu[3];
;       s[4] = d1.x * s[4] + uu[4]; s[5] = d1.y * s[5] + uu[5]; s[6] = d1.z * s[6] + uu[6]; s[7] = d1.w * s[7] + uu[7];
;     }
	v_lshlrev_b32_e32 v114, 16, v24
	v_and_b32_e32 v115, 0xffff0000, v24
	v_lshlrev_b32_e32 v24, 16, v25
	v_and_b32_e32 v25, 0xffff0000, v25
	v_lshlrev_b32_e32 v116, 16, v26
	v_and_b32_e32 v117, 0xffff0000, v26
	v_lshlrev_b32_e32 v26, 16, v27
	v_and_b32_e32 v27, 0xffff0000, v27
	s_waitcnt vmcnt(4)
	v_pk_fma_f32 v[18:19], v[18:19], v[34:35], v[26:27]
	v_pk_fma_f32 v[14:15], v[14:15], v[30:31], v[24:25]
	v_pk_fma_f32 v[16:17], v[16:17], v[32:33], v[116:117]
	v_pk_fma_f32 v[12:13], v[12:13], v[28:29], v[114:115]
	s_waitcnt vmcnt(2)
	v_lshlrev_b32_e32 v24, 16, v0
	v_and_b32_e32 v25, 0xffff0000, v0
	v_lshlrev_b32_e32 v26, 16, v1
	v_and_b32_e32 v27, 0xffff0000, v1
	v_lshlrev_b32_e32 v28, 16, v2
	v_and_b32_e32 v29, 0xffff0000, v2
	v_lshlrev_b32_e32 v30, 16, v3
	v_and_b32_e32 v31, 0xffff0000, v3
	v_cvt_pk_bf16_f32 v0, v12, v13
	v_cvt_pk_bf16_f32 v1, v14, v15
	v_cvt_pk_bf16_f32 v2, v16, v17
	v_cvt_pk_bf16_f32 v3, v18, v19
	s_waitcnt vmcnt(1)
	v_pk_fma_f32 v[38:39], v[18:19], v[38:39], v[30:31]
	s_waitcnt vmcnt(0)
	v_pk_fma_f32 v[44:45], v[14:15], v[44:45], v[26:27]
	v_pk_fma_f32 v[36:37], v[16:17], v[36:37], v[28:29]
	v_pk_fma_f32 v[42:43], v[12:13], v[42:43], v[24:25]
	global_store_dwordx4 v[46:47], v[0:3], off sc1
	global_load_dwordx4 v[12:15], v[48:49], off
	global_load_dwordx4 v[16:19], v[58:59], off offset:16
	global_load_dwordx4 v[24:27], v[58:59], off
	v_cvt_pk_bf16_f32 v0, v42, v43
	v_cvt_pk_bf16_f32 v1, v44, v45
	v_cvt_pk_bf16_f32 v2, v36, v37
	v_cvt_pk_bf16_f32 v3, v38, v39
	global_store_dwordx4 v[50:51], v[0:3], off sc1
	global_load_dwordx4 v[0:3], v[52:53], off
	s_nop 0
	global_load_dwordx4 v[28:31], v[60:61], off offset:16
	global_load_dwordx4 v[32:35], v[60:61], off
	s_waitcnt vmcnt(6)
	v_lshlrev_b32_e32 v46, 16, v12
	v_and_b32_e32 v47, 0xffff0000, v12
	v_lshlrev_b32_e32 v12, 16, v13
	v_and_b32_e32 v13, 0xffff0000, v13
	v_lshlrev_b32_e32 v48, 16, v14
	v_and_b32_e32 v49, 0xffff0000, v14
	v_lshlrev_b32_e32 v14, 16, v15
	v_and_b32_e32 v15, 0xffff0000, v15
	s_waitcnt vmcnt(5)
	v_pk_fma_f32 v[14:15], v[38:39], v[18:19], v[14:15]
	s_waitcnt vmcnt(4)
	v_pk_fma_f32 v[12:13], v[44:45], v[26:27], v[12:13]
	v_pk_fma_f32 v[16:17], v[36:37], v[16:17], v[48:49]
	v_pk_fma_f32 v[18:19], v[42:43], v[24:25], v[46:47]
	s_waitcnt vmcnt(2)
	v_lshlrev_b32_e32 v24, 16, v0
	v_and_b32_e32 v25, 0xffff0000, v0
	v_lshlrev_b32_e32 v26, 16, v1
	v_and_b32_e32 v27, 0xffff0000, v1
	v_lshlrev_b32_e32 v36, 16, v2
	v_and_b32_e32 v37, 0xffff0000, v2
	v_lshlrev_b32_e32 v38, 16, v3
	v_and_b32_e32 v39, 0xffff0000, v3
	v_cvt_pk_bf16_f32 v0, v18, v19
	v_cvt_pk_bf16_f32 v1, v12, v13
	v_cvt_pk_bf16_f32 v2, v16, v17
	v_cvt_pk_bf16_f32 v3, v14, v15
	s_waitcnt vmcnt(1)
	v_pk_fma_f32 v[38:39], v[14:15], v[30:31], v[38:39]
	s_waitcnt vmcnt(0)
	v_pk_fma_f32 v[42:43], v[12:13], v[34:35], v[26:27]
	v_pk_fma_f32 v[36:37], v[16:17], v[28:29], v[36:37]
	v_pk_fma_f32 v[44:45], v[18:19], v[32:33], v[24:25]
	global_store_dwordx4 v[54:55], v[0:3], off sc1
	global_load_dwordx4 v[12:15], v[56:57], off
	global_load_dwordx4 v[16:19], v[62:63], off offset:16
	global_load_dwordx4 v[24:27], v[62:63], off
	v_cvt_pk_bf16_f32 v0, v44, v45
	v_cvt_pk_bf16_f32 v1, v42, v43
	v_cvt_pk_bf16_f32 v2, v36, v37
	v_cvt_pk_bf16_f32 v3, v38, v39
	global_store_dwordx4 v[78:79], v[0:3], off sc1
	global_load_dwordx4 v[0:3], v[80:81], off
	s_nop 0
	global_load_dwordx4 v[28:31], v[64:65], off offset:16
	global_load_dwordx4 v[32:35], v[64:65], off
	s_waitcnt vmcnt(6)
	v_lshlrev_b32_e32 v46, 16, v12
	v_and_b32_e32 v47, 0xffff0000, v12
	v_lshlrev_b32_e32 v12, 16, v13
	v_and_b32_e32 v13, 0xffff0000, v13
	v_lshlrev_b32_e32 v48, 16, v14
	v_and_b32_e32 v49, 0xffff0000, v14
	v_lshlrev_b32_e32 v14, 16, v15
	v_and_b32_e32 v15, 0xffff0000, v15
	s_waitcnt vmcnt(5)
	v_pk_fma_f32 v[14:15], v[38:39], v[18:19], v[14:15]
	s_waitcnt vmcnt(4)
	v_pk_fma_f32 v[12:13], v[42:43], v[26:27], v[12:13]
	v_pk_fma_f32 v[16:17], v[36:37], v[16:17], v[48:49]
	v_pk_fma_f32 v[18:19], v[44:45], v[24:25], v[46:47]
	s_waitcnt vmcnt(2)
	v_lshlrev_b32_e32 v24, 16, v0
	v_and_b32_e32 v25, 0xffff0000, v0
	v_lshlrev_b32_e32 v26, 16, v1
	v_and_b32_e32 v27, 0xffff0000, v1
	v_lshlrev_b32_e32 v36, 16, v2
	v_and_b32_e32 v37, 0xffff0000, v2
	v_lshlrev_b32_e32 v38, 16, v3
	v_and_b32_e32 v39, 0xffff0000, v3
	v_cvt_pk_bf16_f32 v0, v18, v19
	v_cvt_pk_bf16_f32 v1, v12, v13
	v_cvt_pk_bf16_f32 v2, v16, v17
	v_cvt_pk_bf16_f32 v3, v14, v15
	s_waitcnt vmcnt(1)
	v_pk_fma_f32 v[38:39], v[14:15], v[30:31], v[38:39]
	s_waitcnt vmcnt(0)
	v_pk_fma_f32 v[42:43], v[12:13], v[34:35], v[26:27]
	v_pk_fma_f32 v[36:37], v[16:17], v[28:29], v[36:37]
	v_pk_fma_f32 v[44:45], v[18:19], v[32:33], v[24:25]
	global_store_dwordx4 v[82:83], v[0:3], off sc1
	global_load_dwordx4 v[12:15], v[84:85], off
	global_load_dwordx4 v[16:19], v[66:67], off offset:16
	global_load_dwordx4 v[24:27], v[66:67], off
	v_cvt_pk_bf16_f32 v0, v44, v45
	v_cvt_pk_bf16_f32 v1, v42, v43
	v_cvt_pk_bf16_f32 v2, v36, v37
	v_cvt_pk_bf16_f32 v3, v38, v39
	global_store_dwordx4 v[86:87], v[0:3], off sc1
	global_load_dwordx4 v[0:3], v[88:89], off
	s_nop 0
	global_load_dwordx4 v[28:31], v[68:69], off offset:16
	global_load_dwordx4 v[32:35], v[68:69], off
	s_waitcnt vmcnt(6)
	v_lshlrev_b32_e32 v46, 16, v12
	v_and_b32_e32 v47, 0xffff0000, v12
	v_lshlrev_b32_e32 v12, 16, v13
	v_and_b32_e32 v13, 0xffff0000, v13
	v_lshlrev_b32_e32 v48, 16, v14
	v_and_b32_e32 v49, 0xffff0000, v14
	v_lshlrev_b32_e32 v14, 16, v15
	v_and_b32_e32 v15, 0xffff0000, v15
	s_waitcnt vmcnt(5)
	v_pk_fma_f32 v[14:15], v[38:39], v[18:19], v[14:15]
	s_waitcnt vmcnt(4)
	v_pk_fma_f32 v[12:13], v[42:43], v[26:27], v[12:13]
	v_pk_fma_f32 v[16:17], v[36:37], v[16:17], v[48:49]
	v_pk_fma_f32 v[18:19], v[44:45], v[24:25], v[46:47]
	s_waitcnt vmcnt(2)
; __device__ NOINL void phase_scan_combine(const Params& p) {
;     ...
;     for (int cc = 0; cc < 64; ++cc) {
;       int c = dir ? 63 - cc : cc;
;       float uu[8]; unpack8(*(const uint4*)(u + (size_t)c * 16384), uu);
;       float4 d0 = *(const float4*)(dc + c * 128), d1 = *(const float4*)(dc + c * 128 + 4);
;       *(uint4*)(so + (size_t)c * 16384) = pack8(s);
;       s[0] = d0.x * s[0] + uu[0]; s[1] = d0.y * s[1] + uu[1]; s[2] = d0.z * s[2] + uu[2]; s[3] = d0.w * s[3] + uu[3];
;       s[4] = d1.x * s[4] + uu[4]; s[5] = d1.y * s[5] + uu[5]; s[6] = d1.z * s[6] + uu[6]; s[7] = d1.w * s[7] + uu[7];
;     }
	v_lshlrev_b32_e32 v24, 16, v0
	v_and_b32_e32 v25, 0xffff0000, v0
	v_lshlrev_b32_e32 v26, 16, v1
	v_and_b32_e32 v27, 0xffff0000, v1
	v_lshlrev_b32_e32 v36, 16, v2
	v_and_b32_e32 v37, 0xffff0000, v2
	v_lshlrev_b32_e32 v38, 16, v3
	v_and_b32_e32 v39, 0xffff0000, v3
	v_cvt_pk_bf16_f32 v0, v18, v19
	v_cvt_pk_bf16_f32 v1, v12, v13
	v_cvt_pk_bf16_f32 v2, v16, v17
	v_cvt_pk_bf16_f32 v3, v14, v15
	s_waitcnt vmcnt(1)
	v_pk_fma_f32 v[38:39], v[14:15], v[30:31], v[38:39]
	s_waitcnt vmcnt(0)
	v_pk_fma_f32 v[42:43], v[12:13], v[34:35], v[26:27]
	v_pk_fma_f32 v[36:37], v[16:17], v[28:29], v[36:37]
	v_pk_fma_f32 v[44:45], v[18:19], v[32:33], v[24:25]
	global_store_dwordx4 v[90:91], v[0:3], off sc1
	global_load_dwordx4 v[12:15], v[92:93], off
	global_load_dwordx4 v[16:19], v[70:71], off offset:16
	global_load_dwordx4 v[24:27], v[70:71], off
	v_cvt_pk_bf16_f32 v0, v44, v45
	v_cvt_pk_bf16_f32 v1, v42, v43
	v_cvt_pk_bf16_f32 v2, v36, v37
	v_cvt_pk_bf16_f32 v3, v38, v39
	global_store_dwordx4 v[94:95], v[0:3], off sc1
	global_load_dwordx4 v[0:3], v[96:97], off
	s_nop 0
	global_load_dwordx4 v[28:31], v[72:73], off offset:16
	global_load_dwordx4 v[32:35], v[72:73], off
	s_waitcnt vmcnt(6)
	v_lshlrev_b32_e32 v46, 16, v12
	v_and_b32_e32 v47, 0xffff0000, v12
	v_lshlrev_b32_e32 v12, 16, v13
	v_and_b32_e32 v13, 0xffff0000, v13
	v_lshlrev_b32_e32 v48, 16, v14
	v_and_b32_e32 v49, 0xffff0000, v14
	v_lshlrev_b32_e32 v14, 16, v15
	v_and_b32_e32 v15, 0xffff0000, v15
	s_waitcnt vmcnt(5)
	v_pk_fma_f32 v[14:15], v[38:39], v[18:19], v[14:15]
	s_waitcnt vmcnt(4)
	v_pk_fma_f32 v[12:13], v[42:43], v[26:27], v[12:13]
	v_pk_fma_f32 v[16:17], v[36:37], v[16:17], v[48:49]
	v_pk_fma_f32 v[18:19], v[44:45], v[24:25], v[46:47]
	s_waitcnt vmcnt(2)
	v_lshlrev_b32_e32 v24, 16, v0
	v_and_b32_e32 v25, 0xffff0000, v0
	v_lshlrev_b32_e32 v26, 16, v1
	v_and_b32_e32 v27, 0xffff0000, v1
	v_lshlrev_b32_e32 v36, 16, v2
	v_and_b32_e32 v37, 0xffff0000, v2
	v_lshlrev_b32_e32 v38, 16, v3
	v_and_b32_e32 v39, 0xffff0000, v3
	v_cvt_pk_bf16_f32 v0, v18, v19
	v_cvt_pk_bf16_f32 v1, v12, v13
	v_cvt_pk_bf16_f32 v2, v16, v17
	v_cvt_pk_bf16_f32 v3, v14, v15
	s_waitcnt vmcnt(1)
	v_pk_fma_f32 v[38:39], v[14:15], v[30:31], v[38:39]
	s_waitcnt vmcnt(0)
	v_pk_fma_f32 v[42:43], v[12:13], v[34:35], v[26:27]
	v_pk_fma_f32 v[36:37], v[16:17], v[28:29], v[36:37]
	v_pk_fma_f32 v[44:45], v[18:19], v[32:33], v[24:25]
	global_store_dwordx4 v[98:99], v[0:3], off sc1
	global_load_dwordx4 v[12:15], v[100:101], off
	global_load_dwordx4 v[16:19], v[74:75], off offset:16
	global_load_dwordx4 v[24:27], v[74:75], off
	v_cvt_pk_bf16_f32 v0, v44, v45
	v_cvt_pk_bf16_f32 v1, v42, v43
	v_cvt_pk_bf16_f32 v2, v36, v37
	v_cvt_pk_bf16_f32 v3, v38, v39
	global_store_dwordx4 v[102:103], v[0:3], off sc1
	global_load_dwordx4 v[0:3], v[104:105], off
	s_nop 0
	global_load_dwordx4 v[28:31], v[76:77], off offset:16
	global_load_dwordx4 v[32:35], v[76:77], off
	s_waitcnt vmcnt(6)
	v_lshlrev_b32_e32 v46, 16, v12
	v_and_b32_e32 v47, 0xffff0000, v12
	v_lshlrev_b32_e32 v12, 16, v13
	v_and_b32_e32 v13, 0xffff0000, v13
	v_lshlrev_b32_e32 v48, 16, v14
	v_and_b32_e32 v49, 0xffff0000, v14
	v_lshlrev_b32_e32 v14, 16, v15
	v_and_b32_e32 v15, 0xffff0000, v15
	s_waitcnt vmcnt(5)
	v_pk_fma_f32 v[14:15], v[38:39], v[18:19], v[14:15]
	s_waitcnt vmcnt(4)
	v_pk_fma_f32 v[12:13], v[42:43], v[26:27], v[12:13]
	v_pk_fma_f32 v[16:17], v[36:37], v[16:17], v[48:49]
	v_pk_fma_f32 v[18:19], v[44:45], v[24:25], v[46:47]
	s_waitcnt vmcnt(2)
	v_lshlrev_b32_e32 v24, 16, v0
	v_and_b32_e32 v25, 0xffff0000, v0
	v_lshlrev_b32_e32 v26, 16, v1
	v_and_b32_e32 v27, 0xffff0000, v1
	v_lshlrev_b32_e32 v36, 16, v2
	v_and_b32_e32 v37, 0xffff0000, v2
	v_lshlrev_b32_e32 v38, 16, v3
	v_and_b32_e32 v39, 0xffff0000, v3
	v_cvt_pk_bf16_f32 v0, v18, v19
	v_cvt_pk_bf16_f32 v1, v12, v13
	v_cvt_pk_bf16_f32 v2, v16, v17
	v_cvt_pk_bf16_f32 v3, v14, v15
	s_waitcnt vmcnt(1)
	v_pk_fma_f32 v[38:39], v[14:15], v[30:31], v[38:39]
	s_waitcnt vmcnt(0)
; __device__ NOINL void phase_scan_combine(const Params& p) {
;     ...
;   for (int li = threadIdx.x; li < per_blk; li += NT) {
;     const int item = (int)blockIdx.x * per_blk + li;
;     if (item >= n_scan) break;
;     int e8 = (int)(item & 2047); int db = (int)(item >> 11);
;     int dir = db / 24;
;     int k0 = (e8 & 15) * 8;
;     const u16* u = UT + (size_t)db * 64 * 16384 + (size_t)e8 * 8;
;     const float* dc = Dc + (size_t)db * 64 * 128 + k0;
;     u16* so = SIN + (size_t)db * 64 * 16384 + (size_t)e8 * 8;
;     float s[8];
; #pragma unroll
;     for (int i = 0; i < 8; ++i) s[i] = 0.f;
; #pragma unroll 16
;     for (int cc = 0; cc < 64; ++cc) {
;       int c = dir ? 63 - cc : cc;
;       float uu[8]; unpack8(*(const uint4*)(u + (size_t)c * 16384), uu);
;       float4 d0 = *(const float4*)(dc + c * 128), d1 = *(const float4*)(dc + c * 128 + 4);
;       *(uint4*)(so + (size_t)c * 16384) = pack8(s);
;       s[0] = d0.x * s[0] + uu[0]; s[1] = d0.y * s[1] + uu[1]; s[2] = d0.z * s[2] + uu[2]; s[3] = d0.w * s[3] + uu[3];
;       s[4] = d1.x * s[4] + uu[4]; s[5] = d1.y * s[5] + uu[5]; s[6] = d1.z * s[6] + uu[6]; s[7] = d1.w * s[7] + uu[7];
;     }
	v_pk_fma_f32 v[34:35], v[12:13], v[34:35], v[26:27]
	v_pk_fma_f32 v[36:37], v[16:17], v[28:29], v[36:37]
	v_pk_fma_f32 v[42:43], v[18:19], v[32:33], v[24:25]
	global_store_dwordx4 v[106:107], v[0:3], off sc1
	global_load_dwordx4 v[12:15], v[108:109], off
	global_load_dwordx4 v[16:19], v[22:23], off offset:16
	s_nop 0
	global_load_dwordx4 v[22:25], v[22:23], off
	v_cvt_pk_bf16_f32 v0, v42, v43
	v_cvt_pk_bf16_f32 v1, v34, v35
	v_cvt_pk_bf16_f32 v2, v36, v37
	v_cvt_pk_bf16_f32 v3, v38, v39
	global_store_dwordx4 v[110:111], v[0:3], off sc1
	global_load_dwordx4 v[0:3], v[112:113], off
	s_nop 0
	global_load_dwordx4 v[26:29], v[20:21], off offset:16
	global_load_dwordx4 v[30:33], v[20:21], off
	v_mov_b32_e32 v44, s45
	v_mov_b32_e32 v20, s35
	v_mov_b32_e32 v46, s48
	v_cndmask_b32_e32 v41, v41, v44, vcc
	v_mov_b32_e32 v21, v5
	v_cndmask_b32_e32 v52, v20, v46, vcc
	v_lshlrev_b32_e32 v20, 7, v41
	v_lshl_add_u64 v[46:47], v[10:11], 0, v[4:5]
	v_lshlrev_b32_e32 v4, 15, v41
	v_lshl_add_u64 v[20:21], v[20:21], 2, v[8:9]
	v_lshl_add_u64 v[48:49], v[6:7], 0, v[4:5]
	v_lshl_add_u64 v[50:51], v[10:11], 0, v[4:5]
	v_lshlrev_b32_e32 v4, 15, v52
	v_mov_b32_e32 v45, v5
	v_lshlrev_b32_e32 v44, 7, v52
	v_lshl_add_u64 v[52:53], v[6:7], 0, v[4:5]
	v_lshl_add_u64 v[44:45], v[44:45], 2, v[8:9]
	s_add_i32 s35, s35, -16
	s_cmp_lg_u32 s34, 64
	s_waitcnt vmcnt(6)
	v_lshlrev_b32_e32 v54, 16, v12
	v_and_b32_e32 v55, 0xffff0000, v12
	v_lshlrev_b32_e32 v12, 16, v13
	v_and_b32_e32 v13, 0xffff0000, v13
	v_lshlrev_b32_e32 v56, 16, v14
	v_and_b32_e32 v57, 0xffff0000, v14
	v_lshlrev_b32_e32 v14, 16, v15
	v_and_b32_e32 v15, 0xffff0000, v15
	s_waitcnt vmcnt(5)
	v_pk_fma_f32 v[14:15], v[38:39], v[18:19], v[14:15]
	s_waitcnt vmcnt(4)
	v_pk_fma_f32 v[12:13], v[34:35], v[24:25], v[12:13]
	v_pk_fma_f32 v[16:17], v[36:37], v[16:17], v[56:57]
	v_pk_fma_f32 v[18:19], v[42:43], v[22:23], v[54:55]
	s_waitcnt vmcnt(2)
	v_lshlrev_b32_e32 v22, 16, v0
	v_and_b32_e32 v23, 0xffff0000, v0
	v_lshlrev_b32_e32 v24, 16, v1
	v_and_b32_e32 v25, 0xffff0000, v1
	v_lshlrev_b32_e32 v34, 16, v2
	v_and_b32_e32 v35, 0xffff0000, v2
	v_lshlrev_b32_e32 v36, 16, v3
	v_and_b32_e32 v37, 0xffff0000, v3
	v_cvt_pk_bf16_f32 v0, v18, v19
	v_cvt_pk_bf16_f32 v1, v12, v13
	v_cvt_pk_bf16_f32 v2, v16, v17
	v_cvt_pk_bf16_f32 v3, v14, v15
	s_waitcnt vmcnt(1)
	v_pk_fma_f32 v[36:37], v[14:15], v[28:29], v[36:37]
	s_waitcnt vmcnt(0)
	v_pk_fma_f32 v[32:33], v[12:13], v[32:33], v[24:25]
	v_pk_fma_f32 v[34:35], v[16:17], v[26:27], v[34:35]
	v_pk_fma_f32 v[38:39], v[18:19], v[30:31], v[22:23]
	global_store_dwordx4 v[46:47], v[0:3], off sc1
	global_load_dwordx4 v[12:15], v[48:49], off
	global_load_dwordx4 v[16:19], v[20:21], off offset:16
	s_nop 0
	global_load_dwordx4 v[20:23], v[20:21], off
	v_cvt_pk_bf16_f32 v0, v38, v39
	v_cvt_pk_bf16_f32 v1, v32, v33
	v_cvt_pk_bf16_f32 v2, v34, v35
	v_cvt_pk_bf16_f32 v3, v36, v37
	global_store_dwordx4 v[50:51], v[0:3], off sc1
	global_load_dwordx4 v[0:3], v[52:53], off
	s_nop 0
	global_load_dwordx4 v[24:27], v[44:45], off offset:16
	global_load_dwordx4 v[28:31], v[44:45], off
	v_lshl_add_u64 v[42:43], v[10:11], 0, v[4:5]
	s_waitcnt vmcnt(6)
	v_lshlrev_b32_e32 v44, 16, v12
	v_and_b32_e32 v45, 0xffff0000, v12
	v_lshlrev_b32_e32 v12, 16, v13
	v_and_b32_e32 v13, 0xffff0000, v13
	v_lshlrev_b32_e32 v46, 16, v14
	v_and_b32_e32 v47, 0xffff0000, v14
	v_lshlrev_b32_e32 v14, 16, v15
	v_and_b32_e32 v15, 0xffff0000, v15
	s_waitcnt vmcnt(5)
	v_pk_fma_f32 v[14:15], v[36:37], v[18:19], v[14:15]
	s_waitcnt vmcnt(4)
	v_pk_fma_f32 v[12:13], v[32:33], v[22:23], v[12:13]
	v_pk_fma_f32 v[16:17], v[34:35], v[16:17], v[46:47]
	v_pk_fma_f32 v[20:21], v[38:39], v[20:21], v[44:45]
	s_waitcnt vmcnt(2)
	v_lshlrev_b32_e32 v22, 16, v0
	v_and_b32_e32 v23, 0xffff0000, v0
	v_lshlrev_b32_e32 v32, 16, v1
	v_and_b32_e32 v33, 0xffff0000, v1
	v_lshlrev_b32_e32 v34, 16, v2
	v_and_b32_e32 v35, 0xffff0000, v2
	v_lshlrev_b32_e32 v18, 16, v3
	v_and_b32_e32 v19, 0xffff0000, v3
	v_cvt_pk_bf16_f32 v0, v20, v21
	v_cvt_pk_bf16_f32 v1, v12, v13
	v_cvt_pk_bf16_f32 v2, v16, v17
	v_cvt_pk_bf16_f32 v3, v14, v15
	s_waitcnt vmcnt(1)
	v_pk_fma_f32 v[18:19], v[14:15], v[26:27], v[18:19]
	s_waitcnt vmcnt(0)
	v_pk_fma_f32 v[14:15], v[12:13], v[30:31], v[32:33]
	v_pk_fma_f32 v[16:17], v[16:17], v[24:25], v[34:35]
	v_pk_fma_f32 v[12:13], v[20:21], v[28:29], v[22:23]
	global_store_dwordx4 v[42:43], v[0:3], off sc1
	s_cbranch_scc1 .LBB0_373
	v_add_u32_e32 v40, 0x200, v40
	v_cmp_le_i32_e32 vcc, s3, v40
	s_andn2_b64 s[34:35], s[40:41], exec
	s_and_b64 s[40:41], vcc, exec
	s_or_b64 s[40:41], s[34:35], s[40:41]
	s_branch .LBB0_370

; __device__ NOINL void phase_scan_combine(const Params& p) {
;     ...
;   for (size_t item = gtid; item < (size_t)8192 * 192; item += gsz) {
;     size_t tok = item / 192; int hc = (int)(item % 192); int h = hc >> 4, c = hc & 15;
;     int b = (int)(tok >> 12), pos = (int)(tok & 4095);
;     float l0 = lse[(size_t)((0 * 2 + b) * 12 + h) * SEQ + pos];
;     float l1 = lse[(size_t)((1 * 2 + b) * 12 + h) * SEQ + pos];
;     float l2 = lse[(size_t)((2 * 2 + b) * 12 + h) * SEQ + pos];
;     float m = fmaxf(l0, fmaxf(l1, l2));
;     float w0 = __expf(l0 - m), w1 = __expf(l1 - m), w2 = __expf(l2 - m);
;     float inv = 1.f / (w0 + w1 + w2);
;     w0 *= inv; w1 *= inv; w2 *= inv;
;     size_t off = tok * 1536 + h * 128 + 8 * c;
;     float a[8], bb[8], cc[8], o[8];
;     unpack8(*(const uint4*)(part + off), a);
;     unpack8(*(const uint4*)(part + (size_t)8192 * 1536 + off), bb);
;     unpack8(*(const uint4*)(part + (size_t)2 * 8192 * 1536 + off), cc);
; #pragma unroll
;     for (int i = 0; i < 8; ++i) o[i] = w0 * a[i] + w1 * bb[i] + w2 * cc[i];
;     *(uint4*)(mix + tok * 4096 + h * 128 + 8 * c) = pack8(o);
;   }
.LBB0_380:
	v_mul_hi_u32 v6, v2, s3
	v_lshrrev_b32_e32 v0, 7, v6
	v_mul_lo_u32 v4, v0, s15
	v_sub_u32_e32 v12, v2, v4
	v_lshrrev_b32_e32 v18, 4, v12
	v_lshrrev_b32_e32 v4, 19, v6
	v_lshrrev_b32_e32 v6, 5, v6
	v_mad_u32_u24 v10, v4, 12, v18
	v_and_b32_e32 v6, 0x3ffc, v6
	v_mov_b32_e32 v7, v1
	v_lshlrev_b32_e32 v4, 12, v10
	v_mov_b32_e32 v5, v1
	v_lshl_add_u64 v[8:9], s[38:39], 0, v[6:7]
	v_lshl_add_u64 v[4:5], v[4:5], 2, v[8:9]
	v_add_u32_e32 v8, 24, v10
	v_mov_b32_e32 v9, v1
	v_add_u32_e32 v10, 48, v10
	v_mov_b32_e32 v11, v1
	v_lshlrev_b64 v[8:9], 14, v[8:9]
	v_lshlrev_b64 v[10:11], 14, v[10:11]
	v_lshl_add_u64 v[8:9], s[38:39], 0, v[8:9]
	v_lshl_add_u64 v[10:11], s[38:39], 0, v[10:11]
	v_lshl_add_u64 v[8:9], v[8:9], 0, v[6:7]
	v_lshl_add_u64 v[6:7], v[10:11], 0, v[6:7]
	global_load_dword v32, v[4:5], off
	global_load_dword v33, v[8:9], off
	global_load_dword v34, v[6:7], off
	v_lshlrev_b32_e32 v4, 7, v18
	v_mov_b32_e32 v5, v1
	v_lshlrev_b32_e32 v6, 3, v12
	v_mad_u64_u32 v[4:5], s[4:5], v0, s33, v[4:5]
	v_and_b32_e32 v19, 0x78, v6
	v_or_b32_e32 v4, v4, v19
	v_lshlrev_b64 v[4:5], 1, v[4:5]
	v_lshl_add_u64 v[6:7], s[48:49], 0, v[4:5]
	v_lshl_add_u64 v[10:11], s[44:45], 0, v[4:5]
	v_lshl_add_u64 v[4:5], s[12:13], 0, v[4:5]
	global_load_dwordx4 v[6:9], v[6:7], off
	s_or_b64 s[62:63], s[62:63], exec
	global_load_dwordx4 v[10:13], v[10:11], off
	s_waitcnt vmcnt(0)
	v_lshlrev_b32_e32 v22, 16, v13
	global_load_dwordx4 v[14:17], v[4:5], off
	v_lshl_add_u64 v[4:5], v[2:3], 0, s[42:43]
	v_lshlrev_b64 v[2:3], 13, v[0:1]
	v_lshl_add_u64 v[2:3], s[40:41], 0, v[2:3]
	v_lshlrev_b32_e32 v0, 8, v18
	v_lshl_add_u64 v[2:3], v[2:3], 0, v[0:1]
	v_lshlrev_b32_e32 v0, 1, v19
	v_lshl_add_u64 v[2:3], v[2:3], 0, v[0:1]
	v_max3_f32 v0, v32, v33, v34
	v_and_b32_e32 v25, 0xffff0000, v13
	v_lshlrev_b32_e32 v26, 16, v10
	v_and_b32_e32 v29, 0xffff0000, v10
	v_sub_f32_e32 v13, v32, v0
	v_mul_f32_e32 v13, 0x3fb8aa3b, v13
	v_lshlrev_b32_e32 v30, 16, v11
	v_and_b32_e32 v11, 0xffff0000, v11
	v_lshlrev_b32_e32 v18, 16, v6
	v_and_b32_e32 v19, 0xffff0000, v6
	v_lshlrev_b32_e32 v6, 16, v7
	v_and_b32_e32 v7, 0xffff0000, v7
	v_lshlrev_b32_e32 v20, 16, v8
	v_and_b32_e32 v21, 0xffff0000, v8
	v_lshlrev_b32_e32 v8, 16, v9
	v_and_b32_e32 v9, 0xffff0000, v9
	v_cmp_gt_u64_e64 s[4:5], s[8:9], v[4:5]
	s_waitcnt vmcnt(0)
	v_and_b32_e32 v31, 0xffff0000, v15
	v_lshlrev_b32_e32 v10, 16, v15
	v_sub_f32_e32 v15, v33, v0
	v_sub_f32_e32 v0, v34, v0
	v_mul_f32_e32 v15, 0x3fb8aa3b, v15
	v_mul_f32_e32 v0, 0x3fb8aa3b, v0
	v_exp_f32_e32 v33, v13
	v_exp_f32_e32 v32, v15
	v_exp_f32_e32 v13, v0
	v_and_b32_e32 v23, 0xffff0000, v17
	v_lshlrev_b32_e32 v24, 16, v17
	v_add_f32_e32 v0, v33, v32
	v_add_f32_e32 v0, v13, v0
	v_div_scale_f32 v34, s[34:35], v0, v0, 1.0
	v_rcp_f32_e32 v35, v34
	v_and_b32_e32 v27, 0xffff0000, v14
	v_lshlrev_b32_e32 v28, 16, v14
	v_lshlrev_b32_e32 v14, 16, v12
	v_fma_f32 v36, -v34, v35, 1.0
	v_and_b32_e32 v17, 0xffff0000, v12
	v_div_scale_f32 v12, vcc, 1.0, v0, 1.0
	v_fmac_f32_e32 v35, v36, v35
	v_mul_f32_e32 v36, v12, v35
	v_fma_f32 v37, -v34, v36, v12
	v_fmac_f32_e32 v36, v37, v35
	v_fma_f32 v12, -v34, v36, v12
	v_div_fmas_f32 v12, v12, v35, v36
	v_div_fixup_f32 v0, v12, v0, 1.0
	v_and_b32_e32 v15, 0xffff0000, v16
	v_lshlrev_b32_e32 v16, 16, v16
	v_pk_mul_f32 v[32:33], v[32:33], v[0:1] op_sel_hi:[1,0]
	v_mul_f32_e32 v12, v13, v0
	v_pk_mul_f32 v[28:29], v[32:33], v[28:29] op_sel:[1,0] op_sel_hi:[0,1]
	v_pk_mul_f32 v[10:11], v[32:33], v[10:11] op_sel:[1,0] op_sel_hi:[0,1]
	v_pk_mul_f32 v[16:17], v[32:33], v[16:17] op_sel:[1,0] op_sel_hi:[0,1]
	v_pk_mul_f32 v[24:25], v[32:33], v[24:25] op_sel:[1,0] op_sel_hi:[0,1]
	v_pk_fma_f32 v[26:27], v[32:33], v[26:27], v[28:29]
	v_pk_fma_f32 v[10:11], v[32:33], v[30:31], v[10:11]
	v_pk_fma_f32 v[14:15], v[32:33], v[14:15], v[16:17]
	v_pk_fma_f32 v[16:17], v[32:33], v[22:23], v[24:25]
	v_pk_fma_f32 v[18:19], v[12:13], v[18:19], v[26:27] op_sel_hi:[0,1,1]
	v_pk_fma_f32 v[10:11], v[12:13], v[6:7], v[10:11] op_sel_hi:[0,1,1]
	v_pk_fma_f32 v[14:15], v[12:13], v[20:21], v[14:15] op_sel_hi:[0,1,1]
	v_pk_fma_f32 v[12:13], v[12:13], v[8:9], v[16:17] op_sel_hi:[0,1,1]
	v_cvt_pk_bf16_f32 v6, v18, v19
	v_cvt_pk_bf16_f32 v7, v10, v11
	v_cvt_pk_bf16_f32 v8, v14, v15
	v_cvt_pk_bf16_f32 v9, v12, v13
	global_store_dwordx4 v[2:3], v[6:9], off sc1
	s_and_saveexec_b64 s[64:65], s[4:5]
	s_cbranch_execz .LBB0_379
; __device__ NOINL void phase_scan_combine(const Params& p) {
;     ...
;   for (size_t item = gtid; item < (size_t)8192 * 192; item += gsz) {
;     size_t tok = item / 192; int hc = (int)(item % 192); int h = hc >> 4, c = hc & 15;
;     int b = (int)(tok >> 12), pos = (int)(tok & 4095);
;     float l0 = lse[(size_t)((0 * 2 + b) * 12 + h) * SEQ + pos];
;     float l1 = lse[(size_t)((1 * 2 + b) * 12 + h) * SEQ + pos];
;     float l2 = lse[(size_t)((2 * 2 + b) * 12 + h) * SEQ + pos];
;     float m = fmaxf(l0, fmaxf(l1, l2));
;     float w0 = __expf(l0 - m), w1 = __expf(l1 - m), w2 = __expf(l2 - m);
;     float inv = 1.f / (w0 + w1 + w2);
;     w0 *= inv; w1 *= inv; w2 *= inv;
;     size_t off = tok * 1536 + h * 128 + 8 * c;
;     float a[8], bb[8], cc[8], o[8];
;     unpack8(*(const uint4*)(part + off), a);
;     unpack8(*(const uint4*)(part + (size_t)8192 * 1536 + off), bb);
;     unpack8(*(const uint4*)(part + (size_t)2 * 8192 * 1536 + off), cc);
; #pragma unroll
;     for (int i = 0; i < 8; ++i) o[i] = w0 * a[i] + w1 * bb[i] + w2 * cc[i];
;     *(uint4*)(mix + tok * 4096 + h * 128 + 8 * c) = pack8(o);
;   }
	v_mul_hi_u32 v6, v4, s3
	v_lshrrev_b32_e32 v0, 7, v6
	v_mul_lo_u32 v2, v0, s15
	v_sub_u32_e32 v12, v4, v2
	v_lshrrev_b32_e32 v18, 4, v12
	v_lshrrev_b32_e32 v2, 19, v6
	v_lshrrev_b32_e32 v6, 5, v6
	v_mad_u32_u24 v10, v2, 12, v18
	v_and_b32_e32 v6, 0x3ffc, v6
	v_mov_b32_e32 v7, v1
	v_lshlrev_b32_e32 v2, 12, v10
	v_mov_b32_e32 v3, v1
	v_lshl_add_u64 v[8:9], s[38:39], 0, v[6:7]
	v_lshl_add_u64 v[2:3], v[2:3], 2, v[8:9]
	v_add_u32_e32 v8, 24, v10
	v_mov_b32_e32 v9, v1
	v_add_u32_e32 v10, 48, v10
	v_mov_b32_e32 v11, v1
	v_lshlrev_b64 v[8:9], 14, v[8:9]
	v_lshlrev_b64 v[10:11], 14, v[10:11]
	v_lshl_add_u64 v[8:9], s[38:39], 0, v[8:9]
	v_lshl_add_u64 v[10:11], s[38:39], 0, v[10:11]
	v_lshl_add_u64 v[8:9], v[8:9], 0, v[6:7]
	v_lshl_add_u64 v[6:7], v[10:11], 0, v[6:7]
	global_load_dword v32, v[2:3], off
	global_load_dword v33, v[8:9], off
	global_load_dword v34, v[6:7], off
	v_lshlrev_b32_e32 v2, 7, v18
	v_mov_b32_e32 v3, v1
	v_lshlrev_b32_e32 v6, 3, v12
	v_mad_u64_u32 v[2:3], s[4:5], v0, s33, v[2:3]
	v_and_b32_e32 v19, 0x78, v6
	v_or_b32_e32 v2, v2, v19
	v_lshlrev_b64 v[2:3], 1, v[2:3]
	v_lshl_add_u64 v[6:7], s[48:49], 0, v[2:3]
	v_lshl_add_u64 v[10:11], s[44:45], 0, v[2:3]
	v_lshl_add_u64 v[2:3], s[12:13], 0, v[2:3]
	global_load_dwordx4 v[6:9], v[6:7], off
	v_lshl_add_u64 v[4:5], v[4:5], 0, s[42:43]
	global_load_dwordx4 v[10:13], v[10:11], off
	v_cmp_gt_u64_e64 s[4:5], s[8:9], v[4:5]
	global_load_dwordx4 v[14:17], v[2:3], off
	v_lshlrev_b64 v[2:3], 13, v[0:1]
	v_lshl_add_u64 v[2:3], s[40:41], 0, v[2:3]
	v_lshlrev_b32_e32 v0, 8, v18
	v_lshl_add_u64 v[2:3], v[2:3], 0, v[0:1]
	v_lshlrev_b32_e32 v0, 1, v19
	v_lshl_add_u64 v[2:3], v[2:3], 0, v[0:1]
	s_mov_b64 s[68:69], -1
	s_waitcnt vmcnt(3)
	v_max3_f32 v0, v32, v33, v34
	s_waitcnt vmcnt(2)
	v_lshlrev_b32_e32 v18, 16, v6
	v_and_b32_e32 v19, 0xffff0000, v6
	s_waitcnt vmcnt(1)
	v_lshlrev_b32_e32 v22, 16, v13
	v_and_b32_e32 v25, 0xffff0000, v13
	v_lshlrev_b32_e32 v26, 16, v10
	v_and_b32_e32 v29, 0xffff0000, v10
	s_waitcnt vmcnt(0)
	v_and_b32_e32 v31, 0xffff0000, v15
	v_lshlrev_b32_e32 v10, 16, v15
	v_sub_f32_e32 v13, v32, v0
	v_sub_f32_e32 v15, v33, v0
	v_sub_f32_e32 v0, v34, v0
	v_mul_f32_e32 v13, 0x3fb8aa3b, v13
	v_mul_f32_e32 v15, 0x3fb8aa3b, v15
	v_mul_f32_e32 v0, 0x3fb8aa3b, v0
	v_exp_f32_e32 v33, v13
	v_exp_f32_e32 v32, v15
	v_exp_f32_e32 v13, v0
	v_and_b32_e32 v23, 0xffff0000, v17
	v_lshlrev_b32_e32 v24, 16, v17
	v_add_f32_e32 v0, v33, v32
	v_add_f32_e32 v0, v13, v0
	v_div_scale_f32 v34, s[34:35], v0, v0, 1.0
	v_rcp_f32_e32 v35, v34
	v_and_b32_e32 v27, 0xffff0000, v14
	v_lshlrev_b32_e32 v28, 16, v14
	v_lshlrev_b32_e32 v14, 16, v12
	v_fma_f32 v36, -v34, v35, 1.0
	v_and_b32_e32 v17, 0xffff0000, v12
	v_div_scale_f32 v12, vcc, 1.0, v0, 1.0
	v_fmac_f32_e32 v35, v36, v35
	v_mul_f32_e32 v36, v12, v35
	v_fma_f32 v37, -v34, v36, v12
	v_fmac_f32_e32 v36, v37, v35
	v_fma_f32 v12, -v34, v36, v12
	v_div_fmas_f32 v12, v12, v35, v36
	v_div_fixup_f32 v0, v12, v0, 1.0
	v_lshlrev_b32_e32 v30, 16, v11
	v_and_b32_e32 v11, 0xffff0000, v11
	v_and_b32_e32 v15, 0xffff0000, v16
	v_lshlrev_b32_e32 v16, 16, v16
	v_pk_mul_f32 v[32:33], v[32:33], v[0:1] op_sel_hi:[1,0]
	v_lshlrev_b32_e32 v6, 16, v7
	v_pk_mul_f32 v[28:29], v[32:33], v[28:29] op_sel:[1,0] op_sel_hi:[0,1]
	v_pk_mul_f32 v[10:11], v[32:33], v[10:11] op_sel:[1,0] op_sel_hi:[0,1]
	v_pk_mul_f32 v[16:17], v[32:33], v[16:17] op_sel:[1,0] op_sel_hi:[0,1]
	v_pk_mul_f32 v[24:25], v[32:33], v[24:25] op_sel:[1,0] op_sel_hi:[0,1]
	v_and_b32_e32 v7, 0xffff0000, v7
	v_lshlrev_b32_e32 v20, 16, v8
	v_and_b32_e32 v21, 0xffff0000, v8
	v_lshlrev_b32_e32 v8, 16, v9
	v_and_b32_e32 v9, 0xffff0000, v9
	v_mul_f32_e32 v12, v13, v0
	v_pk_fma_f32 v[26:27], v[32:33], v[26:27], v[28:29]
	v_pk_fma_f32 v[10:11], v[32:33], v[30:31], v[10:11]
	v_pk_fma_f32 v[14:15], v[32:33], v[14:15], v[16:17]
	v_pk_fma_f32 v[16:17], v[32:33], v[22:23], v[24:25]
	v_pk_fma_f32 v[18:19], v[12:13], v[18:19], v[26:27] op_sel_hi:[0,1,1]
	v_pk_fma_f32 v[10:11], v[12:13], v[6:7], v[10:11] op_sel_hi:[0,1,1]
	v_pk_fma_f32 v[14:15], v[12:13], v[20:21], v[14:15] op_sel_hi:[0,1,1]
	v_pk_fma_f32 v[12:13], v[12:13], v[8:9], v[16:17] op_sel_hi:[0,1,1]
	v_cvt_pk_bf16_f32 v6, v18, v19
	v_cvt_pk_bf16_f32 v7, v10, v11
	v_cvt_pk_bf16_f32 v8, v14, v15
	v_cvt_pk_bf16_f32 v9, v12, v13
	global_store_dwordx4 v[2:3], v[6:9], off sc1
	s_and_saveexec_b64 s[66:67], s[4:5]
	s_cbranch_execz .LBB0_378
; __device__ NOINL void phase_scan_combine(const Params& p) {
;     ...
;   for (size_t item = gtid; item < (size_t)8192 * 192; item += gsz) {
;     size_t tok = item / 192; int hc = (int)(item % 192); int h = hc >> 4, c = hc & 15;
;     int b = (int)(tok >> 12), pos = (int)(tok & 4095);
;     float l0 = lse[(size_t)((0 * 2 + b) * 12 + h) * SEQ + pos];
;     float l1 = lse[(size_t)((1 * 2 + b) * 12 + h) * SEQ + pos];
;     float l2 = lse[(size_t)((2 * 2 + b) * 12 + h) * SEQ + pos];
;     float m = fmaxf(l0, fmaxf(l1, l2));
;     float w0 = __expf(l0 - m), w1 = __expf(l1 - m), w2 = __expf(l2 - m);
;     float inv = 1.f / (w0 + w1 + w2);
;     w0 *= inv; w1 *= inv; w2 *= inv;
;     size_t off = tok * 1536 + h * 128 + 8 * c;
;     float a[8], bb[8], cc[8], o[8];
;     unpack8(*(const uint4*)(part + off), a);
;     unpack8(*(const uint4*)(part + (size_t)8192 * 1536 + off), bb);
;     unpack8(*(const uint4*)(part + (size_t)2 * 8192 * 1536 + off), cc);
; #pragma unroll
;     for (int i = 0; i < 8; ++i) o[i] = w0 * a[i] + w1 * bb[i] + w2 * cc[i];
;     *(uint4*)(mix + tok * 4096 + h * 128 + 8 * c) = pack8(o);
;   }
	v_mul_hi_u32 v6, v4, s3
	v_lshrrev_b32_e32 v0, 7, v6
	v_mul_lo_u32 v2, v0, s15
	v_sub_u32_e32 v12, v4, v2
	v_lshrrev_b32_e32 v18, 4, v12
	v_lshrrev_b32_e32 v2, 19, v6
	v_lshrrev_b32_e32 v6, 5, v6
	v_mad_u32_u24 v10, v2, 12, v18
	v_and_b32_e32 v6, 0x3ffc, v6
	v_mov_b32_e32 v7, v1
	v_lshlrev_b32_e32 v2, 12, v10
	v_mov_b32_e32 v3, v1
	v_lshl_add_u64 v[8:9], s[38:39], 0, v[6:7]
	v_lshl_add_u64 v[2:3], v[2:3], 2, v[8:9]
	v_add_u32_e32 v8, 24, v10
	v_mov_b32_e32 v9, v1
	v_add_u32_e32 v10, 48, v10
	v_mov_b32_e32 v11, v1
	v_lshlrev_b64 v[8:9], 14, v[8:9]
	v_lshlrev_b64 v[10:11], 14, v[10:11]
	v_lshl_add_u64 v[8:9], s[38:39], 0, v[8:9]
	v_lshl_add_u64 v[10:11], s[38:39], 0, v[10:11]
	v_lshl_add_u64 v[8:9], v[8:9], 0, v[6:7]
	v_lshl_add_u64 v[6:7], v[10:11], 0, v[6:7]
	global_load_dword v32, v[2:3], off
	global_load_dword v33, v[8:9], off
	global_load_dword v34, v[6:7], off
	v_lshlrev_b32_e32 v2, 7, v18
	v_mov_b32_e32 v3, v1
	v_lshlrev_b32_e32 v6, 3, v12
	v_mad_u64_u32 v[2:3], s[4:5], v0, s33, v[2:3]
	v_and_b32_e32 v19, 0x78, v6
	v_or_b32_e32 v2, v2, v19
	v_lshlrev_b64 v[2:3], 1, v[2:3]
	v_lshl_add_u64 v[6:7], s[48:49], 0, v[2:3]
	v_lshl_add_u64 v[10:11], s[44:45], 0, v[2:3]
	v_lshl_add_u64 v[2:3], s[12:13], 0, v[2:3]
	global_load_dwordx4 v[6:9], v[6:7], off
	v_lshl_add_u64 v[4:5], v[4:5], 0, s[42:43]
	global_load_dwordx4 v[10:13], v[10:11], off
	v_cmp_gt_u64_e64 s[4:5], s[8:9], v[4:5]
	global_load_dwordx4 v[14:17], v[2:3], off
	v_lshlrev_b64 v[2:3], 13, v[0:1]
	v_lshl_add_u64 v[2:3], s[40:41], 0, v[2:3]
	v_lshlrev_b32_e32 v0, 8, v18
	v_lshl_add_u64 v[2:3], v[2:3], 0, v[0:1]
	v_lshlrev_b32_e32 v0, 1, v19
	v_lshl_add_u64 v[2:3], v[2:3], 0, v[0:1]
	s_mov_b64 s[70:71], -1
	s_waitcnt vmcnt(3)
	v_max3_f32 v0, v32, v33, v34
	s_waitcnt vmcnt(2)
	v_lshlrev_b32_e32 v18, 16, v6
	v_and_b32_e32 v19, 0xffff0000, v6
	s_waitcnt vmcnt(1)
	v_lshlrev_b32_e32 v22, 16, v13
	v_and_b32_e32 v25, 0xffff0000, v13
	v_lshlrev_b32_e32 v26, 16, v10
	v_and_b32_e32 v29, 0xffff0000, v10
	s_waitcnt vmcnt(0)
	v_and_b32_e32 v31, 0xffff0000, v15
	v_lshlrev_b32_e32 v10, 16, v15
	v_sub_f32_e32 v13, v32, v0
	v_sub_f32_e32 v15, v33, v0
	v_sub_f32_e32 v0, v34, v0
	v_mul_f32_e32 v13, 0x3fb8aa3b, v13
	v_mul_f32_e32 v15, 0x3fb8aa3b, v15
	v_mul_f32_e32 v0, 0x3fb8aa3b, v0
	v_exp_f32_e32 v33, v13
	v_exp_f32_e32 v32, v15
	v_exp_f32_e32 v13, v0
	v_and_b32_e32 v23, 0xffff0000, v17
	v_lshlrev_b32_e32 v24, 16, v17
	v_add_f32_e32 v0, v33, v32
	v_add_f32_e32 v0, v13, v0
	v_div_scale_f32 v34, s[34:35], v0, v0, 1.0
	v_rcp_f32_e32 v35, v34
	v_and_b32_e32 v27, 0xffff0000, v14
	v_lshlrev_b32_e32 v28, 16, v14
	v_lshlrev_b32_e32 v14, 16, v12
	v_fma_f32 v36, -v34, v35, 1.0
	v_and_b32_e32 v17, 0xffff0000, v12
	v_div_scale_f32 v12, vcc, 1.0, v0, 1.0
	v_fmac_f32_e32 v35, v36, v35
	v_mul_f32_e32 v36, v12, v35
	v_fma_f32 v37, -v34, v36, v12
	v_fmac_f32_e32 v36, v37, v35
	v_fma_f32 v12, -v34, v36, v12
	v_div_fmas_f32 v12, v12, v35, v36
	v_div_fixup_f32 v0, v12, v0, 1.0
	v_lshlrev_b32_e32 v30, 16, v11
	v_and_b32_e32 v11, 0xffff0000, v11
	v_and_b32_e32 v15, 0xffff0000, v16
	v_lshlrev_b32_e32 v16, 16, v16
	v_pk_mul_f32 v[32:33], v[32:33], v[0:1] op_sel_hi:[1,0]
	v_lshlrev_b32_e32 v6, 16, v7
	v_pk_mul_f32 v[28:29], v[32:33], v[28:29] op_sel:[1,0] op_sel_hi:[0,1]
	v_pk_mul_f32 v[10:11], v[32:33], v[10:11] op_sel:[1,0] op_sel_hi:[0,1]
	v_pk_mul_f32 v[16:17], v[32:33], v[16:17] op_sel:[1,0] op_sel_hi:[0,1]
	v_pk_mul_f32 v[24:25], v[32:33], v[24:25] op_sel:[1,0] op_sel_hi:[0,1]
	v_and_b32_e32 v7, 0xffff0000, v7
	v_lshlrev_b32_e32 v20, 16, v8
	v_and_b32_e32 v21, 0xffff0000, v8
	v_lshlrev_b32_e32 v8, 16, v9
	v_and_b32_e32 v9, 0xffff0000, v9
	v_mul_f32_e32 v12, v13, v0
	v_pk_fma_f32 v[26:27], v[32:33], v[26:27], v[28:29]
	v_pk_fma_f32 v[10:11], v[32:33], v[30:31], v[10:11]
	v_pk_fma_f32 v[14:15], v[32:33], v[14:15], v[16:17]
	v_pk_fma_f32 v[16:17], v[32:33], v[22:23], v[24:25]
	v_pk_fma_f32 v[18:19], v[12:13], v[18:19], v[26:27] op_sel_hi:[0,1,1]
	v_pk_fma_f32 v[10:11], v[12:13], v[6:7], v[10:11] op_sel_hi:[0,1,1]
	v_pk_fma_f32 v[14:15], v[12:13], v[20:21], v[14:15] op_sel_hi:[0,1,1]
	v_pk_fma_f32 v[12:13], v[12:13], v[8:9], v[16:17] op_sel_hi:[0,1,1]
	v_cvt_pk_bf16_f32 v6, v18, v19
	v_cvt_pk_bf16_f32 v7, v10, v11
	v_cvt_pk_bf16_f32 v8, v14, v15
	v_cvt_pk_bf16_f32 v9, v12, v13
	global_store_dwordx4 v[2:3], v[6:9], off sc1
	s_and_saveexec_b64 s[68:69], s[4:5]
	s_cbranch_execz .LBB0_377
; __device__ NOINL void phase_scan_combine(const Params& p) {
;     ...
;   for (size_t item = gtid; item < (size_t)8192 * 192; item += gsz) {
;     size_t tok = item / 192; int hc = (int)(item % 192); int h = hc >> 4, c = hc & 15;
;     int b = (int)(tok >> 12), pos = (int)(tok & 4095);
;     float l0 = lse[(size_t)((0 * 2 + b) * 12 + h) * SEQ + pos];
;     float l1 = lse[(size_t)((1 * 2 + b) * 12 + h) * SEQ + pos];
;     float l2 = lse[(size_t)((2 * 2 + b) * 12 + h) * SEQ + pos];
;     float m = fmaxf(l0, fmaxf(l1, l2));
;     float w0 = __expf(l0 - m), w1 = __expf(l1 - m), w2 = __expf(l2 - m);
;     float inv = 1.f / (w0 + w1 + w2);
;     w0 *= inv; w1 *= inv; w2 *= inv;
;     size_t off = tok * 1536 + h * 128 + 8 * c;
;     float a[8], bb[8], cc[8], o[8];
;     unpack8(*(const uint4*)(part + off), a);
;     unpack8(*(const uint4*)(part + (size_t)8192 * 1536 + off), bb);
;     unpack8(*(const uint4*)(part + (size_t)2 * 8192 * 1536 + off), cc);
; #pragma unroll
;     for (int i = 0; i < 8; ++i) o[i] = w0 * a[i] + w1 * bb[i] + w2 * cc[i];
;     *(uint4*)(mix + tok * 4096 + h * 128 + 8 * c) = pack8(o);
;   }
	v_mul_hi_u32 v6, v4, s3
	v_lshrrev_b32_e32 v0, 7, v6
	v_mul_lo_u32 v2, v0, s15
	v_sub_u32_e32 v12, v4, v2
	v_lshrrev_b32_e32 v18, 4, v12
	v_lshrrev_b32_e32 v2, 19, v6
	v_lshrrev_b32_e32 v6, 5, v6
	v_mad_u32_u24 v10, v2, 12, v18
	v_and_b32_e32 v6, 0x3ffc, v6
	v_mov_b32_e32 v7, v1
	v_lshlrev_b32_e32 v2, 12, v10
	v_mov_b32_e32 v3, v1
	v_lshl_add_u64 v[8:9], s[38:39], 0, v[6:7]
	v_lshl_add_u64 v[2:3], v[2:3], 2, v[8:9]
	v_add_u32_e32 v8, 24, v10
	v_mov_b32_e32 v9, v1
	v_add_u32_e32 v10, 48, v10
	v_mov_b32_e32 v11, v1
	v_lshlrev_b64 v[8:9], 14, v[8:9]
	v_lshlrev_b64 v[10:11], 14, v[10:11]
	v_lshl_add_u64 v[8:9], s[38:39], 0, v[8:9]
	v_lshl_add_u64 v[10:11], s[38:39], 0, v[10:11]
	v_lshl_add_u64 v[8:9], v[8:9], 0, v[6:7]
	v_lshl_add_u64 v[6:7], v[10:11], 0, v[6:7]
	global_load_dword v32, v[2:3], off
	global_load_dword v33, v[8:9], off
	global_load_dword v34, v[6:7], off
	v_lshlrev_b32_e32 v2, 7, v18
	v_mov_b32_e32 v3, v1
	v_lshlrev_b32_e32 v6, 3, v12
	v_mad_u64_u32 v[2:3], s[4:5], v0, s33, v[2:3]
	v_and_b32_e32 v19, 0x78, v6
	v_or_b32_e32 v2, v2, v19
	v_lshlrev_b64 v[2:3], 1, v[2:3]
	v_lshl_add_u64 v[6:7], s[48:49], 0, v[2:3]
	v_lshl_add_u64 v[10:11], s[44:45], 0, v[2:3]
	v_lshl_add_u64 v[2:3], s[12:13], 0, v[2:3]
	global_load_dwordx4 v[6:9], v[6:7], off
	s_nop 0
	global_load_dwordx4 v[14:17], v[2:3], off
	v_lshl_add_u64 v[2:3], v[4:5], 0, s[42:43]
	global_load_dwordx4 v[10:13], v[10:11], off
	v_lshlrev_b64 v[4:5], 13, v[0:1]
	v_lshl_add_u64 v[4:5], s[40:41], 0, v[4:5]
	v_lshlrev_b32_e32 v0, 8, v18
	v_lshl_add_u64 v[4:5], v[4:5], 0, v[0:1]
	v_lshlrev_b32_e32 v0, 1, v19
	v_lshl_add_u64 v[18:19], v[4:5], 0, v[0:1]
	v_cmp_lt_u64_e64 s[4:5], s[60:61], v[2:3]
	s_orn2_b64 s[70:71], s[4:5], exec
	s_waitcnt vmcnt(3)
	v_max3_f32 v0, v32, v33, v34
	s_waitcnt vmcnt(2)
	v_lshlrev_b32_e32 v4, 16, v6
	v_and_b32_e32 v5, 0xffff0000, v6
	s_waitcnt vmcnt(1)
	v_and_b32_e32 v31, 0xffff0000, v15
	v_and_b32_e32 v23, 0xffff0000, v17
	s_waitcnt vmcnt(0)
	v_lshlrev_b32_e32 v22, 16, v13
	v_and_b32_e32 v25, 0xffff0000, v13
	v_lshlrev_b32_e32 v26, 16, v10
	v_and_b32_e32 v29, 0xffff0000, v10
	v_lshlrev_b32_e32 v10, 16, v15
	v_sub_f32_e32 v13, v32, v0
	v_sub_f32_e32 v15, v33, v0
	v_sub_f32_e32 v0, v34, v0
	v_mul_f32_e32 v13, 0x3fb8aa3b, v13
	v_mul_f32_e32 v15, 0x3fb8aa3b, v15
	v_mul_f32_e32 v0, 0x3fb8aa3b, v0
	v_exp_f32_e32 v33, v13
	v_exp_f32_e32 v32, v15
	v_exp_f32_e32 v13, v0
	v_lshlrev_b32_e32 v24, 16, v17
	v_and_b32_e32 v27, 0xffff0000, v14
	v_add_f32_e32 v0, v33, v32
	v_add_f32_e32 v0, v13, v0
	v_div_scale_f32 v34, s[34:35], v0, v0, 1.0
	v_rcp_f32_e32 v35, v34
	v_lshlrev_b32_e32 v28, 16, v14
	v_lshlrev_b32_e32 v14, 16, v12
	v_and_b32_e32 v17, 0xffff0000, v12
	v_fma_f32 v36, -v34, v35, 1.0
	v_div_scale_f32 v12, vcc, 1.0, v0, 1.0
	v_fmac_f32_e32 v35, v36, v35
	v_mul_f32_e32 v36, v12, v35
	v_fma_f32 v37, -v34, v36, v12
	v_fmac_f32_e32 v36, v37, v35
	v_fma_f32 v12, -v34, v36, v12
	v_div_fmas_f32 v12, v12, v35, v36
	v_div_fixup_f32 v0, v12, v0, 1.0
	v_lshlrev_b32_e32 v30, 16, v11
	v_and_b32_e32 v11, 0xffff0000, v11
	v_and_b32_e32 v15, 0xffff0000, v16
	v_lshlrev_b32_e32 v16, 16, v16
	v_pk_mul_f32 v[32:33], v[32:33], v[0:1] op_sel_hi:[1,0]
	v_lshlrev_b32_e32 v6, 16, v7
	v_pk_mul_f32 v[28:29], v[32:33], v[28:29] op_sel:[1,0] op_sel_hi:[0,1]
	v_pk_mul_f32 v[10:11], v[32:33], v[10:11] op_sel:[1,0] op_sel_hi:[0,1]
	v_pk_mul_f32 v[16:17], v[32:33], v[16:17] op_sel:[1,0] op_sel_hi:[0,1]
	v_pk_mul_f32 v[24:25], v[32:33], v[24:25] op_sel:[1,0] op_sel_hi:[0,1]
	v_and_b32_e32 v7, 0xffff0000, v7
	v_lshlrev_b32_e32 v20, 16, v8
	v_and_b32_e32 v21, 0xffff0000, v8
	v_lshlrev_b32_e32 v8, 16, v9
	v_and_b32_e32 v9, 0xffff0000, v9
	v_mul_f32_e32 v12, v13, v0
	v_pk_fma_f32 v[26:27], v[32:33], v[26:27], v[28:29]
	v_pk_fma_f32 v[10:11], v[32:33], v[30:31], v[10:11]
	v_pk_fma_f32 v[14:15], v[32:33], v[14:15], v[16:17]
	v_pk_fma_f32 v[16:17], v[32:33], v[22:23], v[24:25]
	v_pk_fma_f32 v[4:5], v[12:13], v[4:5], v[26:27] op_sel_hi:[0,1,1]
	v_pk_fma_f32 v[6:7], v[12:13], v[6:7], v[10:11] op_sel_hi:[0,1,1]
	v_pk_fma_f32 v[10:11], v[12:13], v[20:21], v[14:15] op_sel_hi:[0,1,1]
	v_pk_fma_f32 v[8:9], v[12:13], v[8:9], v[16:17] op_sel_hi:[0,1,1]
	v_cvt_pk_bf16_f32 v4, v4, v5
	v_cvt_pk_bf16_f32 v5, v6, v7
	v_cvt_pk_bf16_f32 v6, v10, v11
	v_cvt_pk_bf16_f32 v7, v8, v9
	global_store_dwordx4 v[18:19], v[4:7], off sc1
	s_branch .LBB0_377

; template <int MODE> ...
;     ...
; #pragma unroll 8
;           for (int it = 0; it < 16; ++it) {
;             int item = it * 512 + t2, row = item >> 6, q = item & 63;
;             float4 v = *(const float4*)(ls + row * 1024 + ((q ^ (((row >> 2) & 3) << 3)) << 4));
;             long g = gb + (long)row * ldc + q * 4;
;             float4 r = *(const float4*)(resid + g);
;             if (MODE == 4) {
;               float2 st = *(const float2*)(aux0 + 2 * (long)(brow + ai * HALF + row));
;               float4 gg = *(const float4*)(aux1 + bcol + q * 4), bb = *(const float4*)(aux2 + bcol + q * 4);
;               r.x = (r.x - st.x) * st.y * gg.x + bb.x; r.y = (r.y - st.x) * st.y * gg.y + bb.y;
;               r.z = (r.z - st.x) * st.y * gg.z + bb.z; r.w = (r.w - st.x) * st.y * gg.w + bb.w;
;             }
;             float4 o; o.x = ALPHA * r.x + v.x; o.y = ALPHA * r.y + v.y; o.z = ALPHA * r.z + v.z; o.w = ALPHA * r.w + v.w;
;             *(float4*)(outf + g) = o;
;           }
.LBB0_490:
	v_add_u32_e32 v65, s63, v138
	v_ashrrev_i32_e32 v64, 6, v65
	v_add_u32_e32 v67, 0x200, v65
	v_add_u32_e32 v68, 0x400, v65
	v_add_u32_e32 v87, 0x600, v65
	v_add_u32_e32 v69, 0x800, v65
	v_add_u32_e32 v108, 0xa00, v65
	v_add_u32_e32 v70, 0xc00, v65
	v_add_u32_e32 v109, 0xe00, v65
	v_ashrrev_i32_e32 v65, 31, v64
	v_ashrrev_i32_e32 v142, 6, v67
	v_ashrrev_i32_e32 v116, 6, v68
	v_ashrrev_i32_e32 v162, 6, v87
	v_ashrrev_i32_e32 v118, 6, v69
	v_ashrrev_i32_e32 v170, 6, v108
	v_ashrrev_i32_e32 v124, 6, v70
	v_ashrrev_i32_e32 v172, 6, v109
	v_lshl_add_u64 v[68:69], v[64:65], 0, s[66:67]
	v_ashrrev_i32_e32 v143, 31, v142
	v_ashrrev_i32_e32 v117, 31, v116
	v_ashrrev_i32_e32 v163, 31, v162
	v_ashrrev_i32_e32 v119, 31, v118
	v_ashrrev_i32_e32 v171, 31, v170
	v_ashrrev_i32_e32 v125, 31, v124
	v_ashrrev_i32_e32 v173, 31, v172
	v_lshlrev_b64 v[68:69], 12, v[68:69]
	v_lshl_add_u64 v[70:71], v[142:143], 0, s[66:67]
	v_lshl_add_u64 v[72:73], v[116:117], 0, s[66:67]
	v_lshl_add_u64 v[74:75], v[162:163], 0, s[66:67]
	v_lshl_add_u64 v[76:77], v[118:119], 0, s[66:67]
	v_lshl_add_u64 v[78:79], v[170:171], 0, s[66:67]
	v_lshl_add_u64 v[80:81], v[124:125], 0, s[66:67]
	v_lshl_add_u64 v[82:83], v[172:173], 0, s[66:67]
	v_lshl_add_u64 v[68:69], v[68:69], 0, v[136:137]
	v_lshlrev_b64 v[70:71], 12, v[70:71]
	v_lshlrev_b64 v[72:73], 12, v[72:73]
	v_lshlrev_b64 v[74:75], 12, v[74:75]
	v_lshlrev_b64 v[76:77], 12, v[76:77]
	v_lshlrev_b64 v[78:79], 12, v[78:79]
	v_lshlrev_b64 v[80:81], 12, v[80:81]
	v_lshlrev_b64 v[82:83], 12, v[82:83]
	v_lshlrev_b64 v[186:187], 2, v[68:69]
	v_lshl_add_u64 v[68:69], v[70:71], 0, v[136:137]
	v_lshl_add_u64 v[70:71], v[72:73], 0, v[136:137]
	v_lshl_add_u64 v[72:73], v[74:75], 0, v[136:137]
	v_lshl_add_u64 v[74:75], v[76:77], 0, v[136:137]
	v_lshl_add_u64 v[76:77], v[78:79], 0, v[136:137]
	v_lshl_add_u64 v[78:79], v[80:81], 0, v[136:137]
	v_lshl_add_u64 v[80:81], v[82:83], 0, v[136:137]
	v_lshl_add_u64 v[82:83], s[36:37], 0, v[186:187]
	v_lshlrev_b64 v[188:189], 2, v[68:69]
	v_lshlrev_b64 v[190:191], 2, v[70:71]
	v_lshlrev_b64 v[192:193], 2, v[72:73]
	v_lshlrev_b64 v[194:195], 2, v[74:75]
	v_lshlrev_b64 v[196:197], 2, v[76:77]
	v_lshlrev_b64 v[198:199], 2, v[78:79]
	v_lshlrev_b64 v[200:201], 2, v[80:81]
	global_load_dwordx4 v[68:71], v[82:83], off
	v_lshl_add_u64 v[72:73], s[36:37], 0, v[188:189]
	v_lshl_add_u64 v[76:77], s[36:37], 0, v[190:191]
	v_lshl_add_u64 v[80:81], s[36:37], 0, v[192:193]
	v_lshl_add_u64 v[88:89], s[36:37], 0, v[194:195]
	v_lshl_add_u64 v[92:93], s[36:37], 0, v[196:197]
	v_lshl_add_u64 v[96:97], s[36:37], 0, v[198:199]
	v_lshl_add_u64 v[100:101], s[36:37], 0, v[200:201]
	global_load_dwordx4 v[72:75], v[72:73], off
	s_nop 0
	global_load_dwordx4 v[76:79], v[76:77], off
	s_nop 0
	global_load_dwordx4 v[80:83], v[80:81], off
	s_nop 0
	global_load_dwordx4 v[88:91], v[88:89], off
	s_nop 0
	global_load_dwordx4 v[92:95], v[92:93], off
	s_nop 0
	global_load_dwordx4 v[96:99], v[96:97], off
	s_nop 0
	global_load_dwordx4 v[100:103], v[100:101], off
	v_lshl_or_b32 v64, v64, 10, v66
	v_lshrrev_b32_e32 v65, 5, v67
	v_lshl_or_b32 v125, v118, 10, v66
	v_lshrrev_b32_e32 v67, 5, v87
	v_lshrrev_b32_e32 v87, 5, v108
	v_lshrrev_b32_e32 v117, 5, v109
	ds_read_b128 v[108:111], v64
	v_lshl_or_b32 v141, v124, 10, v66
	ds_read_b128 v[124:127], v125
	v_bitop3_b32 v64, v65, v139, 24 bitop3:0x6c
	v_lshl_or_b32 v65, v116, 10, v66
	v_bitop3_b32 v67, v67, v139, 24 bitop3:0x6c
	v_bitop3_b32 v87, v87, v139, 24 bitop3:0x6c
	v_bitop3_b32 v143, v117, v139, 24 bitop3:0x6c
	v_lshlrev_b32_e32 v64, 4, v64
	ds_read_b128 v[116:119], v65
	ds_read_b128 v[166:169], v141
	v_lshlrev_b32_e32 v65, 4, v67
	v_lshlrev_b32_e32 v67, 4, v87
	v_lshlrev_b32_e32 v87, 4, v143
	v_lshl_or_b32 v64, v142, 10, v64
	v_lshl_or_b32 v65, v162, 10, v65
	v_lshl_or_b32 v67, v170, 10, v67
	v_lshl_or_b32 v87, v172, 10, v87
	ds_read_b128 v[170:173], v64
	ds_read_b128 v[174:177], v65
	ds_read_b128 v[178:181], v67
	ds_read_b128 v[182:185], v87
	s_addk_i32 s63, 0x1000
	v_lshl_add_u64 v[64:65], s[10:11], 0, v[186:187]
	s_cmpk_eq_i32 s63, 0x2000
	v_lshl_add_u64 v[142:143], s[10:11], 0, v[188:189]
	v_lshl_add_u64 v[162:163], s[10:11], 0, v[190:191]
	v_lshl_add_u64 v[186:187], s[10:11], 0, v[192:193]
	v_lshl_add_u64 v[188:189], s[10:11], 0, v[194:195]
	v_lshl_add_u64 v[190:191], s[10:11], 0, v[196:197]
	v_lshl_add_u64 v[192:193], s[10:11], 0, v[198:199]
	v_lshl_add_u64 v[194:195], s[10:11], 0, v[200:201]
	s_waitcnt vmcnt(0) lgkmcnt(0)
	v_pk_fma_f32 v[68:69], v[68:69], s[62:63], v[108:109] op_sel_hi:[1,0,1]
	v_pk_fma_f32 v[70:71], v[70:71], s[62:63], v[110:111] op_sel_hi:[1,0,1]
	global_store_dwordx4 v[64:65], v[68:71], off sc1
	s_nop 1
	v_pk_fma_f32 v[68:69], v[72:73], s[62:63], v[170:171] op_sel_hi:[1,0,1]
	v_pk_fma_f32 v[70:71], v[74:75], s[62:63], v[172:173] op_sel_hi:[1,0,1]
	v_pk_fma_f32 v[72:73], v[76:77], s[62:63], v[116:117] op_sel_hi:[1,0,1]
	v_pk_fma_f32 v[74:75], v[78:79], s[62:63], v[118:119] op_sel_hi:[1,0,1]
	v_pk_fma_f32 v[76:77], v[80:81], s[62:63], v[174:175] op_sel_hi:[1,0,1]
	v_pk_fma_f32 v[78:79], v[82:83], s[62:63], v[176:177] op_sel_hi:[1,0,1]
	v_pk_fma_f32 v[80:81], v[88:89], s[62:63], v[124:125] op_sel_hi:[1,0,1]
	v_pk_fma_f32 v[82:83], v[90:91], s[62:63], v[126:127] op_sel_hi:[1,0,1]
	v_pk_fma_f32 v[88:89], v[92:93], s[62:63], v[178:179] op_sel_hi:[1,0,1]
	v_pk_fma_f32 v[90:91], v[94:95], s[62:63], v[180:181] op_sel_hi:[1,0,1]
	v_pk_fma_f32 v[92:93], v[96:97], s[62:63], v[166:167] op_sel_hi:[1,0,1]
	v_pk_fma_f32 v[94:95], v[98:99], s[62:63], v[168:169] op_sel_hi:[1,0,1]
	v_pk_fma_f32 v[96:97], v[100:101], s[62:63], v[182:183] op_sel_hi:[1,0,1]
	v_pk_fma_f32 v[98:99], v[102:103], s[62:63], v[184:185] op_sel_hi:[1,0,1]
	global_store_dwordx4 v[142:143], v[68:71], off sc1
	global_store_dwordx4 v[162:163], v[72:75], off sc1
	global_store_dwordx4 v[186:187], v[76:79], off sc1
	global_store_dwordx4 v[188:189], v[80:83], off sc1
	global_store_dwordx4 v[190:191], v[88:91], off sc1
	global_store_dwordx4 v[192:193], v[92:95], off sc1
	global_store_dwordx4 v[194:195], v[96:99], off sc1
	s_cbranch_scc0 .LBB0_490
; DEVI void lds_barrier() { asm volatile("s_waitcnt lgkmcnt(0)" ::: "memory"); __builtin_amdgcn_s_barrier(); asm volatile("" ::: "memory"); }
; template <int MODE> ...
;     ...
;         for (int ai = 0; ai < 2; ++ai) {
;           if (ai) lds_barrier();
; #pragma unroll
;           for (int bj = 0; bj < 2; ++bj)
; #pragma unroll
;             for (int m = 0; m < 4; ++m)
; #pragma unroll
;               for (int n = 0; n < 2; ++n)
; #pragma unroll
;                 for (int j = 0; j < 4; ++j)
;                   *(float*)(ls + wbase + ((m * 16 + j) * 1024 + (bj * 32 + n * 4) * 16)) = acc[ai][bj][m][n][j];
;           lds_barrier();
	s_waitcnt lgkmcnt(0)
	s_barrier
	ds_write2_b32 v140, v0, v32 offset1:16
	ds_write2_b32 v120, v1, v33 offset1:16
	ds_write2_b32 v121, v2, v34 offset1:16
	ds_write2_b32 v122, v3, v35 offset1:16
	ds_write2_b32 v123, v4, v36 offset1:16
	ds_write2_b32 v112, v5, v37 offset1:16
	ds_write2_b32 v113, v6, v38 offset1:16
	ds_write2_b32 v114, v7, v39 offset1:16
	ds_write2_b32 v115, v8, v40 offset1:16
	ds_write2_b32 v104, v9, v41 offset1:16
	ds_write2_b32 v105, v10, v42 offset1:16
	ds_write2_b32 v106, v11, v43 offset1:16
	ds_write2_b32 v107, v12, v44 offset1:16
	ds_write2_b32 v84, v13, v45 offset1:16
	ds_write2_b32 v85, v14, v46 offset1:16
	ds_write2_b32 v86, v15, v47 offset1:16
	ds_write2_b32 v140, v16, v48 offset0:128 offset1:144
	ds_write2_b32 v120, v17, v49 offset0:128 offset1:144
	ds_write2_b32 v121, v18, v50 offset0:128 offset1:144
	ds_write2_b32 v122, v19, v51 offset0:128 offset1:144
	ds_write2_b32 v123, v20, v52 offset0:128 offset1:144
	ds_write2_b32 v112, v21, v53 offset0:128 offset1:144
	ds_write2_b32 v113, v22, v54 offset0:128 offset1:144
	ds_write2_b32 v114, v23, v55 offset0:128 offset1:144
	ds_write2_b32 v115, v24, v56 offset0:128 offset1:144
	ds_write2_b32 v104, v25, v57 offset0:128 offset1:144
	ds_write2_b32 v105, v26, v58 offset0:128 offset1:144
	ds_write2_b32 v106, v27, v59 offset0:128 offset1:144
	ds_write2_b32 v107, v28, v60 offset0:128 offset1:144
	ds_write2_b32 v84, v29, v61 offset0:128 offset1:144
	ds_write2_b32 v85, v30, v62 offset0:128 offset1:144
	ds_write2_b32 v86, v31, v63 offset0:128 offset1:144
	s_waitcnt lgkmcnt(0)
	s_barrier
	s_mov_b32 s63, 0
; template <int MODE> ...
;     ...
; #pragma unroll 8
;           for (int it = 0; it < 16; ++it) {
;             int item = it * 512 + t2, row = item >> 6, q = item & 63;
;             float4 v = *(const float4*)(ls + row * 1024 + ((q ^ (((row >> 2) & 3) << 3)) << 4));
;             long g = gb + (long)row * ldc + q * 4;
;             float4 r = *(const float4*)(resid + g);
;             if (MODE == 4) {
;               float2 st = *(const float2*)(aux0 + 2 * (long)(brow + ai * HALF + row));
;               float4 gg = *(const float4*)(aux1 + bcol + q * 4), bb = *(const float4*)(aux2 + bcol + q * 4);
;               r.x = (r.x - st.x) * st.y * gg.x + bb.x; r.y = (r.y - st.x) * st.y * gg.y + bb.y;
;               r.z = (r.z - st.x) * st.y * gg.z + bb.z; r.w = (r.w - st.x) * st.y * gg.w + bb.w;
;             }
;             float4 o; o.x = ALPHA * r.x + v.x; o.y = ALPHA * r.y + v.y; o.z = ALPHA * r.z + v.z; o.w = ALPHA * r.w + v.w;
;             *(float4*)(outf + g) = o;
;           }
.LBB0_492:
	v_add_u32_e32 v1, s63, v138
	v_ashrrev_i32_e32 v0, 6, v1
	v_add_u32_e32 v34, 0x200, v1
	v_add_u32_e32 v2, 0x400, v1
	v_add_u32_e32 v35, 0x600, v1
	v_add_u32_e32 v3, 0x800, v1
	v_add_u32_e32 v36, 0xa00, v1
	v_add_u32_e32 v4, 0xc00, v1
	v_add_u32_e32 v37, 0xe00, v1
	v_ashrrev_i32_e32 v1, 31, v0
	v_ashrrev_i32_e32 v50, 6, v34
	v_ashrrev_i32_e32 v38, 6, v2
	v_ashrrev_i32_e32 v52, 6, v35
	v_ashrrev_i32_e32 v40, 6, v3
	v_ashrrev_i32_e32 v54, 6, v36
	v_ashrrev_i32_e32 v42, 6, v4
	v_ashrrev_i32_e32 v56, 6, v37
	v_lshl_add_u64 v[2:3], v[0:1], 0, s[64:65]
	v_ashrrev_i32_e32 v51, 31, v50
	v_ashrrev_i32_e32 v39, 31, v38
	v_ashrrev_i32_e32 v53, 31, v52
	v_ashrrev_i32_e32 v41, 31, v40
	v_ashrrev_i32_e32 v55, 31, v54
	v_ashrrev_i32_e32 v43, 31, v42
	v_ashrrev_i32_e32 v57, 31, v56
	v_lshlrev_b64 v[2:3], 12, v[2:3]
	v_lshl_add_u64 v[4:5], v[50:51], 0, s[64:65]
	v_lshl_add_u64 v[6:7], v[38:39], 0, s[64:65]
	v_lshl_add_u64 v[8:9], v[52:53], 0, s[64:65]
	v_lshl_add_u64 v[10:11], v[40:41], 0, s[64:65]
	v_lshl_add_u64 v[12:13], v[54:55], 0, s[64:65]
	v_lshl_add_u64 v[14:15], v[42:43], 0, s[64:65]
	v_lshl_add_u64 v[16:17], v[56:57], 0, s[64:65]
	v_lshl_add_u64 v[2:3], v[2:3], 0, v[136:137]
	v_lshlrev_b64 v[4:5], 12, v[4:5]
	v_lshlrev_b64 v[6:7], 12, v[6:7]
	v_lshlrev_b64 v[8:9], 12, v[8:9]
	v_lshlrev_b64 v[10:11], 12, v[10:11]
	v_lshlrev_b64 v[12:13], 12, v[12:13]
	v_lshlrev_b64 v[14:15], 12, v[14:15]
	v_lshlrev_b64 v[16:17], 12, v[16:17]
	v_lshlrev_b64 v[68:69], 2, v[2:3]
	v_lshl_add_u64 v[2:3], v[4:5], 0, v[136:137]
	v_lshl_add_u64 v[4:5], v[6:7], 0, v[136:137]
	v_lshl_add_u64 v[6:7], v[8:9], 0, v[136:137]
	v_lshl_add_u64 v[8:9], v[10:11], 0, v[136:137]
	v_lshl_add_u64 v[10:11], v[12:13], 0, v[136:137]
	v_lshl_add_u64 v[12:13], v[14:15], 0, v[136:137]
	v_lshl_add_u64 v[14:15], v[16:17], 0, v[136:137]
	v_lshl_add_u64 v[16:17], s[36:37], 0, v[68:69]
	v_lshlrev_b64 v[70:71], 2, v[2:3]
	v_lshlrev_b64 v[72:73], 2, v[4:5]
	v_lshlrev_b64 v[74:75], 2, v[6:7]
	v_lshlrev_b64 v[76:77], 2, v[8:9]
	v_lshlrev_b64 v[78:79], 2, v[10:11]
	v_lshlrev_b64 v[80:81], 2, v[12:13]
	v_lshlrev_b64 v[82:83], 2, v[14:15]
	global_load_dwordx4 v[2:5], v[16:17], off
	v_lshl_add_u64 v[6:7], s[36:37], 0, v[70:71]
	v_lshl_add_u64 v[10:11], s[36:37], 0, v[72:73]
	v_lshl_add_u64 v[14:15], s[36:37], 0, v[74:75]
	v_lshl_add_u64 v[18:19], s[36:37], 0, v[76:77]
	v_lshl_add_u64 v[22:23], s[36:37], 0, v[78:79]
	v_lshl_add_u64 v[26:27], s[36:37], 0, v[80:81]
	v_lshl_add_u64 v[30:31], s[36:37], 0, v[82:83]
	global_load_dwordx4 v[6:9], v[6:7], off
	s_nop 0
	global_load_dwordx4 v[10:13], v[10:11], off
	s_nop 0
	global_load_dwordx4 v[14:17], v[14:15], off
	s_nop 0
	global_load_dwordx4 v[18:21], v[18:19], off
	s_nop 0
	global_load_dwordx4 v[22:25], v[22:23], off
	s_nop 0
	global_load_dwordx4 v[26:29], v[26:27], off
	s_nop 0
	global_load_dwordx4 v[30:33], v[30:31], off
	v_lshrrev_b32_e32 v41, 5, v36
	v_lshl_or_b32 v0, v0, 10, v66
	v_lshrrev_b32_e32 v1, 5, v34
	v_lshrrev_b32_e32 v43, 5, v37
	v_bitop3_b32 v46, v41, v139, 24 bitop3:0x6c
	v_lshl_or_b32 v47, v42, 10, v66
	v_lshrrev_b32_e32 v39, 5, v35
	ds_read_b128 v[34:37], v0
	v_bitop3_b32 v51, v43, v139, 24 bitop3:0x6c
	v_lshlrev_b32_e32 v53, 4, v46
	ds_read_b128 v[46:49], v47
	v_bitop3_b32 v0, v1, v139, 24 bitop3:0x6c
	v_lshl_or_b32 v1, v38, 10, v66
	v_bitop3_b32 v44, v39, v139, 24 bitop3:0x6c
	v_lshlrev_b32_e32 v0, 4, v0
	v_lshlrev_b32_e32 v51, 4, v51
	v_lshl_or_b32 v45, v40, 10, v66
	ds_read_b128 v[38:41], v1
	v_lshlrev_b32_e32 v1, 4, v44
	v_lshl_or_b32 v0, v50, 10, v0
	v_lshl_or_b32 v58, v54, 10, v53
	v_lshl_or_b32 v62, v56, 10, v51
	ds_read_b128 v[42:45], v45
	v_lshl_or_b32 v1, v52, 10, v1
	ds_read_b128 v[50:53], v0
	ds_read_b128 v[54:57], v1
	ds_read_b128 v[58:61], v58
	ds_read_b128 v[62:65], v62
	s_addk_i32 s63, 0x1000
	v_lshl_add_u64 v[68:69], s[10:11], 0, v[68:69]
	s_cmpk_lg_i32 s63, 0x2000
	v_lshl_add_u64 v[70:71], s[10:11], 0, v[70:71]
	v_lshl_add_u64 v[72:73], s[10:11], 0, v[72:73]
	v_lshl_add_u64 v[74:75], s[10:11], 0, v[74:75]
	v_lshl_add_u64 v[76:77], s[10:11], 0, v[76:77]
	v_lshl_add_u64 v[78:79], s[10:11], 0, v[78:79]
	v_lshl_add_u64 v[80:81], s[10:11], 0, v[80:81]
	v_lshl_add_u64 v[82:83], s[10:11], 0, v[82:83]
	s_waitcnt vmcnt(7) lgkmcnt(7)
	v_pk_fma_f32 v[0:1], v[2:3], s[62:63], v[34:35] op_sel_hi:[1,0,1]
	v_pk_fma_f32 v[2:3], v[4:5], s[62:63], v[36:37] op_sel_hi:[1,0,1]
	global_store_dwordx4 v[68:69], v[0:3], off sc1
	s_waitcnt vmcnt(6) lgkmcnt(5)
	v_pk_fma_f32 v[4:5], v[10:11], s[62:63], v[38:39] op_sel_hi:[1,0,1]
	s_waitcnt vmcnt(5) lgkmcnt(2)
	v_pk_fma_f32 v[10:11], v[16:17], s[62:63], v[56:57] op_sel_hi:[1,0,1]
	v_pk_fma_f32 v[0:1], v[6:7], s[62:63], v[50:51] op_sel_hi:[1,0,1]
	v_pk_fma_f32 v[2:3], v[8:9], s[62:63], v[52:53] op_sel_hi:[1,0,1]
	v_pk_fma_f32 v[6:7], v[12:13], s[62:63], v[40:41] op_sel_hi:[1,0,1]
	v_pk_fma_f32 v[8:9], v[14:15], s[62:63], v[54:55] op_sel_hi:[1,0,1]
	s_waitcnt vmcnt(4)
	v_pk_fma_f32 v[12:13], v[18:19], s[62:63], v[42:43] op_sel_hi:[1,0,1]
	v_pk_fma_f32 v[14:15], v[20:21], s[62:63], v[44:45] op_sel_hi:[1,0,1]
	s_waitcnt vmcnt(3) lgkmcnt(1)
	v_pk_fma_f32 v[16:17], v[22:23], s[62:63], v[58:59] op_sel_hi:[1,0,1]
	v_pk_fma_f32 v[18:19], v[24:25], s[62:63], v[60:61] op_sel_hi:[1,0,1]
	s_waitcnt vmcnt(2)
	v_pk_fma_f32 v[20:21], v[26:27], s[62:63], v[46:47] op_sel_hi:[1,0,1]
	v_pk_fma_f32 v[22:23], v[28:29], s[62:63], v[48:49] op_sel_hi:[1,0,1]
	s_waitcnt vmcnt(1) lgkmcnt(0)
	v_pk_fma_f32 v[24:25], v[30:31], s[62:63], v[62:63] op_sel_hi:[1,0,1]
	v_pk_fma_f32 v[26:27], v[32:33], s[62:63], v[64:65] op_sel_hi:[1,0,1]
	global_store_dwordx4 v[70:71], v[0:3], off sc1
	global_store_dwordx4 v[72:73], v[4:7], off sc1
	global_store_dwordx4 v[74:75], v[8:11], off sc1
	global_store_dwordx4 v[76:77], v[12:15], off sc1
	global_store_dwordx4 v[78:79], v[16:19], off sc1
	global_store_dwordx4 v[80:81], v[20:23], off sc1
	global_store_dwordx4 v[82:83], v[24:27], off sc1
	s_cbranch_scc1 .LBB0_492
	s_waitcnt lgkmcnt(0)
	s_barrier
	s_add_i32 s35, s35, s14
	s_cmpk_gt_i32 s35, 0x1ff
	s_cbranch_scc0 .LBB0_479

; template <int MODE> ...
;     ...
; #pragma unroll 4
;         for (int it = 0; it < 8; ++it) {
;           int item = it * 512 + t2, row = item >> 4, q = item & 15;
;           uint4 v = *(const uint4*)(ls + 65536 + row * 256 + ((q ^ (((row >> 2) & 3) << 2)) << 4));
;           *(uint4*)(ob + (long)row * ldc + q * 8) = v;
;         }
.LBB0_663:
	v_add_u32_e32 v3, s8, v140
	v_ashrrev_i32_e32 v4, 4, v3
	v_add_u32_e32 v5, 0x200, v3
	v_add_u32_e32 v6, 0x400, v3
	v_add_u32_e32 v3, 0x600, v3
	v_lshl_add_u32 v7, v4, 8, v2
	v_mad_i64_i32 v[20:21], s[10:11], v4, s84, v[0:1]
	v_ashrrev_i32_e32 v4, 4, v5
	v_ashrrev_i32_e32 v5, 4, v6
	v_ashrrev_i32_e32 v3, 4, v3
	v_lshl_add_u32 v8, v4, 8, v2
	v_lshl_add_u32 v12, v5, 8, v2
	v_lshl_add_u32 v16, v3, 8, v2
	v_mad_i64_i32 v[22:23], s[10:11], v4, s84, v[0:1]
	v_mad_i64_i32 v[24:25], s[10:11], v5, s84, v[0:1]
	ds_read_b128 v[4:7], v7
	ds_read_b128 v[8:11], v8
	ds_read_b128 v[12:15], v12
	ds_read_b128 v[16:19], v16
	s_addk_i32 s8, 0x800
	s_cmpk_eq_i32 s8, 0x1000
	v_mad_i64_i32 v[26:27], s[10:11], v3, s84, v[0:1]
	s_waitcnt lgkmcnt(3)
	global_store_dwordx4 v[20:21], v[4:7], off sc1
	s_waitcnt lgkmcnt(2)
	global_store_dwordx4 v[22:23], v[8:11], off sc1
	s_waitcnt lgkmcnt(1)
	global_store_dwordx4 v[24:25], v[12:15], off sc1
	s_waitcnt lgkmcnt(0)
	global_store_dwordx4 v[26:27], v[16:19], off sc1
	s_cbranch_scc0 .LBB0_663
	s_waitcnt lgkmcnt(0)
	s_barrier
	s_add_i32 s85, s85, s14
	s_cmpk_gt_i32 s85, 0xabf
	s_cbranch_scc0 .LBB0_588
	v_lshlrev_b32_e32 v6, 2, v164

; DEVI unsigned pack2(float a, float b) { f32v2 v = {a, b}; return __builtin_bit_cast(unsigned, __builtin_convertvector(v, bf16v2)); }
; DEVI void lds_barrier() { asm volatile("s_waitcnt lgkmcnt(0)" ::: "memory"); __builtin_amdgcn_s_barrier(); asm volatile("" ::: "memory"); }
; DEVI void tconv_store(const TcPre& R, u16* __restrict__ Wt, int K, int N, int t, float* lds, bool perm) {
;     ...
;     float* d = lds + (tid >> 5) * 129 + (tid & 31) * 4;
;     d[0] = R.a[0]; d[1] = R.a[1]; d[2] = R.a[2]; d[3] = R.a[3];
;     d[16 * 129] = R.b[0]; d[16 * 129 + 1] = R.b[1]; d[16 * 129 + 2] = R.b[2]; d[16 * 129 + 3] = R.b[3];
;     d[32 * 129] = R.c[0]; d[32 * 129 + 1] = R.c[1]; d[32 * 129 + 2] = R.c[2]; d[32 * 129 + 3] = R.c[3];
;     d[48 * 129] = R.d[0]; d[48 * 129 + 1] = R.d[1]; d[48 * 129 + 2] = R.d[2]; d[48 * 129 + 3] = R.d[3];
;   }
;   lds_barrier();
;   int n0p = !perm ? n0 : (n0 < DFF ? (n0 / 128) * 256 : ((n0 - DFF) / 128) * 256 + 128);
; #pragma unroll
;   for (int p = 0; p < 2; ++p) {
;     int item = p * 512 + tid, n = item >> 3, kg = item & 7;
;     const float* s = lds + (kg * 8) * 129 + n;
;     uint4 o;
;     o.x = pack2(s[0], s[129]); o.y = pack2(s[2 * 129], s[3 * 129]);
;     o.z = pack2(s[4 * 129], s[5 * 129]); o.w = pack2(s[6 * 129], s[7 * 129]);
;     *(uint4*)(Wt + (size_t)(n0p + n) * K + k0 + kg * 8) = o;
.Ldcv1_a_st:
	s_add_u32 s6, s86, 0
	s_mul_i32 s6, s6, 0x2b0000
	s_add_u32 s72, s84, s6
	s_addc_u32 s73, s85, 0
	s_add_u32 s78, s72, 0x158000
	s_addc_u32 s79, s73, 0
	s_waitcnt vmcnt(20)
	ds_write2_b32 v58, v168, v169 offset1:1
	ds_write2_b32 v58, v170, v171 offset0:2 offset1:3
	ds_write2_b32 v59, v172, v173 offset1:1
	ds_write2_b32 v59, v174, v175 offset0:2 offset1:3
	ds_write2_b32 v60, v176, v177 offset1:1
	ds_write2_b32 v60, v178, v179 offset0:2 offset1:3
	ds_write2_b32 v61, v180, v181 offset1:1
	ds_write2_b32 v61, v182, v183 offset0:2 offset1:3
	global_load_dwordx4 v[168:171], v54, s[68:69]
	s_add_u32 s68, s68, s70
	s_addc_u32 s69, s69, 0
	global_load_dwordx4 v[172:175], v54, s[68:69]
	s_add_u32 s68, s68, s70
	s_addc_u32 s69, s69, 0
	global_load_dwordx4 v[176:179], v54, s[68:69]
	s_add_u32 s68, s68, s70
	s_addc_u32 s69, s69, 0
	global_load_dwordx4 v[180:183], v54, s[68:69]
	s_mul_i32 s6, s70, 3
	s_sub_u32 s68, s68, s6
	s_subb_u32 s69, s69, 0
	s_add_u32 s68, s68, 0x200
	s_addc_u32 s69, s69, 0
	s_waitcnt lgkmcnt(0)
	s_barrier
	ds_read2_b32 v[104:105], v66 offset1:129
	ds_read2_b32 v[106:107], v67 offset1:129
	ds_read2_b32 v[108:109], v68 offset1:129
	ds_read2_b32 v[110:111], v69 offset1:129
	ds_read2_b32 v[112:113], v70 offset1:129
	ds_read2_b32 v[114:115], v71 offset1:129
	ds_read2_b32 v[116:117], v72 offset1:129
	ds_read2_b32 v[118:119], v73 offset1:129
	s_waitcnt lgkmcnt(4)
	v_cvt_pk_bf16_f32 v120, v104, v105
	v_cvt_pk_bf16_f32 v121, v106, v107
	v_cvt_pk_bf16_f32 v122, v108, v109
	v_cvt_pk_bf16_f32 v123, v110, v111
	global_store_dwordx4 v57, v[120:123], s[72:73] sc1
	s_waitcnt lgkmcnt(0)
	v_cvt_pk_bf16_f32 v124, v112, v113
	v_cvt_pk_bf16_f32 v125, v114, v115
	v_cvt_pk_bf16_f32 v126, v116, v117
	v_cvt_pk_bf16_f32 v127, v118, v119
	global_store_dwordx4 v57, v[124:127], s[78:79] sc1
	s_add_u32 s6, s86, 1
	s_mul_i32 s6, s6, 0x2b0000
	s_add_u32 s72, s84, s6
	s_addc_u32 s73, s85, 0
	s_add_u32 s78, s72, 0x158000
	s_addc_u32 s79, s73, 0
	s_waitcnt vmcnt(20)
	ds_write2_b32 v62, v184, v185 offset1:1
	ds_write2_b32 v62, v186, v187 offset0:2 offset1:3
	ds_write2_b32 v63, v188, v189 offset1:1
	ds_write2_b32 v63, v190, v191 offset0:2 offset1:3
	ds_write2_b32 v64, v192, v193 offset1:1
	ds_write2_b32 v64, v194, v195 offset0:2 offset1:3
	ds_write2_b32 v65, v196, v197 offset1:1
	ds_write2_b32 v65, v198, v199 offset0:2 offset1:3
	global_load_dwordx4 v[184:187], v54, s[68:69]
	s_add_u32 s68, s68, s70
	s_addc_u32 s69, s69, 0
	global_load_dwordx4 v[188:191], v54, s[68:69]
	s_add_u32 s68, s68, s70
	s_addc_u32 s69, s69, 0
	global_load_dwordx4 v[192:195], v54, s[68:69]
	s_add_u32 s68, s68, s70
	s_addc_u32 s69, s69, 0
	global_load_dwordx4 v[196:199], v54, s[68:69]
	s_mul_i32 s6, s70, 3
	s_sub_u32 s68, s68, s6
	s_subb_u32 s69, s69, 0
	s_add_u32 s68, s68, 0x200
	s_addc_u32 s69, s69, 0
	s_waitcnt lgkmcnt(0)
	s_barrier
	ds_read2_b32 v[104:105], v74 offset1:129
	ds_read2_b32 v[106:107], v75 offset1:129
	ds_read2_b32 v[108:109], v76 offset1:129
	ds_read2_b32 v[110:111], v77 offset1:129
	ds_read2_b32 v[112:113], v78 offset1:129
	ds_read2_b32 v[114:115], v79 offset1:129
	ds_read2_b32 v[116:117], v80 offset1:129
	ds_read2_b32 v[118:119], v81 offset1:129
	s_waitcnt lgkmcnt(4)
	v_cvt_pk_bf16_f32 v120, v104, v105
	v_cvt_pk_bf16_f32 v121, v106, v107
	v_cvt_pk_bf16_f32 v122, v108, v109
	v_cvt_pk_bf16_f32 v123, v110, v111
	global_store_dwordx4 v57, v[120:123], s[72:73] sc1
	s_waitcnt lgkmcnt(0)
	v_cvt_pk_bf16_f32 v124, v112, v113
	v_cvt_pk_bf16_f32 v125, v114, v115
	v_cvt_pk_bf16_f32 v126, v116, v117
	v_cvt_pk_bf16_f32 v127, v118, v119
	global_store_dwordx4 v57, v[124:127], s[78:79] sc1
	s_add_u32 s6, s86, 2
	s_mul_i32 s6, s6, 0x2b0000
	s_add_u32 s72, s84, s6
	s_addc_u32 s73, s85, 0
	s_add_u32 s78, s72, 0x158000
	s_addc_u32 s79, s73, 0
	s_waitcnt vmcnt(20)
	ds_write2_b32 v58, v200, v201 offset1:1
	ds_write2_b32 v58, v202, v203 offset0:2 offset1:3
	ds_write2_b32 v59, v204, v205 offset1:1
	ds_write2_b32 v59, v206, v207 offset0:2 offset1:3
	ds_write2_b32 v60, v208, v209 offset1:1
	ds_write2_b32 v60, v210, v211 offset0:2 offset1:3
	ds_write2_b32 v61, v212, v213 offset1:1
	ds_write2_b32 v61, v214, v215 offset0:2 offset1:3
	global_load_dwordx4 v[200:203], v54, s[68:69]
	s_add_u32 s68, s68, s70
	s_addc_u32 s69, s69, 0
	global_load_dwordx4 v[204:207], v54, s[68:69]
	s_add_u32 s68, s68, s70
	s_addc_u32 s69, s69, 0
	global_load_dwordx4 v[208:211], v54, s[68:69]
	s_add_u32 s68, s68, s70
	s_addc_u32 s69, s69, 0
	global_load_dwordx4 v[212:215], v54, s[68:69]
	s_mul_i32 s6, s70, 3
	s_sub_u32 s68, s68, s6
	s_subb_u32 s69, s69, 0
	s_add_u32 s68, s68, 0x200
	s_addc_u32 s69, s69, 0
	s_waitcnt lgkmcnt(0)
	s_barrier
	ds_read2_b32 v[104:105], v66 offset1:129
	ds_read2_b32 v[106:107], v67 offset1:129
	ds_read2_b32 v[108:109], v68 offset1:129
	ds_read2_b32 v[110:111], v69 offset1:129
	ds_read2_b32 v[112:113], v70 offset1:129
	ds_read2_b32 v[114:115], v71 offset1:129
	ds_read2_b32 v[116:117], v72 offset1:129
	ds_read2_b32 v[118:119], v73 offset1:129
	s_waitcnt lgkmcnt(4)
	v_cvt_pk_bf16_f32 v120, v104, v105
	v_cvt_pk_bf16_f32 v121, v106, v107
	v_cvt_pk_bf16_f32 v122, v108, v109
	v_cvt_pk_bf16_f32 v123, v110, v111
	global_store_dwordx4 v57, v[120:123], s[72:73] sc1
	s_waitcnt lgkmcnt(0)
	v_cvt_pk_bf16_f32 v124, v112, v113
	v_cvt_pk_bf16_f32 v125, v114, v115
	v_cvt_pk_bf16_f32 v126, v116, v117
	v_cvt_pk_bf16_f32 v127, v118, v119
	global_store_dwordx4 v57, v[124:127], s[78:79] sc1
	s_add_u32 s6, s86, 3
	s_mul_i32 s6, s6, 0x2b0000
	s_add_u32 s72, s84, s6
	s_addc_u32 s73, s85, 0
	s_add_u32 s78, s72, 0x158000
	s_addc_u32 s79, s73, 0
	s_waitcnt vmcnt(20)
	ds_write2_b32 v62, v216, v217 offset1:1
	ds_write2_b32 v62, v218, v219 offset0:2 offset1:3
	ds_write2_b32 v63, v220, v221 offset1:1
	ds_write2_b32 v63, v222, v223 offset0:2 offset1:3
	ds_write2_b32 v64, v224, v225 offset1:1
	ds_write2_b32 v64, v226, v227 offset0:2 offset1:3
	ds_write2_b32 v65, v228, v229 offset1:1
	ds_write2_b32 v65, v230, v231 offset0:2 offset1:3
	global_load_dwordx4 v[216:219], v54, s[68:69]
	s_add_u32 s68, s68, s70
	s_addc_u32 s69, s69, 0
	global_load_dwordx4 v[220:223], v54, s[68:69]
	s_add_u32 s68, s68, s70
	s_addc_u32 s69, s69, 0
	global_load_dwordx4 v[224:227], v54, s[68:69]
	s_add_u32 s68, s68, s70
	s_addc_u32 s69, s69, 0
	global_load_dwordx4 v[228:231], v54, s[68:69]
	s_mul_i32 s6, s70, 3
	s_sub_u32 s68, s68, s6
	s_subb_u32 s69, s69, 0
	s_add_u32 s68, s68, 0x200
	s_addc_u32 s69, s69, 0
	s_cmp_lg_u32 s33, 0
	s_cbranch_scc1 .Ldcv1_b_st
	s_mov_b64 exec, 1
	s_waitcnt vmcnt(22)
	ds_write_b32 v84, v52
	s_mov_b64 exec, s[76:77]

; DEVI unsigned pack2(float a, float b) { f32v2 v = {a, b}; return __builtin_bit_cast(unsigned, __builtin_convertvector(v, bf16v2)); }
; DEVI void lds_barrier() { asm volatile("s_waitcnt lgkmcnt(0)" ::: "memory"); __builtin_amdgcn_s_barrier(); asm volatile("" ::: "memory"); }
; DEVI void tconv_store(const TcPre& R, u16* __restrict__ Wt, int K, int N, int t, float* lds, bool perm) {
;     ...
;   int tk = t / tnN, tn = t % tnN, k0 = tk * 64, n0 = tn * 128;
;     ...
;     float* d = lds + (tid >> 5) * 129 + (tid & 31) * 4;
;     d[0] = R.a[0]; d[1] = R.a[1]; d[2] = R.a[2]; d[3] = R.a[3];
;     d[16 * 129] = R.b[0]; d[16 * 129 + 1] = R.b[1]; d[16 * 129 + 2] = R.b[2]; d[16 * 129 + 3] = R.b[3];
;     d[32 * 129] = R.c[0]; d[32 * 129 + 1] = R.c[1]; d[32 * 129 + 2] = R.c[2]; d[32 * 129 + 3] = R.c[3];
;     d[48 * 129] = R.d[0]; d[48 * 129 + 1] = R.d[1]; d[48 * 129 + 2] = R.d[2]; d[48 * 129 + 3] = R.d[3];
;   }
;   lds_barrier();
;   int n0p = !perm ? n0 : (n0 < DFF ? (n0 / 128) * 256 : ((n0 - DFF) / 128) * 256 + 128);
; #pragma unroll
;   for (int p = 0; p < 2; ++p) {
;     int item = p * 512 + tid, n = item >> 3, kg = item & 7;
;     const float* s = lds + (kg * 8) * 129 + n;
;     uint4 o;
;     o.x = pack2(s[0], s[129]); o.y = pack2(s[2 * 129], s[3 * 129]);
;     o.z = pack2(s[4 * 129], s[5 * 129]); o.w = pack2(s[6 * 129], s[7 * 129]);
;     *(uint4*)(Wt + (size_t)(n0p + n) * K + k0 + kg * 8) = o;
.Ldcv1_last:
	s_lshr_b32 s6, s3, 5
	s_and_b32 s86, s3, 31
	s_lshl_b32 s6, s6, 7
	s_add_u32 s6, s6, 0x17400000
	s_add_u32 s84, s56, s6
	s_addc_u32 s85, s57, 0
	s_waitcnt vmcnt(0)
	s_add_u32 s6, s86, 0
	s_mul_i32 s6, s6, 0x2b0000
	s_add_u32 s72, s84, s6
	s_addc_u32 s73, s85, 0
	s_add_u32 s78, s72, 0x158000
	s_addc_u32 s79, s73, 0
	ds_write2_b32 v58, v168, v169 offset1:1
	ds_write2_b32 v58, v170, v171 offset0:2 offset1:3
	ds_write2_b32 v59, v172, v173 offset1:1
	ds_write2_b32 v59, v174, v175 offset0:2 offset1:3
	ds_write2_b32 v60, v176, v177 offset1:1
	ds_write2_b32 v60, v178, v179 offset0:2 offset1:3
	ds_write2_b32 v61, v180, v181 offset1:1
	ds_write2_b32 v61, v182, v183 offset0:2 offset1:3
	s_waitcnt lgkmcnt(0)
	s_barrier
	ds_read2_b32 v[104:105], v66 offset1:129
	ds_read2_b32 v[106:107], v67 offset1:129
	ds_read2_b32 v[108:109], v68 offset1:129
	ds_read2_b32 v[110:111], v69 offset1:129
	ds_read2_b32 v[112:113], v70 offset1:129
	ds_read2_b32 v[114:115], v71 offset1:129
	ds_read2_b32 v[116:117], v72 offset1:129
	ds_read2_b32 v[118:119], v73 offset1:129
	s_waitcnt lgkmcnt(4)
	v_cvt_pk_bf16_f32 v120, v104, v105
	v_cvt_pk_bf16_f32 v121, v106, v107
	v_cvt_pk_bf16_f32 v122, v108, v109
	v_cvt_pk_bf16_f32 v123, v110, v111
	global_store_dwordx4 v57, v[120:123], s[72:73] sc1
	s_waitcnt lgkmcnt(0)
	v_cvt_pk_bf16_f32 v124, v112, v113
	v_cvt_pk_bf16_f32 v125, v114, v115
	v_cvt_pk_bf16_f32 v126, v116, v117
	v_cvt_pk_bf16_f32 v127, v118, v119
	global_store_dwordx4 v57, v[124:127], s[78:79] sc1
	s_add_u32 s6, s86, 1
	s_mul_i32 s6, s6, 0x2b0000
	s_add_u32 s72, s84, s6
	s_addc_u32 s73, s85, 0
	s_add_u32 s78, s72, 0x158000
	s_addc_u32 s79, s73, 0
	ds_write2_b32 v62, v184, v185 offset1:1
	ds_write2_b32 v62, v186, v187 offset0:2 offset1:3
	ds_write2_b32 v63, v188, v189 offset1:1
	ds_write2_b32 v63, v190, v191 offset0:2 offset1:3
	ds_write2_b32 v64, v192, v193 offset1:1
	ds_write2_b32 v64, v194, v195 offset0:2 offset1:3
	ds_write2_b32 v65, v196, v197 offset1:1
	ds_write2_b32 v65, v198, v199 offset0:2 offset1:3
	s_waitcnt lgkmcnt(0)
	s_barrier
	ds_read2_b32 v[104:105], v74 offset1:129
	ds_read2_b32 v[106:107], v75 offset1:129
	ds_read2_b32 v[108:109], v76 offset1:129
	ds_read2_b32 v[110:111], v77 offset1:129
	ds_read2_b32 v[112:113], v78 offset1:129
	ds_read2_b32 v[114:115], v79 offset1:129
	ds_read2_b32 v[116:117], v80 offset1:129
	ds_read2_b32 v[118:119], v81 offset1:129
	s_waitcnt lgkmcnt(4)
	v_cvt_pk_bf16_f32 v120, v104, v105
	v_cvt_pk_bf16_f32 v121, v106, v107
	v_cvt_pk_bf16_f32 v122, v108, v109
	v_cvt_pk_bf16_f32 v123, v110, v111
	global_store_dwordx4 v57, v[120:123], s[72:73] sc1
	s_waitcnt lgkmcnt(0)
	v_cvt_pk_bf16_f32 v124, v112, v113
	v_cvt_pk_bf16_f32 v125, v114, v115
	v_cvt_pk_bf16_f32 v126, v116, v117
	v_cvt_pk_bf16_f32 v127, v118, v119
	global_store_dwordx4 v57, v[124:127], s[78:79] sc1
	s_add_u32 s6, s86, 2
	s_mul_i32 s6, s6, 0x2b0000
	s_add_u32 s72, s84, s6
	s_addc_u32 s73, s85, 0
	s_add_u32 s78, s72, 0x158000
	s_addc_u32 s79, s73, 0
	ds_write2_b32 v58, v200, v201 offset1:1
	ds_write2_b32 v58, v202, v203 offset0:2 offset1:3
	ds_write2_b32 v59, v204, v205 offset1:1
	ds_write2_b32 v59, v206, v207 offset0:2 offset1:3
	ds_write2_b32 v60, v208, v209 offset1:1
	ds_write2_b32 v60, v210, v211 offset0:2 offset1:3
	ds_write2_b32 v61, v212, v213 offset1:1
	ds_write2_b32 v61, v214, v215 offset0:2 offset1:3
	s_waitcnt lgkmcnt(0)
	s_barrier
	ds_read2_b32 v[104:105], v66 offset1:129
	ds_read2_b32 v[106:107], v67 offset1:129
	ds_read2_b32 v[108:109], v68 offset1:129
	ds_read2_b32 v[110:111], v69 offset1:129
	ds_read2_b32 v[112:113], v70 offset1:129
	ds_read2_b32 v[114:115], v71 offset1:129
	ds_read2_b32 v[116:117], v72 offset1:129
	ds_read2_b32 v[118:119], v73 offset1:129
	s_waitcnt lgkmcnt(4)
	v_cvt_pk_bf16_f32 v120, v104, v105
	v_cvt_pk_bf16_f32 v121, v106, v107
	v_cvt_pk_bf16_f32 v122, v108, v109
	v_cvt_pk_bf16_f32 v123, v110, v111
	global_store_dwordx4 v57, v[120:123], s[72:73] sc1
	s_waitcnt lgkmcnt(0)
	v_cvt_pk_bf16_f32 v124, v112, v113
	v_cvt_pk_bf16_f32 v125, v114, v115
	v_cvt_pk_bf16_f32 v126, v116, v117
	v_cvt_pk_bf16_f32 v127, v118, v119
	global_store_dwordx4 v57, v[124:127], s[78:79] sc1
	s_add_u32 s6, s86, 3
	s_mul_i32 s6, s6, 0x2b0000
	s_add_u32 s72, s84, s6
	s_addc_u32 s73, s85, 0
	s_add_u32 s78, s72, 0x158000
	s_addc_u32 s79, s73, 0
	ds_write2_b32 v62, v216, v217 offset1:1
	ds_write2_b32 v62, v218, v219 offset0:2 offset1:3
	ds_write2_b32 v63, v220, v221 offset1:1
	ds_write2_b32 v63, v222, v223 offset0:2 offset1:3
	ds_write2_b32 v64, v224, v225 offset1:1
	ds_write2_b32 v64, v226, v227 offset0:2 offset1:3
	ds_write2_b32 v65, v228, v229 offset1:1
	ds_write2_b32 v65, v230, v231 offset0:2 offset1:3
	s_waitcnt lgkmcnt(0)
	s_barrier
	ds_read2_b32 v[104:105], v74 offset1:129
	ds_read2_b32 v[106:107], v75 offset1:129
	ds_read2_b32 v[108:109], v76 offset1:129
	ds_read2_b32 v[110:111], v77 offset1:129
	ds_read2_b32 v[112:113], v78 offset1:129
	ds_read2_b32 v[114:115], v79 offset1:129
	ds_read2_b32 v[116:117], v80 offset1:129
	ds_read2_b32 v[118:119], v81 offset1:129
	s_waitcnt lgkmcnt(4)
	v_cvt_pk_bf16_f32 v120, v104, v105
	v_cvt_pk_bf16_f32 v121, v106, v107
	v_cvt_pk_bf16_f32 v122, v108, v109
	v_cvt_pk_bf16_f32 v123, v110, v111
	global_store_dwordx4 v57, v[120:123], s[72:73] sc1
	s_waitcnt lgkmcnt(0)
	v_cvt_pk_bf16_f32 v124, v112, v113
	v_cvt_pk_bf16_f32 v125, v114, v115
	v_cvt_pk_bf16_f32 v126, v116, v117
	v_cvt_pk_bf16_f32 v127, v118, v119
	global_store_dwordx4 v57, v[124:127], s[78:79] sc1

; template <int MODE> ...
;     ...
; #pragma unroll 8
;           for (int it = 0; it < 16; ++it) {
;             int item = it * 512 + t2, row = item >> 6, q = item & 63;
;             float4 v = *(const float4*)(ls + row * 1024 + ((q ^ (((row >> 2) & 3) << 3)) << 4));
;             long g = gb + (long)row * ldc + q * 4;
;             float4 r = *(const float4*)(resid + g);
;             if (MODE == 4) {
;               float2 st = *(const float2*)(aux0 + 2 * (long)(brow + ai * HALF + row));
;               float4 gg = *(const float4*)(aux1 + bcol + q * 4), bb = *(const float4*)(aux2 + bcol + q * 4);
;               r.x = (r.x - st.x) * st.y * gg.x + bb.x; r.y = (r.y - st.x) * st.y * gg.y + bb.y;
;               r.z = (r.z - st.x) * st.y * gg.z + bb.z; r.w = (r.w - st.x) * st.y * gg.w + bb.w;
.LBB0_852:
	v_add_u32_e32 v79, s45, v138
	v_ashrrev_i32_e32 v80, 6, v79
	v_add_u32_e32 v82, 0x200, v79
	v_add_u32_e32 v83, 0x400, v79
	v_add_u32_e32 v87, 0x600, v79
	v_add_u32_e32 v89, 0x800, v79
	v_add_u32_e32 v91, 0xa00, v79
	v_add_u32_e32 v93, 0xc00, v79
	v_add_u32_e32 v79, 0xe00, v79
	v_ashrrev_i32_e32 v81, 31, v80
	v_add_u32_e32 v88, s48, v80
	v_ashrrev_i32_e32 v90, 6, v83
	v_ashrrev_i32_e32 v96, 6, v93
	v_ashrrev_i32_e32 v110, 6, v79
	v_lshl_or_b32 v97, v80, 10, v78
	v_ashrrev_i32_e32 v100, 6, v82
	v_lshrrev_b32_e32 v98, 5, v82
	v_ashrrev_i32_e32 v102, 6, v87
	v_lshrrev_b32_e32 v87, 5, v87
	v_ashrrev_i32_e32 v92, 6, v89
	v_ashrrev_i32_e32 v108, 6, v91
	v_lshrrev_b32_e32 v99, 5, v91
	v_lshrrev_b32_e32 v79, 5, v79
	v_lshl_add_u64 v[94:95], v[80:81], 0, s[48:49]
	v_ashrrev_i32_e32 v89, 31, v88
	v_lshl_or_b32 v125, v90, 10, v78
	v_ashrrev_i32_e32 v91, 31, v90
	v_add_u32_e32 v144, s48, v96
	v_add_u32_e32 v146, s48, v110
	ds_read_b128 v[80:83], v97
	v_bitop3_b32 v98, v98, v139, 24 bitop3:0x6c
	v_ashrrev_i32_e32 v101, 31, v100
	v_add_u32_e32 v116, s48, v100
	v_add_u32_e32 v118, s48, v90
	v_bitop3_b32 v87, v87, v139, 24 bitop3:0x6c
	v_ashrrev_i32_e32 v103, 31, v102
	v_add_u32_e32 v124, s48, v102
	v_lshl_or_b32 v128, v92, 10, v78
	v_ashrrev_i32_e32 v93, 31, v92
	v_add_u32_e32 v126, s48, v92
	v_bitop3_b32 v99, v99, v139, 24 bitop3:0x6c
	v_ashrrev_i32_e32 v109, 31, v108
	v_bitop3_b32 v79, v79, v139, 24 bitop3:0x6c
	v_ashrrev_i32_e32 v111, 31, v110
	v_lshlrev_b64 v[148:149], 12, v[94:95]
	v_lshl_add_u64 v[170:171], v[88:89], 3, s[12:13]
	v_lshl_add_u64 v[174:175], v[90:91], 0, s[48:49]
	ds_read_b128 v[88:91], v125
	v_ashrrev_i32_e32 v97, 31, v96
	v_ashrrev_i32_e32 v145, 31, v144
	v_ashrrev_i32_e32 v147, 31, v146
	v_add_u32_e32 v142, s48, v108
	v_lshl_or_b32 v141, v96, 10, v78
	v_lshlrev_b32_e32 v169, 4, v98
	v_lshl_add_u64 v[172:173], v[100:101], 0, s[48:49]
	v_ashrrev_i32_e32 v117, 31, v116
	v_ashrrev_i32_e32 v119, 31, v118
	v_lshlrev_b32_e32 v87, 4, v87
	v_lshl_add_u64 v[176:177], v[102:103], 0, s[48:49]
	v_ashrrev_i32_e32 v125, 31, v124
	v_lshl_add_u64 v[178:179], v[92:93], 0, s[48:49]
	v_ashrrev_i32_e32 v127, 31, v126
	ds_read_b128 v[92:95], v128
	v_lshlrev_b32_e32 v128, 4, v99
	v_lshl_add_u64 v[180:181], v[108:109], 0, s[48:49]
	v_lshl_add_u64 v[182:183], v[96:97], 0, s[48:49]
	v_lshlrev_b32_e32 v79, 4, v79
	v_lshl_add_u64 v[184:185], v[110:111], 0, s[48:49]
	v_lshl_add_u64 v[148:149], v[148:149], 0, v[72:73]
	v_lshl_add_u64 v[144:145], v[144:145], 3, s[12:13]
	v_lshl_add_u64 v[146:147], v[146:147], 3, s[12:13]
	v_ashrrev_i32_e32 v143, 31, v142
	ds_read_b128 v[96:99], v141
	global_load_dwordx2 v[194:195], v[170:171], off
	global_load_dwordx2 v[208:209], v[144:145], off
	global_load_dwordx2 v[210:211], v[146:147], off
	v_lshl_or_b32 v141, v100, 10, v169
	v_lshlrev_b64 v[100:101], 12, v[172:173]
	v_lshl_add_u64 v[116:117], v[116:117], 3, s[12:13]
	v_lshlrev_b64 v[170:171], 12, v[174:175]
	v_lshl_add_u64 v[118:119], v[118:119], 3, s[12:13]
	v_lshl_or_b32 v87, v102, 10, v87
	v_lshlrev_b64 v[102:103], 12, v[176:177]
	v_lshl_add_u64 v[124:125], v[124:125], 3, s[12:13]
	v_lshlrev_b64 v[172:173], 12, v[178:179]
	v_lshl_add_u64 v[126:127], v[126:127], 3, s[12:13]
	v_lshl_or_b32 v128, v108, 10, v128
	v_lshlrev_b64 v[108:109], 12, v[180:181]
	v_lshlrev_b64 v[174:175], 12, v[182:183]
	v_lshl_or_b32 v79, v110, 10, v79
	v_lshlrev_b64 v[110:111], 12, v[184:185]
	v_lshlrev_b64 v[196:197], 2, v[148:149]
	v_lshl_add_u64 v[142:143], v[142:143], 3, s[12:13]
	v_lshl_add_u64 v[100:101], v[100:101], 0, v[72:73]
	global_load_dwordx2 v[198:199], v[116:117], off
	global_load_dwordx2 v[200:201], v[118:119], off
	global_load_dwordx2 v[202:203], v[124:125], off
	global_load_dwordx2 v[204:205], v[126:127], off
	v_lshl_add_u64 v[116:117], v[170:171], 0, v[72:73]
	v_lshl_add_u64 v[102:103], v[102:103], 0, v[72:73]
	v_lshl_add_u64 v[118:119], v[172:173], 0, v[72:73]
	v_lshl_add_u64 v[108:109], v[108:109], 0, v[72:73]
	v_lshl_add_u64 v[124:125], v[174:175], 0, v[72:73]
	v_lshl_add_u64 v[110:111], v[110:111], 0, v[72:73]
	v_lshl_add_u64 v[126:127], s[10:11], 0, v[196:197]
	global_load_dwordx2 v[206:207], v[142:143], off
	v_lshlrev_b64 v[212:213], 2, v[100:101]
	v_lshlrev_b64 v[214:215], 2, v[116:117]
	v_lshlrev_b64 v[216:217], 2, v[102:103]
	v_lshlrev_b64 v[218:219], 2, v[118:119]
	v_lshlrev_b64 v[220:221], 2, v[108:109]
	v_lshlrev_b64 v[222:223], 2, v[124:125]
	v_lshlrev_b64 v[224:225], 2, v[110:111]
	global_load_dwordx4 v[100:103], v[126:127], off
	v_lshl_add_u64 v[108:109], s[10:11], 0, v[212:213]
	v_lshl_add_u64 v[116:117], s[10:11], 0, v[214:215]
	v_lshl_add_u64 v[124:125], s[10:11], 0, v[216:217]
	v_lshl_add_u64 v[142:143], s[10:11], 0, v[218:219]
	v_lshl_add_u64 v[146:147], s[10:11], 0, v[220:221]
	v_lshl_add_u64 v[170:171], s[10:11], 0, v[222:223]
	v_lshl_add_u64 v[174:175], s[10:11], 0, v[224:225]
	global_load_dwordx4 v[108:111], v[108:109], off
	s_nop 0
	global_load_dwordx4 v[116:119], v[116:117], off
	s_nop 0
	global_load_dwordx4 v[124:127], v[124:125], off
	s_nop 0
	global_load_dwordx4 v[142:145], v[142:143], off
	s_nop 0
	global_load_dwordx4 v[146:149], v[146:147], off
	s_nop 0
	global_load_dwordx4 v[170:173], v[170:171], off
	s_nop 0
	global_load_dwordx4 v[174:177], v[174:175], off
	ds_read_b128 v[178:181], v141
	ds_read_b128 v[182:185], v87
	ds_read_b128 v[186:189], v128
	ds_read_b128 v[190:193], v79
	s_addk_i32 s45, 0x1000
	v_lshl_add_u64 v[196:197], s[54:55], 0, v[196:197]
	s_cmpk_eq_i32 s45, 0x2000
	v_lshl_add_u64 v[212:213], s[54:55], 0, v[212:213]
	v_lshl_add_u64 v[214:215], s[54:55], 0, v[214:215]
	v_lshl_add_u64 v[216:217], s[54:55], 0, v[216:217]
	v_lshl_add_u64 v[218:219], s[54:55], 0, v[218:219]
	v_lshl_add_u64 v[220:221], s[54:55], 0, v[220:221]
	v_lshl_add_u64 v[222:223], s[54:55], 0, v[222:223]
	v_lshl_add_u64 v[224:225], s[54:55], 0, v[224:225]
	s_waitcnt vmcnt(0)
; DEVI void lds_barrier() { asm volatile("s_waitcnt lgkmcnt(0)" ::: "memory"); __builtin_amdgcn_s_barrier(); asm volatile("" ::: "memory"); }
; template <int MODE> ...
;     ...
;         for (int ai = 0; ai < 2; ++ai) {
;           if (ai) lds_barrier();
; #pragma unroll
;           for (int bj = 0; bj < 2; ++bj)
; #pragma unroll
;             for (int m = 0; m < 4; ++m)
; #pragma unroll
;               for (int n = 0; n < 2; ++n)
; #pragma unroll
;                 for (int j = 0; j < 4; ++j)
;                   *(float*)(ls + wbase + ((m * 16 + j) * 1024 + (bj * 32 + n * 4) * 16)) = acc[ai][bj][m][n][j];
;     ...
;             if (MODE == 4) {
;               float2 st = *(const float2*)(aux0 + 2 * (long)(brow + ai * HALF + row));
;               float4 gg = *(const float4*)(aux1 + bcol + q * 4), bb = *(const float4*)(aux2 + bcol + q * 4);
;               r.x = (r.x - st.x) * st.y * gg.x + bb.x; r.y = (r.y - st.x) * st.y * gg.y + bb.y;
;               r.z = (r.z - st.x) * st.y * gg.z + bb.z; r.w = (r.w - st.x) * st.y * gg.w + bb.w;
;             }
;             float4 o; o.x = ALPHA * r.x + v.x; o.y = ALPHA * r.y + v.y; o.z = ALPHA * r.z + v.z; o.w = ALPHA * r.w + v.w;
;             *(float4*)(outf + g) = o;
	v_pk_add_f32 v[100:101], v[100:101], v[194:195] op_sel_hi:[1,0] neg_lo:[0,1] neg_hi:[0,1]
	v_pk_add_f32 v[102:103], v[102:103], v[194:195] op_sel_hi:[1,0] neg_lo:[0,1] neg_hi:[0,1]
	v_pk_mul_f32 v[100:101], v[100:101], v[194:195] op_sel:[0,1]
	v_pk_mul_f32 v[102:103], v[102:103], v[194:195] op_sel:[0,1]
	v_pk_add_f32 v[108:109], v[108:109], v[198:199] op_sel_hi:[1,0] neg_lo:[0,1] neg_hi:[0,1]
	v_pk_add_f32 v[110:111], v[110:111], v[198:199] op_sel_hi:[1,0] neg_lo:[0,1] neg_hi:[0,1]
	v_pk_add_f32 v[116:117], v[116:117], v[200:201] op_sel_hi:[1,0] neg_lo:[0,1] neg_hi:[0,1]
	v_pk_add_f32 v[118:119], v[118:119], v[200:201] op_sel_hi:[1,0] neg_lo:[0,1] neg_hi:[0,1]
	v_pk_add_f32 v[124:125], v[124:125], v[202:203] op_sel_hi:[1,0] neg_lo:[0,1] neg_hi:[0,1]
	v_pk_add_f32 v[126:127], v[126:127], v[202:203] op_sel_hi:[1,0] neg_lo:[0,1] neg_hi:[0,1]
	v_pk_add_f32 v[142:143], v[142:143], v[204:205] op_sel_hi:[1,0] neg_lo:[0,1] neg_hi:[0,1]
	v_pk_add_f32 v[144:145], v[144:145], v[204:205] op_sel_hi:[1,0] neg_lo:[0,1] neg_hi:[0,1]
	v_pk_add_f32 v[146:147], v[146:147], v[206:207] op_sel_hi:[1,0] neg_lo:[0,1] neg_hi:[0,1]
	v_pk_add_f32 v[148:149], v[148:149], v[206:207] op_sel_hi:[1,0] neg_lo:[0,1] neg_hi:[0,1]
	v_pk_add_f32 v[170:171], v[170:171], v[208:209] op_sel_hi:[1,0] neg_lo:[0,1] neg_hi:[0,1]
	v_pk_add_f32 v[172:173], v[172:173], v[208:209] op_sel_hi:[1,0] neg_lo:[0,1] neg_hi:[0,1]
	v_pk_add_f32 v[174:175], v[174:175], v[210:211] op_sel_hi:[1,0] neg_lo:[0,1] neg_hi:[0,1]
	v_pk_add_f32 v[176:177], v[176:177], v[210:211] op_sel_hi:[1,0] neg_lo:[0,1] neg_hi:[0,1]
	v_pk_fma_f32 v[100:101], v[64:65], v[100:101], v[68:69]
	v_pk_fma_f32 v[102:103], v[66:67], v[102:103], v[70:71]
	v_pk_mul_f32 v[108:109], v[108:109], v[198:199] op_sel:[0,1]
	v_pk_mul_f32 v[110:111], v[110:111], v[198:199] op_sel:[0,1]
	v_pk_mul_f32 v[116:117], v[116:117], v[200:201] op_sel:[0,1]
	v_pk_mul_f32 v[118:119], v[118:119], v[200:201] op_sel:[0,1]
	v_pk_mul_f32 v[124:125], v[124:125], v[202:203] op_sel:[0,1]
	v_pk_mul_f32 v[126:127], v[126:127], v[202:203] op_sel:[0,1]
	v_pk_mul_f32 v[142:143], v[142:143], v[204:205] op_sel:[0,1]
	v_pk_mul_f32 v[144:145], v[144:145], v[204:205] op_sel:[0,1]
	v_pk_mul_f32 v[146:147], v[146:147], v[206:207] op_sel:[0,1]
	v_pk_mul_f32 v[148:149], v[148:149], v[206:207] op_sel:[0,1]
	v_pk_mul_f32 v[170:171], v[170:171], v[208:209] op_sel:[0,1]
	v_pk_mul_f32 v[172:173], v[172:173], v[208:209] op_sel:[0,1]
	v_pk_mul_f32 v[174:175], v[174:175], v[210:211] op_sel:[0,1]
	v_pk_mul_f32 v[176:177], v[176:177], v[210:211] op_sel:[0,1]
	s_waitcnt lgkmcnt(7)
	v_pk_fma_f32 v[80:81], v[100:101], s[44:45], v[80:81] op_sel_hi:[1,0,1]
	v_pk_fma_f32 v[82:83], v[102:103], s[44:45], v[82:83] op_sel_hi:[1,0,1]
	v_pk_fma_f32 v[100:101], v[64:65], v[108:109], v[68:69]
	v_pk_fma_f32 v[102:103], v[66:67], v[110:111], v[70:71]
	v_pk_fma_f32 v[108:109], v[64:65], v[116:117], v[68:69]
	v_pk_fma_f32 v[110:111], v[66:67], v[118:119], v[70:71]
	v_pk_fma_f32 v[116:117], v[64:65], v[124:125], v[68:69]
	v_pk_fma_f32 v[118:119], v[66:67], v[126:127], v[70:71]
	v_pk_fma_f32 v[124:125], v[64:65], v[142:143], v[68:69]
	v_pk_fma_f32 v[126:127], v[66:67], v[144:145], v[70:71]
	v_pk_fma_f32 v[142:143], v[64:65], v[146:147], v[68:69]
	v_pk_fma_f32 v[144:145], v[66:67], v[148:149], v[70:71]
	v_pk_fma_f32 v[146:147], v[64:65], v[170:171], v[68:69]
	v_pk_fma_f32 v[148:149], v[66:67], v[172:173], v[70:71]
	v_pk_fma_f32 v[170:171], v[64:65], v[174:175], v[68:69]
	v_pk_fma_f32 v[172:173], v[66:67], v[176:177], v[70:71]
	global_store_dwordx4 v[196:197], v[80:83], off sc1
	s_waitcnt lgkmcnt(6)
	v_pk_fma_f32 v[88:89], v[108:109], s[44:45], v[88:89] op_sel_hi:[1,0,1]
	v_pk_fma_f32 v[90:91], v[110:111], s[44:45], v[90:91] op_sel_hi:[1,0,1]
	s_waitcnt lgkmcnt(3)
	v_pk_fma_f32 v[80:81], v[100:101], s[44:45], v[178:179] op_sel_hi:[1,0,1]
	v_pk_fma_f32 v[82:83], v[102:103], s[44:45], v[180:181] op_sel_hi:[1,0,1]
	s_waitcnt lgkmcnt(2)
	v_pk_fma_f32 v[100:101], v[116:117], s[44:45], v[182:183] op_sel_hi:[1,0,1]
	v_pk_fma_f32 v[102:103], v[118:119], s[44:45], v[184:185] op_sel_hi:[1,0,1]
	v_pk_fma_f32 v[92:93], v[124:125], s[44:45], v[92:93] op_sel_hi:[1,0,1]
	v_pk_fma_f32 v[94:95], v[126:127], s[44:45], v[94:95] op_sel_hi:[1,0,1]
	s_waitcnt lgkmcnt(1)
	v_pk_fma_f32 v[108:109], v[142:143], s[44:45], v[186:187] op_sel_hi:[1,0,1]
	v_pk_fma_f32 v[110:111], v[144:145], s[44:45], v[188:189] op_sel_hi:[1,0,1]
	v_pk_fma_f32 v[96:97], v[146:147], s[44:45], v[96:97] op_sel_hi:[1,0,1]
	v_pk_fma_f32 v[98:99], v[148:149], s[44:45], v[98:99] op_sel_hi:[1,0,1]
	s_waitcnt lgkmcnt(0)
	v_pk_fma_f32 v[116:117], v[170:171], s[44:45], v[190:191] op_sel_hi:[1,0,1]
	v_pk_fma_f32 v[118:119], v[172:173], s[44:45], v[192:193] op_sel_hi:[1,0,1]
	global_store_dwordx4 v[212:213], v[80:83], off sc1
	global_store_dwordx4 v[214:215], v[88:91], off sc1
	global_store_dwordx4 v[216:217], v[100:103], off sc1
	global_store_dwordx4 v[218:219], v[92:95], off sc1
	global_store_dwordx4 v[220:221], v[108:111], off sc1
	global_store_dwordx4 v[222:223], v[96:99], off sc1
	global_store_dwordx4 v[224:225], v[116:119], off sc1
	s_cbranch_scc0 .LBB0_852
	s_waitcnt lgkmcnt(0)
	s_barrier
	ds_write2_b32 v140, v0, v32 offset1:16
	ds_write2_b32 v120, v1, v33 offset1:16
	ds_write2_b32 v121, v2, v34 offset1:16
	ds_write2_b32 v122, v3, v35 offset1:16
	ds_write2_b32 v123, v4, v36 offset1:16
	ds_write2_b32 v112, v5, v37 offset1:16
	ds_write2_b32 v113, v6, v38 offset1:16
	ds_write2_b32 v114, v7, v39 offset1:16
	ds_write2_b32 v115, v8, v40 offset1:16
	ds_write2_b32 v104, v9, v41 offset1:16
	ds_write2_b32 v105, v10, v42 offset1:16
	ds_write2_b32 v106, v11, v43 offset1:16
	ds_write2_b32 v107, v12, v44 offset1:16
	ds_write2_b32 v84, v13, v45 offset1:16
	ds_write2_b32 v85, v14, v46 offset1:16
	ds_write2_b32 v86, v15, v47 offset1:16
	ds_write2_b32 v140, v16, v48 offset0:128 offset1:144
	ds_write2_b32 v120, v17, v49 offset0:128 offset1:144
	ds_write2_b32 v121, v18, v50 offset0:128 offset1:144
	ds_write2_b32 v122, v19, v51 offset0:128 offset1:144
	ds_write2_b32 v123, v20, v52 offset0:128 offset1:144
	ds_write2_b32 v112, v21, v53 offset0:128 offset1:144
	ds_write2_b32 v113, v22, v54 offset0:128 offset1:144
	ds_write2_b32 v114, v23, v55 offset0:128 offset1:144
	ds_write2_b32 v115, v24, v56 offset0:128 offset1:144
	ds_write2_b32 v104, v25, v57 offset0:128 offset1:144
	ds_write2_b32 v105, v26, v58 offset0:128 offset1:144
	ds_write2_b32 v106, v27, v59 offset0:128 offset1:144
	ds_write2_b32 v107, v28, v60 offset0:128 offset1:144
	ds_write2_b32 v84, v29, v61 offset0:128 offset1:144
	ds_write2_b32 v85, v30, v62 offset0:128 offset1:144
	ds_write2_b32 v86, v31, v63 offset0:128 offset1:144
	s_waitcnt lgkmcnt(0)
	s_barrier
	global_load_dwordx4 v[0:3], v[76:77], off
	global_load_dwordx4 v[4:7], v[74:75], off
	s_mov_b32 s45, 0
; template <int MODE> ...
;     ...
; #pragma unroll 8
;           for (int it = 0; it < 16; ++it) {
;             int item = it * 512 + t2, row = item >> 6, q = item & 63;
;             float4 v = *(const float4*)(ls + row * 1024 + ((q ^ (((row >> 2) & 3) << 3)) << 4));
;             long g = gb + (long)row * ldc + q * 4;
;             float4 r = *(const float4*)(resid + g);
;             if (MODE == 4) {
;               float2 st = *(const float2*)(aux0 + 2 * (long)(brow + ai * HALF + row));
;               float4 gg = *(const float4*)(aux1 + bcol + q * 4), bb = *(const float4*)(aux2 + bcol + q * 4);
;               r.x = (r.x - st.x) * st.y * gg.x + bb.x; r.y = (r.y - st.x) * st.y * gg.y + bb.y;
;               r.z = (r.z - st.x) * st.y * gg.z + bb.z; r.w = (r.w - st.x) * st.y * gg.w + bb.w;
.LBB0_854:
	v_add_u32_e32 v9, s45, v138
	v_ashrrev_i32_e32 v8, 6, v9
	v_add_u32_e32 v11, 0x400, v9
	v_add_u32_e32 v10, 0x200, v9
	v_add_u32_e32 v13, 0x600, v9
	v_add_u32_e32 v15, 0x800, v9
	v_add_u32_e32 v17, 0xa00, v9
	v_add_u32_e32 v18, 0xc00, v9
	v_add_u32_e32 v19, 0xe00, v9
	v_add_u32_e32 v12, s46, v8
	v_ashrrev_i32_e32 v14, 6, v11
	v_lshl_or_b32 v21, v8, 10, v78
	v_ashrrev_i32_e32 v9, 31, v8
	v_lshrrev_b32_e32 v22, 5, v10
	v_ashrrev_i32_e32 v26, 6, v13
	v_lshrrev_b32_e32 v23, 5, v13
	v_ashrrev_i32_e32 v16, 6, v15
	v_lshrrev_b32_e32 v29, 5, v17
	v_ashrrev_i32_e32 v20, 6, v18
	v_ashrrev_i32_e32 v30, 6, v19
	v_ashrrev_i32_e32 v13, 31, v12
	v_lshl_or_b32 v37, v14, 10, v78
	v_ashrrev_i32_e32 v15, 31, v14
	v_ashrrev_i32_e32 v24, 6, v10
	v_ashrrev_i32_e32 v28, 6, v17
	v_lshrrev_b32_e32 v31, 5, v19
	v_lshl_add_u64 v[18:19], v[8:9], 0, s[46:47]
	ds_read_b128 v[8:11], v21
	v_bitop3_b32 v22, v22, v139, 24 bitop3:0x6c
	v_add_u32_e32 v34, s46, v14
	v_bitop3_b32 v23, v23, v139, 24 bitop3:0x6c
	v_lshl_or_b32 v41, v16, 10, v78
	v_ashrrev_i32_e32 v17, 31, v16
	v_bitop3_b32 v43, v29, v139, 24 bitop3:0x6c
	v_lshl_or_b32 v45, v20, 10, v78
	v_add_u32_e32 v42, s46, v20
	v_add_u32_e32 v44, s46, v30
	v_lshl_add_u64 v[48:49], v[12:13], 3, s[12:13]
	v_lshl_add_u64 v[52:53], v[14:15], 0, s[46:47]
	ds_read_b128 v[12:15], v37
	v_ashrrev_i32_e32 v21, 31, v20
	v_ashrrev_i32_e32 v25, 31, v24
	v_add_u32_e32 v32, s46, v24
	v_ashrrev_i32_e32 v27, 31, v26
	v_add_u32_e32 v36, s46, v26
	v_add_u32_e32 v38, s46, v16
	v_ashrrev_i32_e32 v29, 31, v28
	v_bitop3_b32 v62, v31, v139, 24 bitop3:0x6c
	v_ashrrev_i32_e32 v31, 31, v30
	v_lshlrev_b64 v[46:47], 12, v[18:19]
	v_lshlrev_b32_e32 v64, 4, v22
	v_lshlrev_b32_e32 v65, 4, v23
	v_lshl_add_u64 v[56:57], v[16:17], 0, s[46:47]
	ds_read_b128 v[16:19], v41
	v_lshlrev_b32_e32 v66, 4, v43
	v_lshl_add_u64 v[60:61], v[20:21], 0, s[46:47]
	v_ashrrev_i32_e32 v43, 31, v42
	ds_read_b128 v[20:23], v45
	v_ashrrev_i32_e32 v45, 31, v44
	v_add_u32_e32 v40, s46, v28
	v_lshl_add_u64 v[50:51], v[24:25], 0, s[46:47]
	v_ashrrev_i32_e32 v33, 31, v32
	v_ashrrev_i32_e32 v35, 31, v34
	v_lshl_add_u64 v[54:55], v[26:27], 0, s[46:47]
	v_ashrrev_i32_e32 v37, 31, v36
	v_ashrrev_i32_e32 v39, 31, v38
	v_lshl_add_u64 v[58:59], v[28:29], 0, s[46:47]
	v_lshlrev_b32_e32 v67, 4, v62
	v_lshl_add_u64 v[62:63], v[30:31], 0, s[46:47]
	v_lshl_add_u64 v[46:47], v[46:47], 0, v[72:73]
	v_lshl_add_u64 v[42:43], v[42:43], 3, s[12:13]
	v_lshl_add_u64 v[44:45], v[44:45], 3, s[12:13]
	v_ashrrev_i32_e32 v41, 31, v40
	global_load_dwordx2 v[74:75], v[48:49], off
	global_load_dwordx2 v[90:91], v[42:43], off
	global_load_dwordx2 v[92:93], v[44:45], off
	v_lshl_or_b32 v64, v24, 10, v64
	v_lshlrev_b64 v[24:25], 12, v[50:51]
	v_lshl_add_u64 v[32:33], v[32:33], 3, s[12:13]
	v_lshlrev_b64 v[48:49], 12, v[52:53]
	v_lshl_add_u64 v[34:35], v[34:35], 3, s[12:13]
	v_lshl_or_b32 v65, v26, 10, v65
	v_lshlrev_b64 v[26:27], 12, v[54:55]
	v_lshl_add_u64 v[36:37], v[36:37], 3, s[12:13]
	v_lshlrev_b64 v[50:51], 12, v[56:57]
	v_lshl_add_u64 v[38:39], v[38:39], 3, s[12:13]
	v_lshl_or_b32 v66, v28, 10, v66
	v_lshlrev_b64 v[28:29], 12, v[58:59]
	v_lshlrev_b64 v[52:53], 12, v[60:61]
	v_lshl_or_b32 v68, v30, 10, v67
	v_lshlrev_b64 v[30:31], 12, v[62:63]
	v_lshlrev_b64 v[76:77], 2, v[46:47]
	v_lshl_add_u64 v[40:41], v[40:41], 3, s[12:13]
	v_lshl_add_u64 v[24:25], v[24:25], 0, v[72:73]
	global_load_dwordx2 v[80:81], v[32:33], off
	global_load_dwordx2 v[82:83], v[34:35], off
	global_load_dwordx2 v[84:85], v[36:37], off
	global_load_dwordx2 v[86:87], v[38:39], off
	v_lshl_add_u64 v[32:33], v[48:49], 0, v[72:73]
	v_lshl_add_u64 v[26:27], v[26:27], 0, v[72:73]
	v_lshl_add_u64 v[34:35], v[50:51], 0, v[72:73]
	v_lshl_add_u64 v[28:29], v[28:29], 0, v[72:73]
	v_lshl_add_u64 v[36:37], v[52:53], 0, v[72:73]
	v_lshl_add_u64 v[30:31], v[30:31], 0, v[72:73]
	v_lshl_add_u64 v[38:39], s[10:11], 0, v[76:77]
	global_load_dwordx2 v[88:89], v[40:41], off
	v_lshlrev_b64 v[94:95], 2, v[24:25]
	v_lshlrev_b64 v[96:97], 2, v[32:33]
	v_lshlrev_b64 v[98:99], 2, v[26:27]
	v_lshlrev_b64 v[100:101], 2, v[34:35]
	v_lshlrev_b64 v[102:103], 2, v[28:29]
	v_lshlrev_b64 v[104:105], 2, v[36:37]
	v_lshlrev_b64 v[106:107], 2, v[30:31]
	global_load_dwordx4 v[24:27], v[38:39], off
	v_lshl_add_u64 v[28:29], s[10:11], 0, v[94:95]
	v_lshl_add_u64 v[32:33], s[10:11], 0, v[96:97]
	v_lshl_add_u64 v[36:37], s[10:11], 0, v[98:99]
	v_lshl_add_u64 v[40:41], s[10:11], 0, v[100:101]
	v_lshl_add_u64 v[44:45], s[10:11], 0, v[102:103]
	v_lshl_add_u64 v[48:49], s[10:11], 0, v[104:105]
	v_lshl_add_u64 v[52:53], s[10:11], 0, v[106:107]
	global_load_dwordx4 v[28:31], v[28:29], off
	s_nop 0
	global_load_dwordx4 v[32:35], v[32:33], off
	s_nop 0
	global_load_dwordx4 v[36:39], v[36:37], off
	s_nop 0
	global_load_dwordx4 v[40:43], v[40:41], off
	s_nop 0
	global_load_dwordx4 v[44:47], v[44:45], off
	s_nop 0
	global_load_dwordx4 v[48:51], v[48:49], off
	s_nop 0
	global_load_dwordx4 v[52:55], v[52:53], off
	ds_read_b128 v[56:59], v64
	ds_read_b128 v[60:63], v65
	ds_read_b128 v[64:67], v66
	ds_read_b128 v[68:71], v68
	s_addk_i32 s45, 0x1000
	v_lshl_add_u64 v[76:77], s[54:55], 0, v[76:77]
	s_cmpk_lg_i32 s45, 0x2000
	v_lshl_add_u64 v[94:95], s[54:55], 0, v[94:95]
	v_lshl_add_u64 v[96:97], s[54:55], 0, v[96:97]
	v_lshl_add_u64 v[98:99], s[54:55], 0, v[98:99]
	v_lshl_add_u64 v[100:101], s[54:55], 0, v[100:101]
	v_lshl_add_u64 v[102:103], s[54:55], 0, v[102:103]
	v_lshl_add_u64 v[104:105], s[54:55], 0, v[104:105]
	v_lshl_add_u64 v[106:107], s[54:55], 0, v[106:107]
	s_waitcnt vmcnt(7)
; template <int MODE> ...
;     ...
;             if (MODE == 4) {
;               float2 st = *(const float2*)(aux0 + 2 * (long)(brow + ai * HALF + row));
;               float4 gg = *(const float4*)(aux1 + bcol + q * 4), bb = *(const float4*)(aux2 + bcol + q * 4);
;               r.x = (r.x - st.x) * st.y * gg.x + bb.x; r.y = (r.y - st.x) * st.y * gg.y + bb.y;
;               r.z = (r.z - st.x) * st.y * gg.z + bb.z; r.w = (r.w - st.x) * st.y * gg.w + bb.w;
;             }
;             float4 o; o.x = ALPHA * r.x + v.x; o.y = ALPHA * r.y + v.y; o.z = ALPHA * r.z + v.z; o.w = ALPHA * r.w + v.w;
;             *(float4*)(outf + g) = o;
;           }
	v_pk_add_f32 v[24:25], v[24:25], v[74:75] op_sel_hi:[1,0] neg_lo:[0,1] neg_hi:[0,1]
	v_pk_add_f32 v[26:27], v[26:27], v[74:75] op_sel_hi:[1,0] neg_lo:[0,1] neg_hi:[0,1]
	v_pk_mul_f32 v[24:25], v[24:25], v[74:75] op_sel:[0,1]
	v_pk_mul_f32 v[26:27], v[26:27], v[74:75] op_sel:[0,1]
	s_waitcnt vmcnt(6)
	v_pk_add_f32 v[28:29], v[28:29], v[80:81] op_sel_hi:[1,0] neg_lo:[0,1] neg_hi:[0,1]
	v_pk_add_f32 v[30:31], v[30:31], v[80:81] op_sel_hi:[1,0] neg_lo:[0,1] neg_hi:[0,1]
	s_waitcnt vmcnt(5)
	v_pk_add_f32 v[32:33], v[32:33], v[82:83] op_sel_hi:[1,0] neg_lo:[0,1] neg_hi:[0,1]
	v_pk_add_f32 v[34:35], v[34:35], v[82:83] op_sel_hi:[1,0] neg_lo:[0,1] neg_hi:[0,1]
	s_waitcnt vmcnt(4)
	v_pk_add_f32 v[36:37], v[36:37], v[84:85] op_sel_hi:[1,0] neg_lo:[0,1] neg_hi:[0,1]
	v_pk_add_f32 v[38:39], v[38:39], v[84:85] op_sel_hi:[1,0] neg_lo:[0,1] neg_hi:[0,1]
	s_waitcnt vmcnt(3)
	v_pk_add_f32 v[40:41], v[40:41], v[86:87] op_sel_hi:[1,0] neg_lo:[0,1] neg_hi:[0,1]
	v_pk_add_f32 v[42:43], v[42:43], v[86:87] op_sel_hi:[1,0] neg_lo:[0,1] neg_hi:[0,1]
	s_waitcnt vmcnt(2)
	v_pk_add_f32 v[44:45], v[44:45], v[88:89] op_sel_hi:[1,0] neg_lo:[0,1] neg_hi:[0,1]
	v_pk_add_f32 v[46:47], v[46:47], v[88:89] op_sel_hi:[1,0] neg_lo:[0,1] neg_hi:[0,1]
	s_waitcnt vmcnt(1)
	v_pk_add_f32 v[48:49], v[48:49], v[90:91] op_sel_hi:[1,0] neg_lo:[0,1] neg_hi:[0,1]
	v_pk_add_f32 v[50:51], v[50:51], v[90:91] op_sel_hi:[1,0] neg_lo:[0,1] neg_hi:[0,1]
	s_waitcnt vmcnt(0)
	v_pk_add_f32 v[52:53], v[52:53], v[92:93] op_sel_hi:[1,0] neg_lo:[0,1] neg_hi:[0,1]
	v_pk_add_f32 v[54:55], v[54:55], v[92:93] op_sel_hi:[1,0] neg_lo:[0,1] neg_hi:[0,1]
	v_pk_fma_f32 v[24:25], v[0:1], v[24:25], v[4:5]
	v_pk_fma_f32 v[26:27], v[2:3], v[26:27], v[6:7]
	v_pk_mul_f32 v[28:29], v[28:29], v[80:81] op_sel:[0,1]
	v_pk_mul_f32 v[30:31], v[30:31], v[80:81] op_sel:[0,1]
	v_pk_mul_f32 v[32:33], v[32:33], v[82:83] op_sel:[0,1]
	v_pk_mul_f32 v[34:35], v[34:35], v[82:83] op_sel:[0,1]
	v_pk_mul_f32 v[36:37], v[36:37], v[84:85] op_sel:[0,1]
	v_pk_mul_f32 v[38:39], v[38:39], v[84:85] op_sel:[0,1]
	v_pk_mul_f32 v[40:41], v[40:41], v[86:87] op_sel:[0,1]
	v_pk_mul_f32 v[42:43], v[42:43], v[86:87] op_sel:[0,1]
	v_pk_mul_f32 v[44:45], v[44:45], v[88:89] op_sel:[0,1]
	v_pk_mul_f32 v[46:47], v[46:47], v[88:89] op_sel:[0,1]
	v_pk_mul_f32 v[48:49], v[48:49], v[90:91] op_sel:[0,1]
	v_pk_mul_f32 v[50:51], v[50:51], v[90:91] op_sel:[0,1]
	v_pk_mul_f32 v[52:53], v[52:53], v[92:93] op_sel:[0,1]
	v_pk_mul_f32 v[54:55], v[54:55], v[92:93] op_sel:[0,1]
	s_waitcnt lgkmcnt(7)
	v_pk_fma_f32 v[8:9], v[24:25], s[44:45], v[8:9] op_sel_hi:[1,0,1]
	v_pk_fma_f32 v[10:11], v[26:27], s[44:45], v[10:11] op_sel_hi:[1,0,1]
	v_pk_fma_f32 v[24:25], v[0:1], v[28:29], v[4:5]
	v_pk_fma_f32 v[26:27], v[2:3], v[30:31], v[6:7]
	v_pk_fma_f32 v[28:29], v[0:1], v[32:33], v[4:5]
	v_pk_fma_f32 v[30:31], v[2:3], v[34:35], v[6:7]
	v_pk_fma_f32 v[32:33], v[0:1], v[36:37], v[4:5]
	v_pk_fma_f32 v[34:35], v[2:3], v[38:39], v[6:7]
	v_pk_fma_f32 v[36:37], v[0:1], v[40:41], v[4:5]
	v_pk_fma_f32 v[38:39], v[2:3], v[42:43], v[6:7]
	v_pk_fma_f32 v[40:41], v[0:1], v[44:45], v[4:5]
	v_pk_fma_f32 v[42:43], v[2:3], v[46:47], v[6:7]
	v_pk_fma_f32 v[44:45], v[0:1], v[48:49], v[4:5]
	v_pk_fma_f32 v[46:47], v[2:3], v[50:51], v[6:7]
	v_pk_fma_f32 v[48:49], v[0:1], v[52:53], v[4:5]
	v_pk_fma_f32 v[50:51], v[2:3], v[54:55], v[6:7]
	global_store_dwordx4 v[76:77], v[8:11], off sc1
	s_waitcnt lgkmcnt(6)
	v_pk_fma_f32 v[12:13], v[28:29], s[44:45], v[12:13] op_sel_hi:[1,0,1]
	v_pk_fma_f32 v[14:15], v[30:31], s[44:45], v[14:15] op_sel_hi:[1,0,1]
	s_waitcnt lgkmcnt(3)
	v_pk_fma_f32 v[8:9], v[24:25], s[44:45], v[56:57] op_sel_hi:[1,0,1]
	v_pk_fma_f32 v[10:11], v[26:27], s[44:45], v[58:59] op_sel_hi:[1,0,1]
	s_waitcnt lgkmcnt(2)
	v_pk_fma_f32 v[24:25], v[32:33], s[44:45], v[60:61] op_sel_hi:[1,0,1]
	v_pk_fma_f32 v[26:27], v[34:35], s[44:45], v[62:63] op_sel_hi:[1,0,1]
	v_pk_fma_f32 v[16:17], v[36:37], s[44:45], v[16:17] op_sel_hi:[1,0,1]
	v_pk_fma_f32 v[18:19], v[38:39], s[44:45], v[18:19] op_sel_hi:[1,0,1]
	s_waitcnt lgkmcnt(1)
	v_pk_fma_f32 v[28:29], v[40:41], s[44:45], v[64:65] op_sel_hi:[1,0,1]
	v_pk_fma_f32 v[30:31], v[42:43], s[44:45], v[66:67] op_sel_hi:[1,0,1]
	v_pk_fma_f32 v[20:21], v[44:45], s[44:45], v[20:21] op_sel_hi:[1,0,1]
	v_pk_fma_f32 v[22:23], v[46:47], s[44:45], v[22:23] op_sel_hi:[1,0,1]
	s_waitcnt lgkmcnt(0)
	v_pk_fma_f32 v[32:33], v[48:49], s[44:45], v[68:69] op_sel_hi:[1,0,1]
	v_pk_fma_f32 v[34:35], v[50:51], s[44:45], v[70:71] op_sel_hi:[1,0,1]
	global_store_dwordx4 v[94:95], v[8:11], off sc1
	global_store_dwordx4 v[96:97], v[12:15], off sc1
	global_store_dwordx4 v[98:99], v[24:27], off sc1
	global_store_dwordx4 v[100:101], v[16:19], off sc1
	global_store_dwordx4 v[102:103], v[28:31], off sc1
	global_store_dwordx4 v[104:105], v[20:23], off sc1
	global_store_dwordx4 v[106:107], v[32:35], off sc1
	s_cbranch_scc1 .LBB0_854
	s_waitcnt lgkmcnt(0)
	s_barrier
	s_add_i32 s35, s35, s14
	s_cmpk_gt_i32 s35, 0x1ff
	s_cbranch_scc0 .LBB0_841

; DEVI float wave_sum(float v) { for (int o = 32; o > 0; o >>= 1) v += __shfl_xor(v, o); return v; }
; __device__ NOINL void phase_ln(float* __restrict__ buf, const float* __restrict__ g, const float* __restrict__ bta, u16* __restrict__ outb,
;                                float* __restrict__ stats) {
;     ...
;   for (int row = blockIdx.x * 8 + w; row < 8192; row += gridDim.x * 8) {
;     float* rp = buf + (size_t)row * 4096;
;     float s = 0.f, q = 0.f;
; #pragma unroll 16
;     for (int i = 0; i < 16; ++i) {
;       float4 v = *(const float4*)(rp + (i * 64 + lane) * 4);
;       s += v.x + v.y + v.z + v.w;
;     }
;     float mu = wave_sum(s) * (1.f / 4096.f);
.LBB0_898:
	v_ashrrev_i32_e32 v113, 31, v112
	v_lshlrev_b64 v[40:41], 14, v[112:113]
	v_lshl_add_u64 v[210:211], s[54:55], 0, v[40:41]
	v_lshl_add_u64 v[212:213], v[210:211], 0, v[114:115]
	global_load_dwordx4 v[80:83], v[212:213], off
	global_load_dwordx4 v[92:95], v[212:213], off offset:1024
	global_load_dwordx4 v[96:99], v[212:213], off offset:2048
	global_load_dwordx4 v[84:87], v[212:213], off offset:3072
	v_add_co_u32_e32 v40, vcc, s4, v212
	v_mov_b32_e32 v209, v115
	s_nop 0
	v_addc_co_u32_e32 v41, vcc, 0, v213, vcc
	v_add_co_u32_e32 v42, vcc, s2, v212
	v_lshl_add_u64 v[214:215], v[210:211], 0, v[208:209]
	s_nop 0
	v_addc_co_u32_e32 v43, vcc, 0, v213, vcc
	global_load_dwordx4 v[100:103], v[42:43], off offset:-4096
	global_load_dwordx4 v[88:91], v[40:41], off offset:1024
	global_load_dwordx4 v[76:79], v[40:41], off offset:2048
	global_load_dwordx4 v[72:75], v[40:41], off offset:3072
	global_load_dwordx4 v[68:71], v[42:43], off
	global_load_dwordx4 v[64:67], v[42:43], off offset:1024
	global_load_dwordx4 v[56:59], v[42:43], off offset:2048
	global_load_dwordx4 v[48:51], v[42:43], off offset:3072
	v_add_co_u32_e32 v60, vcc, s5, v212
	v_mov_b32_e32 v203, v115
	s_nop 0
	v_addc_co_u32_e32 v61, vcc, 0, v213, vcc
	global_load_dwordx4 v[40:43], v[60:61], off
	global_load_dwordx4 v[44:47], v[60:61], off offset:1024
	global_load_dwordx4 v[52:55], v[60:61], off offset:2048
	s_nop 0
	global_load_dwordx4 v[60:63], v[60:61], off offset:3072
	s_nop 0
	global_load_dwordx4 v[108:111], v[212:213], off
	global_load_dwordx4 v[104:107], v[214:215], off
	v_mov_b32_e32 v205, v115
	v_mov_b32_e32 v207, v115
	v_add_u32_e32 v112, s3, v112
	s_waitcnt vmcnt(17)
	v_add_f32_e32 v113, v80, v81
	s_waitcnt vmcnt(16)
	v_add_f32_e32 v181, v92, v93
	v_add_f32_e32 v113, v113, v82
	s_waitcnt vmcnt(15)
	v_add_f32_e32 v183, v96, v97
	v_add_f32_e32 v181, v181, v94
	v_add_f32_e32 v113, v113, v83
	s_waitcnt vmcnt(14)
	v_add_f32_e32 v185, v84, v85
	v_add_f32_e32 v183, v183, v98
	v_add_f32_e32 v181, v181, v95
	v_add_f32_e32 v113, 0, v113
	v_add_f32_e32 v185, v185, v86
	s_waitcnt vmcnt(13)
	v_add_f32_e32 v187, v100, v101
	v_add_f32_e32 v183, v183, v99
	v_add_f32_e32 v113, v113, v181
	s_waitcnt vmcnt(12)
	v_add_f32_e32 v189, v88, v89
	v_add_f32_e32 v185, v185, v87
	v_add_f32_e32 v187, v187, v102
	v_add_f32_e32 v113, v113, v183
	s_waitcnt vmcnt(11)
	v_add_f32_e32 v191, v76, v77
	v_add_f32_e32 v189, v189, v90
	v_add_f32_e32 v187, v187, v103
	v_add_f32_e32 v113, v113, v185
	s_waitcnt vmcnt(10)
	v_add_f32_e32 v193, v72, v73
	v_add_f32_e32 v191, v191, v78
	v_add_f32_e32 v189, v189, v91
	v_add_f32_e32 v113, v113, v187
	s_waitcnt vmcnt(9)
	v_add_f32_e32 v195, v68, v69
	v_add_f32_e32 v193, v193, v74
	v_add_f32_e32 v191, v191, v79
	v_add_f32_e32 v113, v113, v189
	s_waitcnt vmcnt(8)
	v_add_f32_e32 v197, v64, v65
	v_add_f32_e32 v195, v195, v70
	v_add_f32_e32 v193, v193, v75
	v_add_f32_e32 v113, v113, v191
	s_waitcnt vmcnt(7)
	v_add_f32_e32 v199, v56, v57
	v_add_f32_e32 v197, v197, v66
	v_add_f32_e32 v195, v195, v71
	v_add_f32_e32 v113, v113, v193
	s_waitcnt vmcnt(6)
	v_add_f32_e32 v201, v48, v49
	s_waitcnt vmcnt(5)
	v_mov_b32_e32 v224, v40
	s_waitcnt vmcnt(4)
	v_mov_b32_e32 v225, v44
	v_mov_b32_e32 v226, v41
	v_mov_b32_e32 v227, v45
	v_add_f32_e32 v199, v199, v58
	v_add_f32_e32 v197, v197, v67
	v_add_f32_e32 v113, v113, v195
	v_mov_b32_e32 v228, v42
	v_mov_b32_e32 v229, v46
	v_add_f32_e32 v201, v201, v50
	v_pk_add_f32 v[224:225], v[224:225], v[226:227]
	v_add_f32_e32 v199, v199, v59
	v_add_f32_e32 v113, v113, v197
	v_mov_b32_e32 v230, v43
	v_mov_b32_e32 v231, v47
	v_add_f32_e32 v201, v201, v51
	v_pk_add_f32 v[224:225], v[224:225], v[228:229]
	v_add_f32_e32 v113, v113, v199
	v_pk_add_f32 v[224:225], v[224:225], v[230:231]
	v_add_f32_e32 v113, v113, v201
	s_waitcnt vmcnt(3)
	v_mov_b32_e32 v232, v52
	s_waitcnt vmcnt(2)
	v_mov_b32_e32 v233, v60
	v_mov_b32_e32 v234, v53
	v_mov_b32_e32 v235, v61
	v_add_f32_e32 v113, v113, v224
	v_add_f32_e32 v113, v113, v225
	v_pk_add_f32 v[224:225], v[232:233], v[234:235]
	v_mov_b32_e32 v226, v54
	v_mov_b32_e32 v227, v62
	v_pk_add_f32 v[224:225], v[224:225], v[226:227]
	v_mov_b32_e32 v226, v55
	v_mov_b32_e32 v227, v63
	v_pk_add_f32 v[224:225], v[224:225], v[226:227]
	v_mov_b32_e32 v183, v115
	v_add_f32_e32 v113, v113, v224
	v_add_f32_e32 v113, v113, v225
	ds_bpermute_b32 v181, v217, v113
	v_mov_b32_e32 v185, v115
	v_mov_b32_e32 v187, v115
	v_mov_b32_e32 v189, v115
	v_mov_b32_e32 v191, v115
	s_waitcnt lgkmcnt(0)
	v_add_f32_e32 v113, v113, v181
	ds_bpermute_b32 v181, v218, v113
	v_mov_b32_e32 v193, v115
	v_mov_b32_e32 v195, v115
	v_mov_b32_e32 v197, v115
	v_mov_b32_e32 v199, v115
	s_waitcnt lgkmcnt(0)
	v_add_f32_e32 v113, v113, v181
	ds_bpermute_b32 v181, v219, v113
	v_mov_b32_e32 v201, v115
	v_lshl_add_u64 v[224:225], v[210:211], 0, v[204:205]
	s_waitcnt lgkmcnt(0)
	v_add_f32_e32 v113, v113, v181
	ds_bpermute_b32 v181, v220, v113
	s_waitcnt lgkmcnt(0)
	v_add_f32_e32 v113, v113, v181
	ds_bpermute_b32 v181, v221, v113
	s_waitcnt lgkmcnt(0)
	v_add_f32_e32 v113, v113, v181
	ds_bpermute_b32 v181, v222, v113
	s_waitcnt lgkmcnt(0)
; DEVI float wave_sum(float v) { for (int o = 32; o > 0; o >>= 1) v += __shfl_xor(v, o); return v; }
; __device__ NOINL void phase_ln(float* __restrict__ buf, const float* __restrict__ g, const float* __restrict__ bta, u16* __restrict__ outb,
;                                float* __restrict__ stats) {
;     ...
; #pragma unroll 16
;     for (int i = 0; i < 16; ++i) {
;       float4 v = *(const float4*)(rp + (i * 64 + lane) * 4);
;       float a = v.x - mu, b = v.y - mu, c = v.z - mu, d = v.w - mu;
;       q += a * a + b * b + c * c + d * d;
;     }
;     float rs = rsqrtf(wave_sum(q) * (1.f / 4096.f) + 1e-5f);
;     if (stats && lane == 0) { stats[2 * row] = mu; stats[2 * row + 1] = rs; }
; #pragma unroll 8
;     for (int i = 0; i < 16; ++i) {
;       int col = (i * 64 + lane) * 4;
	v_add_f32_e32 v113, v113, v181
	v_fmamk_f32 v81, v113, 0xb9800000, v81
	v_fmamk_f32 v93, v113, 0xb9800000, v93
	v_fmamk_f32 v80, v113, 0xb9800000, v80
	v_fmamk_f32 v92, v113, 0xb9800000, v92
	v_mul_f32_e32 v81, v81, v81
	v_mul_f32_e32 v93, v93, v93
	v_fmamk_f32 v82, v113, 0xb9800000, v82
	v_fmamk_f32 v94, v113, 0xb9800000, v94
	v_fmac_f32_e32 v81, v80, v80
	v_fmac_f32_e32 v93, v92, v92
	v_fmac_f32_e32 v83, 0xb9800000, v113
	v_fmac_f32_e32 v95, 0xb9800000, v113
	v_fmamk_f32 v97, v113, 0xb9800000, v97
	v_fmac_f32_e32 v81, v82, v82
	v_fmac_f32_e32 v93, v94, v94
	v_fmamk_f32 v96, v113, 0xb9800000, v96
	v_mul_f32_e32 v97, v97, v97
	v_fmac_f32_e32 v81, v83, v83
	v_fmac_f32_e32 v93, v95, v95
	v_fmamk_f32 v82, v113, 0xb9800000, v85
	v_fmamk_f32 v98, v113, 0xb9800000, v98
	v_add_f32_e32 v80, v81, v93
	v_fmac_f32_e32 v97, v96, v96
	v_fmamk_f32 v81, v113, 0xb9800000, v84
	v_mul_f32_e32 v82, v82, v82
	v_fmac_f32_e32 v99, 0xb9800000, v113
	v_fmac_f32_e32 v97, v98, v98
	v_fmamk_f32 v83, v113, 0xb9800000, v86
	v_fmac_f32_e32 v82, v81, v81
	v_fmac_f32_e32 v97, v99, v99
	v_fmac_f32_e32 v87, 0xb9800000, v113
	v_fmac_f32_e32 v82, v83, v83
	v_add_f32_e32 v80, v97, v80
	v_fmac_f32_e32 v82, v87, v87
	v_add_f32_e32 v80, v82, v80
	v_fmamk_f32 v82, v113, 0xb9800000, v101
	v_fmamk_f32 v81, v113, 0xb9800000, v100
	v_mul_f32_e32 v82, v82, v82
	v_fmamk_f32 v83, v113, 0xb9800000, v102
	v_fmac_f32_e32 v82, v81, v81
	v_fmac_f32_e32 v103, 0xb9800000, v113
	v_fmac_f32_e32 v82, v83, v83
	v_fmac_f32_e32 v82, v103, v103
	v_add_f32_e32 v80, v82, v80
	v_fmamk_f32 v82, v113, 0xb9800000, v89
	v_fmamk_f32 v81, v113, 0xb9800000, v88
	v_mul_f32_e32 v82, v82, v82
	v_fmamk_f32 v77, v113, 0xb9800000, v77
	v_fmamk_f32 v83, v113, 0xb9800000, v90
	v_fmac_f32_e32 v82, v81, v81
	v_fmamk_f32 v76, v113, 0xb9800000, v76
	v_mul_f32_e32 v77, v77, v77
	v_fmamk_f32 v73, v113, 0xb9800000, v73
	v_fmac_f32_e32 v91, 0xb9800000, v113
	v_fmac_f32_e32 v82, v83, v83
	v_fmamk_f32 v78, v113, 0xb9800000, v78
	v_fmac_f32_e32 v77, v76, v76
	v_fmamk_f32 v72, v113, 0xb9800000, v72
	v_mul_f32_e32 v73, v73, v73
	v_fmamk_f32 v69, v113, 0xb9800000, v69
	v_fmac_f32_e32 v82, v91, v91
	v_fmac_f32_e32 v79, 0xb9800000, v113
	v_fmac_f32_e32 v77, v78, v78
	v_fmamk_f32 v74, v113, 0xb9800000, v74
	v_fmac_f32_e32 v73, v72, v72
	v_fmamk_f32 v68, v113, 0xb9800000, v68
	v_mul_f32_e32 v69, v69, v69
	v_fmamk_f32 v65, v113, 0xb9800000, v65
	v_add_f32_e32 v80, v82, v80
	v_fmac_f32_e32 v77, v79, v79
	v_fmac_f32_e32 v75, 0xb9800000, v113
	v_fmac_f32_e32 v73, v74, v74
	v_fmamk_f32 v70, v113, 0xb9800000, v70
	v_fmac_f32_e32 v69, v68, v68
	v_fmamk_f32 v64, v113, 0xb9800000, v64
	v_mul_f32_e32 v65, v65, v65
	v_fmamk_f32 v57, v113, 0xb9800000, v57
	v_add_f32_e32 v76, v77, v80
	v_fmac_f32_e32 v73, v75, v75
	v_fmac_f32_e32 v71, 0xb9800000, v113
	v_fmac_f32_e32 v69, v70, v70
	v_fmamk_f32 v66, v113, 0xb9800000, v66
	v_fmac_f32_e32 v65, v64, v64
	v_fmamk_f32 v56, v113, 0xb9800000, v56
	v_mul_f32_e32 v57, v57, v57
	v_fmamk_f32 v49, v113, 0xb9800000, v49
	v_add_f32_e32 v72, v73, v76
	v_fmac_f32_e32 v69, v71, v71
	v_fmac_f32_e32 v67, 0xb9800000, v113
	v_fmac_f32_e32 v65, v66, v66
	v_fmamk_f32 v58, v113, 0xb9800000, v58
	v_fmac_f32_e32 v57, v56, v56
	v_fmamk_f32 v48, v113, 0xb9800000, v48
	v_mul_f32_e32 v49, v49, v49
	v_add_f32_e32 v68, v69, v72
	v_fmac_f32_e32 v65, v67, v67
	v_fmac_f32_e32 v59, 0xb9800000, v113
	v_fmac_f32_e32 v57, v58, v58
	v_fmamk_f32 v50, v113, 0xb9800000, v50
	v_fmac_f32_e32 v49, v48, v48
	v_add_f32_e32 v64, v65, v68
	v_fmac_f32_e32 v57, v59, v59
	v_fmac_f32_e32 v51, 0xb9800000, v113
	v_fmac_f32_e32 v49, v50, v50
	v_add_f32_e32 v56, v57, v64
	v_fmac_f32_e32 v49, v51, v51
	v_mul_f32_e32 v216, 0x39800000, v113
	v_add_f32_e32 v58, v49, v56
	v_mov_b32_e32 v49, v40
	v_mov_b32_e32 v40, v45
	v_mov_b32_e32 v181, v115
	v_mov_b32_e32 v48, v44
	v_pk_add_f32 v[40:41], v[40:41], v[216:217] op_sel_hi:[1,0] neg_lo:[0,1] neg_hi:[0,1]
	v_lshl_add_u64 v[76:77], v[210:211], 0, v[180:181]
	v_pk_add_f32 v[56:57], v[48:49], v[216:217] op_sel_hi:[1,0] neg_lo:[0,1] neg_hi:[0,1]
	v_mov_b32_e32 v44, v46
	v_mov_b32_e32 v45, v42
	global_load_dwordx4 v[48:51], v[76:77], off
	v_pk_mul_f32 v[40:41], v[40:41], v[40:41]
	v_pk_add_f32 v[44:45], v[44:45], v[216:217] op_sel_hi:[1,0] neg_lo:[0,1] neg_hi:[0,1]
	v_mov_b32_e32 v42, v47
	v_pk_fma_f32 v[40:41], v[56:57], v[56:57], v[40:41]
	v_pk_add_f32 v[42:43], v[42:43], v[216:217] op_sel_hi:[1,0] neg_lo:[0,1] neg_hi:[0,1]
	v_pk_fma_f32 v[40:41], v[44:45], v[44:45], v[40:41]
	v_mov_b32_e32 v44, v62
	v_pk_fma_f32 v[40:41], v[42:43], v[42:43], v[40:41]
	v_mov_b32_e32 v45, v54
	v_add_f32_e32 v41, v41, v58
	v_add_f32_e32 v56, v40, v41
	v_mov_b32_e32 v41, v52
	v_mov_b32_e32 v52, v61
	v_mov_b32_e32 v40, v60
	v_pk_add_f32 v[42:43], v[52:53], v[216:217] op_sel_hi:[1,0] neg_lo:[0,1] neg_hi:[0,1]
	v_pk_add_f32 v[40:41], v[40:41], v[216:217] op_sel_hi:[1,0] neg_lo:[0,1] neg_hi:[0,1]
	v_pk_mul_f32 v[42:43], v[42:43], v[42:43]
	v_pk_add_f32 v[44:45], v[44:45], v[216:217] op_sel_hi:[1,0] neg_lo:[0,1] neg_hi:[0,1]
	v_mov_b32_e32 v54, v63
	v_pk_fma_f32 v[40:41], v[40:41], v[40:41], v[42:43]
	v_lshl_add_u64 v[78:79], v[210:211], 0, v[182:183]
	v_pk_add_f32 v[46:47], v[54:55], v[216:217] op_sel_hi:[1,0] neg_lo:[0,1] neg_hi:[0,1]
	v_pk_fma_f32 v[40:41], v[44:45], v[44:45], v[40:41]
	v_lshl_add_u64 v[80:81], v[210:211], 0, v[184:185]
	global_load_dwordx4 v[42:45], v[78:79], off
	global_load_dwordx4 v[52:55], v[80:81], off
	v_pk_fma_f32 v[40:41], v[46:47], v[46:47], v[40:41]
	v_lshl_add_u64 v[82:83], v[210:211], 0, v[186:187]
	v_add_f32_e32 v41, v41, v56
	v_lshl_add_u64 v[84:85], v[210:211], 0, v[188:189]
	global_load_dwordx4 v[56:59], v[82:83], off
	global_load_dwordx4 v[60:63], v[84:85], off
	v_add_f32_e32 v40, v40, v41
	ds_bpermute_b32 v41, v217, v40
	s_waitcnt vmcnt(6)
; DEVI float wave_sum(float v) { for (int o = 32; o > 0; o >>= 1) v += __shfl_xor(v, o); return v; }
; __device__ NOINL void phase_ln(float* __restrict__ buf, const float* __restrict__ g, const float* __restrict__ bta, u16* __restrict__ outb,
;                                float* __restrict__ stats) {
;     ...
;     float rs = rsqrtf(wave_sum(q) * (1.f / 4096.f) + 1e-5f);
;     if (stats && lane == 0) { stats[2 * row] = mu; stats[2 * row + 1] = rs; }
; #pragma unroll 8
;     for (int i = 0; i < 16; ++i) {
;       int col = (i * 64 + lane) * 4;
;       float4 v = *(const float4*)(rp + col);
;       float4 gg = *(const float4*)(g + col), bb = *(const float4*)(bta + col);
;       float4 o;
;       o.x = (v.x - mu) * rs * gg.x + bb.x; o.y = (v.y - mu) * rs * gg.y + bb.y;
;       o.z = (v.z - mu) * rs * gg.z + bb.z; o.w = (v.w - mu) * rs * gg.w + bb.w;
;       if (!stats) *(float4*)(rp + col) = o;
	v_mov_b32_e32 v46, v108
	v_mov_b32_e32 v64, v110
	v_lshl_add_u64 v[88:89], v[210:211], 0, v[190:191]
	v_lshl_add_u64 v[90:91], v[210:211], 0, v[192:193]
	s_waitcnt lgkmcnt(0)
	v_add_f32_e32 v40, v40, v41
	ds_bpermute_b32 v41, v218, v40
	v_lshl_add_u64 v[100:101], v[210:211], 0, v[194:195]
	v_lshl_add_u64 v[102:103], v[210:211], 0, v[196:197]
	s_waitcnt lgkmcnt(0)
	v_add_f32_e32 v40, v40, v41
	ds_bpermute_b32 v41, v219, v40
	s_waitcnt lgkmcnt(0)
	v_add_f32_e32 v40, v40, v41
	ds_bpermute_b32 v41, v220, v40
	s_waitcnt lgkmcnt(0)
	v_add_f32_e32 v40, v40, v41
	ds_bpermute_b32 v41, v221, v40
	s_waitcnt lgkmcnt(0)
	v_add_f32_e32 v40, v40, v41
	ds_bpermute_b32 v41, v222, v40
	s_waitcnt lgkmcnt(0)
	v_add_f32_e32 v40, v40, v41
	v_fmamk_f32 v40, v40, 0x39800000, v223
	v_mul_f32_e32 v41, 0x4b800000, v40
	v_cmp_gt_f32_e32 vcc, s6, v40
	s_waitcnt vmcnt(4)
	v_mov_b32_e32 v47, v48
	v_cndmask_b32_e32 v40, v40, v41, vcc
	v_rsq_f32_e32 v40, v40
	v_pk_add_f32 v[46:47], v[46:47], v[216:217] op_sel_hi:[1,0] neg_lo:[0,1] neg_hi:[0,1]
	v_mov_b32_e32 v48, v109
	v_mov_b32_e32 v65, v50
	v_mul_f32_e32 v41, 0x45800000, v40
	v_cndmask_b32_e32 v40, v40, v41, vcc
	v_pk_mul_f32 v[46:47], v[40:41], v[46:47] op_sel_hi:[0,1]
	v_pk_fma_f32 v[86:87], v[46:47], v[116:117], v[120:121]
	v_pk_add_f32 v[46:47], v[48:49], v[216:217] op_sel_hi:[1,0] neg_lo:[0,1] neg_hi:[0,1]
	v_pk_add_f32 v[48:49], v[64:65], v[216:217] op_sel_hi:[1,0] neg_lo:[0,1] neg_hi:[0,1]
	v_mov_b32_e32 v50, v111
	v_pk_mul_f32 v[48:49], v[40:41], v[48:49] op_sel_hi:[0,1]
	global_load_dwordx4 v[64:67], v[88:89], off
	global_load_dwordx4 v[68:71], v[90:91], off
	v_pk_fma_f32 v[92:93], v[48:49], v[118:119], v[122:123]
	v_pk_add_f32 v[48:49], v[50:51], v[216:217] op_sel_hi:[1,0] neg_lo:[0,1] neg_hi:[0,1]
	v_pk_mul_f32 v[46:47], v[40:41], v[46:47] op_sel_hi:[0,1]
	v_pk_mul_f32 v[48:49], v[40:41], v[48:49] op_sel_hi:[0,1]
	v_pk_fma_f32 v[46:47], v[46:47], v[0:1], v[4:5]
	v_pk_fma_f32 v[48:49], v[48:49], v[2:3], v[6:7]
	v_mov_b32_e32 v73, v46
	v_mov_b32_e32 v75, v48
	v_mov_b32_e32 v46, v87
	v_mov_b32_e32 v48, v93
	global_store_dwordx4 v[76:77], v[46:49], off sc1
	v_mov_b32_e32 v72, v86
	v_mov_b32_e32 v74, v92
	s_waitcnt vmcnt(6)
	v_mov_b32_e32 v46, v42
	s_waitcnt vmcnt(5)
	v_mov_b32_e32 v47, v52
	v_mov_b32_e32 v48, v44
	v_mov_b32_e32 v49, v54
	v_mov_b32_e32 v52, v43
	v_mov_b32_e32 v54, v45
	v_pk_add_f32 v[42:43], v[46:47], v[216:217] op_sel_hi:[1,0] neg_lo:[0,1] neg_hi:[0,1]
	v_pk_add_f32 v[44:45], v[48:49], v[216:217] op_sel_hi:[1,0] neg_lo:[0,1] neg_hi:[0,1]
	v_pk_mul_f32 v[42:43], v[40:41], v[42:43] op_sel_hi:[0,1]
	v_pk_mul_f32 v[44:45], v[40:41], v[44:45] op_sel_hi:[0,1]
	v_pk_fma_f32 v[76:77], v[42:43], v[124:125], v[128:129]
	v_pk_add_f32 v[42:43], v[52:53], v[216:217] op_sel_hi:[1,0] neg_lo:[0,1] neg_hi:[0,1]
	v_pk_fma_f32 v[86:87], v[44:45], v[126:127], v[130:131]
	v_pk_add_f32 v[44:45], v[54:55], v[216:217] op_sel_hi:[1,0] neg_lo:[0,1] neg_hi:[0,1]
	v_pk_mul_f32 v[42:43], v[40:41], v[42:43] op_sel_hi:[0,1]
	v_pk_mul_f32 v[44:45], v[40:41], v[44:45] op_sel_hi:[0,1]
	v_pk_fma_f32 v[42:43], v[42:43], v[8:9], v[12:13]
	v_pk_fma_f32 v[44:45], v[44:45], v[10:11], v[14:15]
	global_store_dwordx4 v[212:213], v[72:75], off sc1
	global_load_dwordx4 v[46:49], v[100:101], off
	global_load_dwordx4 v[50:53], v[102:103], off
	v_mov_b32_e32 v73, v42
	v_mov_b32_e32 v75, v44
	v_mov_b32_e32 v42, v77
	v_mov_b32_e32 v44, v87
	global_store_dwordx4 v[80:81], v[42:45], off sc1
	v_mov_b32_e32 v74, v86
	v_mov_b32_e32 v72, v76
	s_waitcnt vmcnt(8)
	v_mov_b32_e32 v42, v56
	s_waitcnt vmcnt(7)
	v_mov_b32_e32 v43, v60
	v_mov_b32_e32 v44, v58
	v_mov_b32_e32 v45, v62
	v_pk_add_f32 v[42:43], v[42:43], v[216:217] op_sel_hi:[1,0] neg_lo:[0,1] neg_hi:[0,1]
	v_pk_add_f32 v[44:45], v[44:45], v[216:217] op_sel_hi:[1,0] neg_lo:[0,1] neg_hi:[0,1]
	v_mov_b32_e32 v60, v57
	v_mov_b32_e32 v62, v59
	v_pk_mul_f32 v[42:43], v[40:41], v[42:43] op_sel_hi:[0,1]
	v_pk_mul_f32 v[44:45], v[40:41], v[44:45] op_sel_hi:[0,1]
	v_pk_fma_f32 v[80:81], v[42:43], v[132:133], v[136:137]
	v_pk_add_f32 v[42:43], v[60:61], v[216:217] op_sel_hi:[1,0] neg_lo:[0,1] neg_hi:[0,1]
	v_pk_fma_f32 v[86:87], v[44:45], v[134:135], v[138:139]
	v_pk_add_f32 v[44:45], v[62:63], v[216:217] op_sel_hi:[1,0] neg_lo:[0,1] neg_hi:[0,1]
	v_pk_mul_f32 v[42:43], v[40:41], v[42:43] op_sel_hi:[0,1]
	v_pk_mul_f32 v[44:45], v[40:41], v[44:45] op_sel_hi:[0,1]
	v_pk_fma_f32 v[42:43], v[42:43], v[16:17], v[20:21]
	v_pk_fma_f32 v[44:45], v[44:45], v[18:19], v[22:23]
	global_store_dwordx4 v[78:79], v[72:75], off sc1
	v_lshl_add_u64 v[108:109], v[210:211], 0, v[198:199]
	v_lshl_add_u64 v[110:111], v[210:211], 0, v[200:201]
	v_mov_b32_e32 v72, v80
	v_mov_b32_e32 v73, v42
	v_mov_b32_e32 v74, v86
	v_mov_b32_e32 v75, v44
	global_store_dwordx4 v[82:83], v[72:75], off sc1
	global_load_dwordx4 v[54:57], v[108:109], off
	global_load_dwordx4 v[58:61], v[110:111], off
	s_nop 0
	global_load_dwordx4 v[72:75], v[156:157], off
	global_load_dwordx4 v[76:79], v[158:159], off
	v_mov_b32_e32 v42, v81
	v_mov_b32_e32 v44, v87
	global_store_dwordx4 v[84:85], v[42:45], off sc1
	v_lshl_add_u64 v[212:213], v[210:211], 0, v[202:203]
	v_lshl_add_u64 v[210:211], v[210:211], 0, v[206:207]
	v_cmp_lt_i32_e32 vcc, s7, v112
	s_or_b64 s[0:1], vcc, s[0:1]
	s_waitcnt vmcnt(13)
	v_mov_b32_e32 v80, v64
	s_waitcnt vmcnt(12)
; __device__ NOINL void phase_ln(float* __restrict__ buf, const float* __restrict__ g, const float* __restrict__ bta, u16* __restrict__ outb,
;                                float* __restrict__ stats) {
;     ...
; #pragma unroll 8
;     for (int i = 0; i < 16; ++i) {
;       int col = (i * 64 + lane) * 4;
;       float4 v = *(const float4*)(rp + col);
;       float4 gg = *(const float4*)(g + col), bb = *(const float4*)(bta + col);
;       float4 o;
;       o.x = (v.x - mu) * rs * gg.x + bb.x; o.y = (v.y - mu) * rs * gg.y + bb.y;
;       o.z = (v.z - mu) * rs * gg.z + bb.z; o.w = (v.w - mu) * rs * gg.w + bb.w;
;       if (!stats) *(float4*)(rp + col) = o;
	v_mov_b32_e32 v81, v68
	v_mov_b32_e32 v82, v66
	v_mov_b32_e32 v83, v70
	v_mov_b32_e32 v70, v67
	v_pk_add_f32 v[66:67], v[80:81], v[216:217] op_sel_hi:[1,0] neg_lo:[0,1] neg_hi:[0,1]
	v_mov_b32_e32 v68, v65
	global_load_dwordx4 v[42:45], v[160:161], off
	global_load_dwordx4 v[62:65], v[162:163], off
	v_pk_mul_f32 v[66:67], v[40:41], v[66:67] op_sel_hi:[0,1]
	v_pk_fma_f32 v[92:93], v[66:67], v[140:141], v[144:145]
	v_pk_add_f32 v[66:67], v[68:69], v[216:217] op_sel_hi:[1,0] neg_lo:[0,1] neg_hi:[0,1]
	v_pk_add_f32 v[68:69], v[82:83], v[216:217] op_sel_hi:[1,0] neg_lo:[0,1] neg_hi:[0,1]
	v_pk_mul_f32 v[66:67], v[40:41], v[66:67] op_sel_hi:[0,1]
	v_pk_mul_f32 v[68:69], v[40:41], v[68:69] op_sel_hi:[0,1]
	v_pk_fma_f32 v[94:95], v[68:69], v[142:143], v[146:147]
	v_pk_add_f32 v[68:69], v[70:71], v[216:217] op_sel_hi:[1,0] neg_lo:[0,1] neg_hi:[0,1]
	v_pk_fma_f32 v[66:67], v[66:67], v[24:25], v[28:29]
	v_pk_mul_f32 v[68:69], v[40:41], v[68:69] op_sel_hi:[0,1]
	v_pk_fma_f32 v[68:69], v[68:69], v[26:27], v[30:31]
	v_mov_b32_e32 v80, v92
	v_mov_b32_e32 v81, v66
	v_mov_b32_e32 v82, v94
	v_mov_b32_e32 v83, v68
	global_store_dwordx4 v[88:89], v[80:83], off sc1
	global_load_dwordx4 v[80:83], v[212:213], off
	s_nop 0
	global_load_dwordx4 v[84:87], v[224:225], off
	v_mov_b32_e32 v66, v93
	v_mov_b32_e32 v68, v95
	global_store_dwordx4 v[90:91], v[66:69], off sc1
	global_load_dwordx4 v[66:69], v[164:165], off
	s_nop 0
	global_load_dwordx4 v[88:91], v[166:167], off
	global_load_dwordx4 v[92:95], v[168:169], off
	global_load_dwordx4 v[96:99], v[170:171], off
	s_waitcnt vmcnt(19)
	v_mov_b32_e32 v70, v46
	s_waitcnt vmcnt(18)
	v_mov_b32_e32 v71, v50
	v_mov_b32_e32 v226, v48
	v_mov_b32_e32 v227, v52
	v_mov_b32_e32 v50, v47
	v_mov_b32_e32 v52, v49
	v_pk_add_f32 v[46:47], v[70:71], v[216:217] op_sel_hi:[1,0] neg_lo:[0,1] neg_hi:[0,1]
	v_pk_add_f32 v[48:49], v[226:227], v[216:217] op_sel_hi:[1,0] neg_lo:[0,1] neg_hi:[0,1]
	v_pk_mul_f32 v[46:47], v[40:41], v[46:47] op_sel_hi:[0,1]
	v_pk_mul_f32 v[48:49], v[40:41], v[48:49] op_sel_hi:[0,1]
	v_pk_fma_f32 v[70:71], v[46:47], v[148:149], v[152:153]
	v_pk_add_f32 v[46:47], v[50:51], v[216:217] op_sel_hi:[1,0] neg_lo:[0,1] neg_hi:[0,1]
	v_pk_fma_f32 v[226:227], v[48:49], v[150:151], v[154:155]
	v_pk_add_f32 v[48:49], v[52:53], v[216:217] op_sel_hi:[1,0] neg_lo:[0,1] neg_hi:[0,1]
	v_pk_mul_f32 v[46:47], v[40:41], v[46:47] op_sel_hi:[0,1]
	v_pk_mul_f32 v[48:49], v[40:41], v[48:49] op_sel_hi:[0,1]
	v_pk_fma_f32 v[46:47], v[46:47], v[32:33], v[36:37]
	v_pk_fma_f32 v[48:49], v[48:49], v[34:35], v[38:39]
	v_mov_b32_e32 v51, v46
	v_mov_b32_e32 v53, v48
	v_mov_b32_e32 v46, v71
	v_mov_b32_e32 v48, v227
	v_mov_b32_e32 v50, v70
	v_mov_b32_e32 v52, v226
	global_store_dwordx4 v[102:103], v[46:49], off sc1
	global_load_dwordx4 v[46:49], v[210:211], off
	s_waitcnt vmcnt(16)
	v_mov_b32_e32 v226, v54
	global_store_dwordx4 v[100:101], v[50:53], off sc1
	s_waitcnt vmcnt(16)
	v_mov_b32_e32 v227, v58
	v_mov_b32_e32 v58, v55
	v_mov_b32_e32 v228, v56
	v_mov_b32_e32 v229, v60
	v_mov_b32_e32 v60, v57
	global_load_dwordx4 v[50:53], v[172:173], off
	global_load_dwordx4 v[54:57], v[174:175], off
	s_waitcnt vmcnt(17)
	v_mov_b32_e32 v230, v72
	s_waitcnt vmcnt(16)
	v_mov_b32_e32 v231, v76
	v_mov_b32_e32 v76, v73
	global_load_dwordx4 v[70:73], v[176:177], off
	global_load_dwordx4 v[100:103], v[178:179], off
	v_mov_b32_e32 v232, v74
	v_mov_b32_e32 v233, v78
	v_mov_b32_e32 v78, v75
	s_waitcnt vmcnt(16)
	v_mov_b32_e32 v74, v42
	s_waitcnt vmcnt(15)
; __device__ NOINL void phase_ln(float* __restrict__ buf, const float* __restrict__ g, const float* __restrict__ bta, u16* __restrict__ outb,
;                                float* __restrict__ stats) {
;     ...
; #pragma unroll 8
;     for (int i = 0; i < 16; ++i) {
;       int col = (i * 64 + lane) * 4;
;       float4 v = *(const float4*)(rp + col);
;       float4 gg = *(const float4*)(g + col), bb = *(const float4*)(bta + col);
;       float4 o;
;       o.x = (v.x - mu) * rs * gg.x + bb.x; o.y = (v.y - mu) * rs * gg.y + bb.y;
;       o.z = (v.z - mu) * rs * gg.z + bb.z; o.w = (v.w - mu) * rs * gg.w + bb.w;
;       if (!stats) *(float4*)(rp + col) = o;
	v_mov_b32_e32 v75, v62
	v_mov_b32_e32 v62, v43
	v_pk_add_f32 v[42:43], v[226:227], v[216:217] op_sel_hi:[1,0] neg_lo:[0,1] neg_hi:[0,1]
	v_mov_b32_e32 v234, v44
	v_pk_mul_f32 v[42:43], v[40:41], v[42:43] op_sel_hi:[0,1]
	v_mov_b32_e32 v235, v64
	v_mov_b32_e32 v64, v45
	v_pk_fma_f32 v[74:75], v[42:43], v[230:231], v[74:75]
	v_pk_add_f32 v[42:43], v[58:59], v[216:217] op_sel_hi:[1,0] neg_lo:[0,1] neg_hi:[0,1]
	v_pk_add_f32 v[44:45], v[228:229], v[216:217] op_sel_hi:[1,0] neg_lo:[0,1] neg_hi:[0,1]
	v_pk_mul_f32 v[42:43], v[40:41], v[42:43] op_sel_hi:[0,1]
	v_pk_mul_f32 v[44:45], v[40:41], v[44:45] op_sel_hi:[0,1]
	v_pk_fma_f32 v[42:43], v[42:43], v[76:77], v[62:63]
	v_pk_fma_f32 v[62:63], v[44:45], v[232:233], v[234:235]
	v_pk_add_f32 v[44:45], v[60:61], v[216:217] op_sel_hi:[1,0] neg_lo:[0,1] neg_hi:[0,1]
	v_mov_b32_e32 v59, v42
	v_pk_mul_f32 v[44:45], v[40:41], v[44:45] op_sel_hi:[0,1]
	v_pk_fma_f32 v[44:45], v[44:45], v[78:79], v[64:65]
	v_mov_b32_e32 v42, v75
	v_mov_b32_e32 v61, v44
	v_mov_b32_e32 v44, v63
	global_store_dwordx4 v[110:111], v[42:45], off sc1
	v_mov_b32_e32 v58, v74
	v_mov_b32_e32 v60, v62
	s_waitcnt vmcnt(14)
	v_mov_b32_e32 v42, v80
	s_waitcnt vmcnt(13)
	v_mov_b32_e32 v43, v84
	v_mov_b32_e32 v44, v82
	v_mov_b32_e32 v45, v86
	v_pk_add_f32 v[42:43], v[42:43], v[216:217] op_sel_hi:[1,0] neg_lo:[0,1] neg_hi:[0,1]
	v_pk_add_f32 v[44:45], v[44:45], v[216:217] op_sel_hi:[1,0] neg_lo:[0,1] neg_hi:[0,1]
	global_store_dwordx4 v[108:109], v[58:61], off sc1
	v_mov_b32_e32 v84, v81
	v_mov_b32_e32 v86, v83
	s_waitcnt vmcnt(12)
	v_mov_b32_e32 v58, v66
	s_waitcnt vmcnt(11)
	v_mov_b32_e32 v59, v88
	v_mov_b32_e32 v60, v68
	v_mov_b32_e32 v61, v90
	s_waitcnt vmcnt(10)
	v_mov_b32_e32 v62, v92
	s_waitcnt vmcnt(9)
	v_mov_b32_e32 v63, v96
	v_mov_b32_e32 v64, v94
	v_mov_b32_e32 v65, v98
	v_pk_mul_f32 v[42:43], v[40:41], v[42:43] op_sel_hi:[0,1]
	v_pk_mul_f32 v[44:45], v[40:41], v[44:45] op_sel_hi:[0,1]
	v_pk_fma_f32 v[62:63], v[42:43], v[58:59], v[62:63]
	v_pk_add_f32 v[42:43], v[84:85], v[216:217] op_sel_hi:[1,0] neg_lo:[0,1] neg_hi:[0,1]
	v_pk_fma_f32 v[64:65], v[44:45], v[60:61], v[64:65]
	v_pk_add_f32 v[44:45], v[86:87], v[216:217] op_sel_hi:[1,0] neg_lo:[0,1] neg_hi:[0,1]
	v_mov_b32_e32 v88, v67
	v_mov_b32_e32 v90, v69
	v_mov_b32_e32 v96, v93
	v_mov_b32_e32 v98, v95
	v_pk_mul_f32 v[42:43], v[40:41], v[42:43] op_sel_hi:[0,1]
	v_pk_mul_f32 v[44:45], v[40:41], v[44:45] op_sel_hi:[0,1]
	v_pk_fma_f32 v[42:43], v[42:43], v[88:89], v[96:97]
	v_pk_fma_f32 v[44:45], v[44:45], v[90:91], v[98:99]
	v_mov_b32_e32 v59, v42
	v_mov_b32_e32 v61, v44
	v_mov_b32_e32 v42, v63
	v_mov_b32_e32 v44, v65
	global_store_dwordx4 v[224:225], v[42:45], off sc1
	v_mov_b32_e32 v58, v62
	v_mov_b32_e32 v60, v64
	s_waitcnt vmcnt(8)
	v_mov_b32_e32 v42, v46
	v_mov_b32_e32 v43, v104
	v_mov_b32_e32 v44, v48
	v_mov_b32_e32 v45, v106
	v_pk_add_f32 v[42:43], v[42:43], v[216:217] op_sel_hi:[1,0] neg_lo:[0,1] neg_hi:[0,1]
	v_pk_add_f32 v[44:45], v[44:45], v[216:217] op_sel_hi:[1,0] neg_lo:[0,1] neg_hi:[0,1]
	v_mov_b32_e32 v104, v47
	v_mov_b32_e32 v106, v49
	s_waitcnt vmcnt(6)
	v_mov_b32_e32 v46, v50
	s_waitcnt vmcnt(5)
	v_mov_b32_e32 v47, v54
	v_mov_b32_e32 v54, v51
	v_mov_b32_e32 v48, v52
	v_mov_b32_e32 v49, v56
	v_mov_b32_e32 v56, v53
	s_waitcnt vmcnt(4)
	v_mov_b32_e32 v50, v70
	s_waitcnt vmcnt(3)
	v_mov_b32_e32 v51, v100
	v_mov_b32_e32 v52, v72
	v_mov_b32_e32 v53, v102
	v_pk_mul_f32 v[42:43], v[40:41], v[42:43] op_sel_hi:[0,1]
	v_pk_mul_f32 v[44:45], v[40:41], v[44:45] op_sel_hi:[0,1]
	v_pk_fma_f32 v[50:51], v[42:43], v[46:47], v[50:51]
	v_pk_add_f32 v[42:43], v[104:105], v[216:217] op_sel_hi:[1,0] neg_lo:[0,1] neg_hi:[0,1]
	v_pk_fma_f32 v[52:53], v[44:45], v[48:49], v[52:53]
	v_pk_add_f32 v[44:45], v[106:107], v[216:217] op_sel_hi:[1,0] neg_lo:[0,1] neg_hi:[0,1]
	v_mov_b32_e32 v100, v71
	v_mov_b32_e32 v102, v73
	v_pk_mul_f32 v[42:43], v[40:41], v[42:43] op_sel_hi:[0,1]
	v_pk_mul_f32 v[40:41], v[40:41], v[44:45] op_sel_hi:[0,1]
	v_pk_fma_f32 v[42:43], v[42:43], v[54:55], v[100:101]
	v_pk_fma_f32 v[44:45], v[40:41], v[56:57], v[102:103]
	v_mov_b32_e32 v46, v50
	v_mov_b32_e32 v47, v42
	v_mov_b32_e32 v48, v52
	v_mov_b32_e32 v49, v44
	v_mov_b32_e32 v42, v51
	v_mov_b32_e32 v44, v53
	global_store_dwordx4 v[212:213], v[58:61], off sc1
	global_store_dwordx4 v[210:211], v[46:49], off sc1
	global_store_dwordx4 v[214:215], v[42:45], off sc1
	s_andn2_b64 exec, exec, s[0:1]
	s_cbranch_execnz .LBB0_898
